# v19: GEMM K loops: per-segment s_setprio toggles removed, one static s_setprio 1 for waves 4-7 around each K loop
# baseline (speedup 1.0000x reference)
; template <class Epi, class Sched, bool ALIGN_EPI = false, bool SP2 = false>
; __device__ __forceinline__ void gemm_phase(PG8_LAS unsigned char* lds, const Gemm g, const Sched& S, const Epi& E, int tid_in) {
;     ...
; #pragma unroll
;     for (int a = 0; a < 2; ++a)
; #pragma unroll
;         for (int b = 0; b < 2; ++b)
; #pragma unroll
;             for (int m = 0; m < 4; ++m)
; #pragma unroll
;                 for (int n = 0; n < 2; ++n) acc[a][b][m][n] = (f32x4){0.f, 0.f, 0.f, 0.f};
;     ...
; #pragma unroll
;         for (int a = 0; a < 2; ++a)
; #pragma unroll
;             for (int b = 0; b < 2; ++b)
; #pragma unroll
;                 for (int m = 0; m < 4; ++m)
; #pragma unroll
;                     for (int n = 0; n < 2; ++n) acc[a][b][m][n] = (f32x4){0.f, 0.f, 0.f, 0.f};
.LBB0_106:
	v_mov_b32_e32 v129, 0
	s_andn2_b64 vcc, exec, s[40:41]
	v_mov_b32_e32 v128, v129
	v_mov_b32_e32 v127, v129
	v_mov_b32_e32 v126, v129
	v_mov_b32_e32 v125, v129
	v_mov_b32_e32 v124, v129
	v_mov_b32_e32 v123, v129
	v_mov_b32_e32 v122, v129
	v_mov_b32_e32 v113, v129
	v_mov_b32_e32 v112, v129
	v_mov_b32_e32 v111, v129
	v_mov_b32_e32 v110, v129
	v_mov_b32_e32 v109, v129
	v_mov_b32_e32 v108, v129
	v_mov_b32_e32 v107, v129
	v_mov_b32_e32 v106, v129
	v_mov_b32_e32 v97, v129
	v_mov_b32_e32 v96, v129
	v_mov_b32_e32 v95, v129
	v_mov_b32_e32 v94, v129
	v_mov_b32_e32 v93, v129
	v_mov_b32_e32 v92, v129
	v_mov_b32_e32 v91, v129
	v_mov_b32_e32 v90, v129
	v_mov_b32_e32 v81, v129
	v_mov_b32_e32 v80, v129
	v_mov_b32_e32 v79, v129
	v_mov_b32_e32 v78, v129
	v_mov_b32_e32 v77, v129
	v_mov_b32_e32 v76, v129
	v_mov_b32_e32 v75, v129
	v_mov_b32_e32 v74, v129
	v_mov_b32_e32 v121, v129
	v_mov_b32_e32 v120, v129
	v_mov_b32_e32 v119, v129
	v_mov_b32_e32 v118, v129
	v_mov_b32_e32 v117, v129
	v_mov_b32_e32 v116, v129
	v_mov_b32_e32 v115, v129
	v_mov_b32_e32 v114, v129
	v_mov_b32_e32 v105, v129
	v_mov_b32_e32 v104, v129
	v_mov_b32_e32 v103, v129
	v_mov_b32_e32 v102, v129
	v_mov_b32_e32 v101, v129
	v_mov_b32_e32 v100, v129
	v_mov_b32_e32 v99, v129
	v_mov_b32_e32 v98, v129
	v_mov_b32_e32 v89, v129
	v_mov_b32_e32 v88, v129
	v_mov_b32_e32 v87, v129
	v_mov_b32_e32 v86, v129
	v_mov_b32_e32 v85, v129
	v_mov_b32_e32 v84, v129
	v_mov_b32_e32 v83, v129
	v_mov_b32_e32 v82, v129
	v_mov_b32_e32 v73, v129
	v_mov_b32_e32 v72, v129
	v_mov_b32_e32 v71, v129
	v_mov_b32_e32 v70, v129
	v_mov_b32_e32 v69, v129
	v_mov_b32_e32 v68, v129
	v_mov_b32_e32 v67, v129
	v_mov_b32_e32 v66, v129
	v_mov_b32_e32 v65, v129
	v_mov_b32_e32 v64, v129
	v_mov_b32_e32 v63, v129
	v_mov_b32_e32 v62, v129
	v_mov_b32_e32 v61, v129
	v_mov_b32_e32 v60, v129
	v_mov_b32_e32 v59, v129
	v_mov_b32_e32 v58, v129
	s_waitcnt vmcnt(0)
	v_mov_b32_e32 v49, v129
	v_mov_b32_e32 v48, v129
	v_mov_b32_e32 v47, v129
	v_mov_b32_e32 v46, v129
	v_mov_b32_e32 v45, v129
	v_mov_b32_e32 v44, v129
	v_mov_b32_e32 v43, v129
	v_mov_b32_e32 v42, v129
	v_mov_b32_e32 v33, v129
	v_mov_b32_e32 v32, v129
	v_mov_b32_e32 v31, v129
	v_mov_b32_e32 v30, v129
	v_mov_b32_e32 v29, v129
	v_mov_b32_e32 v28, v129
	v_mov_b32_e32 v27, v129
	v_mov_b32_e32 v26, v129
	v_mov_b32_e32 v17, v129
	v_mov_b32_e32 v16, v129
	v_mov_b32_e32 v15, v129
	v_mov_b32_e32 v14, v129
	v_mov_b32_e32 v13, v129
	v_mov_b32_e32 v12, v129
	v_mov_b32_e32 v11, v129
	v_mov_b32_e32 v10, v129
	v_mov_b32_e32 v57, v129
	v_mov_b32_e32 v56, v129
	v_mov_b32_e32 v55, v129
	v_mov_b32_e32 v54, v129
	v_mov_b32_e32 v53, v129
	v_mov_b32_e32 v52, v129
	v_mov_b32_e32 v51, v129
	v_mov_b32_e32 v50, v129
	v_mov_b32_e32 v41, v129
	v_mov_b32_e32 v40, v129
	v_mov_b32_e32 v39, v129
	v_mov_b32_e32 v38, v129
	v_mov_b32_e32 v37, v129
	v_mov_b32_e32 v36, v129
	v_mov_b32_e32 v35, v129
	v_mov_b32_e32 v34, v129
	v_mov_b32_e32 v25, v129
	v_mov_b32_e32 v24, v129
	v_mov_b32_e32 v23, v129
	v_mov_b32_e32 v22, v129
	v_mov_b32_e32 v21, v129
	v_mov_b32_e32 v20, v129
	v_mov_b32_e32 v19, v129
	v_mov_b32_e32 v18, v129
	v_mov_b32_e32 v9, v129
	v_mov_b32_e32 v8, v129
	v_mov_b32_e32 v7, v129
	v_mov_b32_e32 v6, v129
	v_mov_b32_e32 v5, v129
	v_mov_b32_e32 v4, v129
	v_mov_b32_e32 v3, v129
	v_mov_b32_e32 v2, v129
	s_cbranch_vccnz .LBB0_110
	s_add_u32 s18, s18, 0x80
	s_addc_u32 s19, s19, 0
	s_add_u32 s12, s20, 0x100
	v_mov_b32_e32 v2, 0
	s_addc_u32 s13, s21, 0
	s_mov_b32 s15, 0
	v_mov_b32_e32 v3, v2
	v_mov_b32_e32 v4, v2
	v_mov_b32_e32 v5, v2
	v_mov_b32_e32 v6, v2
	v_mov_b32_e32 v7, v2
	v_mov_b32_e32 v8, v2
	v_mov_b32_e32 v9, v2
	v_mov_b32_e32 v18, v2
	v_mov_b32_e32 v19, v2
	v_mov_b32_e32 v20, v2
	v_mov_b32_e32 v21, v2
	v_mov_b32_e32 v22, v2
	v_mov_b32_e32 v23, v2
	v_mov_b32_e32 v24, v2
	v_mov_b32_e32 v25, v2
	v_mov_b32_e32 v34, v2
	v_mov_b32_e32 v35, v2
	v_mov_b32_e32 v36, v2
	v_mov_b32_e32 v37, v2
	v_mov_b32_e32 v38, v2
	v_mov_b32_e32 v39, v2
	v_mov_b32_e32 v40, v2
	v_mov_b32_e32 v41, v2
	v_mov_b32_e32 v50, v2
	v_mov_b32_e32 v51, v2
	v_mov_b32_e32 v52, v2
	v_mov_b32_e32 v53, v2
	v_mov_b32_e32 v54, v2
	v_mov_b32_e32 v55, v2
	v_mov_b32_e32 v56, v2
	v_mov_b32_e32 v57, v2
	v_mov_b32_e32 v10, v2
	v_mov_b32_e32 v11, v2
	v_mov_b32_e32 v12, v2
	v_mov_b32_e32 v13, v2
	v_mov_b32_e32 v14, v2
	v_mov_b32_e32 v15, v2
	v_mov_b32_e32 v16, v2
	v_mov_b32_e32 v17, v2
	v_mov_b32_e32 v26, v2
	v_mov_b32_e32 v27, v2
	v_mov_b32_e32 v28, v2
	v_mov_b32_e32 v29, v2
	v_mov_b32_e32 v30, v2
	v_mov_b32_e32 v31, v2
	v_mov_b32_e32 v32, v2
	v_mov_b32_e32 v33, v2
	v_mov_b32_e32 v42, v2
	v_mov_b32_e32 v43, v2
	v_mov_b32_e32 v44, v2
	v_mov_b32_e32 v45, v2
	v_mov_b32_e32 v46, v2
	v_mov_b32_e32 v47, v2
	v_mov_b32_e32 v48, v2
	v_mov_b32_e32 v49, v2
	v_mov_b32_e32 v58, v2
	v_mov_b32_e32 v59, v2
	v_mov_b32_e32 v60, v2
	v_mov_b32_e32 v61, v2
	v_mov_b32_e32 v62, v2
	v_mov_b32_e32 v63, v2
	v_mov_b32_e32 v64, v2
	v_mov_b32_e32 v65, v2
	v_mov_b32_e32 v66, v2
	v_mov_b32_e32 v67, v2
	v_mov_b32_e32 v68, v2
	v_mov_b32_e32 v69, v2
	v_mov_b32_e32 v70, v2
	v_mov_b32_e32 v71, v2
	v_mov_b32_e32 v72, v2
	v_mov_b32_e32 v73, v2
	v_mov_b32_e32 v82, v2
	v_mov_b32_e32 v83, v2
	v_mov_b32_e32 v84, v2
	v_mov_b32_e32 v85, v2
	v_mov_b32_e32 v86, v2
	v_mov_b32_e32 v87, v2
	v_mov_b32_e32 v88, v2
	v_mov_b32_e32 v89, v2
	v_mov_b32_e32 v98, v2
	v_mov_b32_e32 v99, v2
	v_mov_b32_e32 v100, v2
	v_mov_b32_e32 v101, v2
	v_mov_b32_e32 v102, v2
	v_mov_b32_e32 v103, v2
	v_mov_b32_e32 v104, v2
	v_mov_b32_e32 v105, v2
	v_mov_b32_e32 v114, v2
	v_mov_b32_e32 v115, v2
	v_mov_b32_e32 v116, v2
	v_mov_b32_e32 v117, v2
	v_mov_b32_e32 v118, v2
	v_mov_b32_e32 v119, v2
	v_mov_b32_e32 v120, v2
	v_mov_b32_e32 v121, v2
	v_mov_b32_e32 v74, v2
	v_mov_b32_e32 v75, v2
	v_mov_b32_e32 v76, v2
	v_mov_b32_e32 v77, v2
	v_mov_b32_e32 v78, v2
	v_mov_b32_e32 v79, v2
	v_mov_b32_e32 v80, v2
	v_mov_b32_e32 v81, v2
	v_mov_b32_e32 v90, v2
	v_mov_b32_e32 v91, v2
	v_mov_b32_e32 v92, v2
	v_mov_b32_e32 v93, v2
	v_mov_b32_e32 v94, v2
	v_mov_b32_e32 v95, v2
	v_mov_b32_e32 v96, v2
	v_mov_b32_e32 v97, v2
	v_mov_b32_e32 v106, v2
	v_mov_b32_e32 v107, v2
	v_mov_b32_e32 v108, v2
	v_mov_b32_e32 v109, v2
	v_mov_b32_e32 v110, v2
	v_mov_b32_e32 v111, v2
	v_mov_b32_e32 v112, v2
	v_mov_b32_e32 v113, v2
	v_mov_b32_e32 v122, v2
	v_mov_b32_e32 v123, v2
	v_mov_b32_e32 v124, v2
	v_mov_b32_e32 v125, v2
	v_mov_b32_e32 v126, v2
	v_mov_b32_e32 v127, v2
	v_mov_b32_e32 v128, v2
	v_mov_b32_e32 v129, v2
	s_waitcnt vmcnt(0)
	s_cmp_ge_u32 s84, 0x100
	s_cbranch_scc0 .Lprio_skip108
	s_setprio 1
; #define PG8_STAGE(bufoff, gbase, voff) do { _Pragma("unroll") for (int _i = 0; _i < 2; ++_i) \
;         __builtin_amdgcn_global_load_lds((const unsigned*)((const char*)(gbase) + (voff)[_i]), (PG8_LAS unsigned*)(lds + (bufoff) + ldsw + _i * 8192), 16, 0, 0); } while (0)
; #define PG8_LDA(dst, b, h) do { _Pragma("unroll") for (int m = 0; m < 4; ++m) _Pragma("unroll") for (int k = 0; k < 2; ++k) dst[m][k] = *(const PG8_LAS bf16x8*)(lds + PG8_SA(b, h) + aoff + m * 2048 + k * 1024); } while (0)
; #define PG8_LDB(dst, b, h) do { _Pragma("unroll") for (int n = 0; n < 2; ++n) _Pragma("unroll") for (int k = 0; k < 2; ++k) dst[n][k] = *(const PG8_LAS bf16x8*)(lds + PG8_SB(b, h) + boff + n * 2048 + k * 1024); } while (0)
; #define PG8_MMA(ai, bj, At, Bt) do { __builtin_amdgcn_s_setprio(1); _Pragma("unroll") for (int m = 0; m < 4; ++m) _Pragma("unroll") for (int n = 0; n < 2; ++n) _Pragma("unroll") for (int k = 0; k < 2; ++k) \
;         acc[ai][bj][m][n] = __builtin_amdgcn_mfma_f32_16x16x32_bf16(Bt[n][k], At[m][k], acc[ai][bj][m][n], 0, 0, 0); __builtin_amdgcn_s_setprio(0); } while (0)
; #define PG8_WAIT_V(n) asm volatile("s_waitcnt vmcnt(" #n ")" ::: "memory")
; #define PG8_WAIT_L(n) asm volatile("s_waitcnt lgkmcnt(" #n ")" ::: "memory")
; #define PG8_BAR __builtin_amdgcn_s_barrier()
; #define PG8_SCHED __builtin_amdgcn_sched_barrier(0)
; template <class Epi, class Sched, bool ALIGN_EPI = false, bool SP2 = false>
; __device__ __forceinline__ void gemm_phase(PG8_LAS unsigned char* lds, const Gemm g, const Sched& S, const Epi& E, int tid_in) {
;     ...
;         for (int t = 0; t < nt; t += 2) {
;             const bool last = (t == nt - 2);
;             const char* a1 = cA + (size_t)(t + 1) * kstep;
;             const char* a2 = last ? nA : cA + (size_t)(t + 2) * kstep; const char* b2 = last ? nB : cB + (size_t)(t + 2) * kstep;
;             const char* a3 = a2 + kstep; const char* b3 = b2 + kstep;
;             if (last && has_next) S.a_ready(nxt);
;             if constexpr (SP2) {
;             PG8_LDB(B0, 0, 0); PG8_LDB(B1, 0, 1); PG8_SCHED; PG8_LDA(At, 0, 0); PG8_STAGE(PG8_SA(1, 1), a1 + hstepA, voffA);
;             PG8_WAIT_V(8); PG8_WAIT_L(0); PG8_BAR; PG8_MMA(0, 0, At, B0); PG8_MMA(0, 1, At, B1); PG8_BAR; PG8_SCHED;
;             PG8_LDA(At, 0, 1); PG8_STAGE(PG8_SB(0, 0), b2, voffB); PG8_STAGE(PG8_SB(0, 1), b2 + hstep, voffB); PG8_STAGE(PG8_SA(0, 0), a2, voffA);
.Lprio_skip108:
.LBB0_108:
	s_add_i32 s62, s15, 2
	s_add_u32 s20, s18, 0x80
	s_addc_u32 s21, s19, 0
	s_add_i32 s63, 0, 0x10000
	s_cmp_eq_u32 s57, s15
	s_cselect_b32 s21, s39, s21
	s_cselect_b32 s20, s38, s20
	v_add_u32_e32 v146, s63, v145
	s_cselect_b32 s65, s45, s13
	s_cselect_b32 s64, s44, s12
	s_add_i32 s15, 0, 0x14000
	ds_read_b128 v[140:143], v146
	ds_read_b128 v[150:153], v146 offset:1024
	ds_read_b128 v[154:157], v146 offset:2048
	ds_read_b128 v[158:161], v146 offset:3072
	v_add_u32_e32 v146, s15, v145
	ds_read_b128 v[162:165], v146
	ds_read_b128 v[166:169], v146 offset:1024
	ds_read_b128 v[170:173], v146 offset:2048
	ds_read_b128 v[174:177], v146 offset:3072
	v_lshl_add_u64 v[146:147], s[18:19], 0, v[136:137]
	s_add_i32 m0, s50, 0xc000
	ds_read_b128 v[178:181], v149
	ds_read_b128 v[182:185], v149 offset:1024
	ds_read_b128 v[186:189], v149 offset:2048
	ds_read_b128 v[190:193], v149 offset:3072
	ds_read_b128 v[204:207], v149 offset:4096
	ds_read_b128 v[208:211], v149 offset:5120
	ds_read_b128 v[212:215], v149 offset:6144
	ds_read_b128 v[216:219], v149 offset:7168
	global_load_lds_dwordx4 v[146:147], off
	v_lshl_add_u64 v[146:147], s[18:19], 0, v[138:139]
	s_add_i32 m0, s50, 0xe000
	s_nop 0
	global_load_lds_dwordx4 v[146:147], off
	s_waitcnt vmcnt(8)
	s_waitcnt lgkmcnt(0)
	s_barrier
	s_waitcnt lgkmcnt(0)
	v_mfma_f32_16x16x32_bf16 v[126:129], v[140:143], v[178:181], v[126:129]
	v_mfma_f32_16x16x32_bf16 v[122:125], v[154:157], v[178:181], v[122:125]
	v_mfma_f32_16x16x32_bf16 v[110:113], v[140:143], v[186:189], v[110:113]
	v_mfma_f32_16x16x32_bf16 v[106:109], v[154:157], v[186:189], v[106:109]
	v_mfma_f32_16x16x32_bf16 v[94:97], v[140:143], v[204:207], v[94:97]
	v_mfma_f32_16x16x32_bf16 v[90:93], v[154:157], v[204:207], v[90:93]
	v_mfma_f32_16x16x32_bf16 v[78:81], v[140:143], v[212:215], v[78:81]
	v_mfma_f32_16x16x32_bf16 v[74:77], v[154:157], v[212:215], v[74:77]
	v_mfma_f32_16x16x32_bf16 v[126:129], v[150:153], v[182:185], v[126:129]
	v_mfma_f32_16x16x32_bf16 v[122:125], v[158:161], v[182:185], v[122:125]
	v_mfma_f32_16x16x32_bf16 v[110:113], v[150:153], v[190:193], v[110:113]
	v_mfma_f32_16x16x32_bf16 v[106:109], v[158:161], v[190:193], v[106:109]
	v_mfma_f32_16x16x32_bf16 v[94:97], v[150:153], v[208:211], v[94:97]
	v_mfma_f32_16x16x32_bf16 v[90:93], v[158:161], v[208:211], v[90:93]
	v_mfma_f32_16x16x32_bf16 v[78:81], v[150:153], v[216:219], v[78:81]
	v_mfma_f32_16x16x32_bf16 v[74:77], v[158:161], v[216:219], v[74:77]
	v_mfma_f32_16x16x32_bf16 v[118:121], v[162:165], v[178:181], v[118:121]
	v_mfma_f32_16x16x32_bf16 v[114:117], v[170:173], v[178:181], v[114:117]
	v_mfma_f32_16x16x32_bf16 v[102:105], v[162:165], v[186:189], v[102:105]
	v_mfma_f32_16x16x32_bf16 v[98:101], v[170:173], v[186:189], v[98:101]
	v_mfma_f32_16x16x32_bf16 v[86:89], v[162:165], v[204:207], v[86:89]
	v_mfma_f32_16x16x32_bf16 v[82:85], v[170:173], v[204:207], v[82:85]
	v_mfma_f32_16x16x32_bf16 v[70:73], v[162:165], v[212:215], v[70:73]
	v_mfma_f32_16x16x32_bf16 v[66:69], v[170:173], v[212:215], v[66:69]
	v_mfma_f32_16x16x32_bf16 v[118:121], v[166:169], v[182:185], v[118:121]
	v_mfma_f32_16x16x32_bf16 v[114:117], v[174:177], v[182:185], v[114:117]
	v_mfma_f32_16x16x32_bf16 v[102:105], v[166:169], v[190:193], v[102:105]
	v_mfma_f32_16x16x32_bf16 v[98:101], v[174:177], v[190:193], v[98:101]
	v_mfma_f32_16x16x32_bf16 v[86:89], v[166:169], v[208:211], v[86:89]
	v_mfma_f32_16x16x32_bf16 v[82:85], v[174:177], v[208:211], v[82:85]
	v_mfma_f32_16x16x32_bf16 v[70:73], v[166:169], v[216:219], v[70:73]
	v_mfma_f32_16x16x32_bf16 v[66:69], v[174:177], v[216:219], v[66:69]
	s_barrier
	s_add_i32 s63, s63, s49
	v_lshl_add_u64 v[146:147], s[64:65], 0, v[0:1]
	s_mov_b32 m0, s63
	ds_read_b128 v[178:181], v149 offset:16384
	ds_read_b128 v[182:185], v149 offset:17408
	ds_read_b128 v[186:189], v149 offset:18432
	ds_read_b128 v[190:193], v149 offset:19456
	ds_read_b128 v[204:207], v149 offset:20480
	ds_read_b128 v[208:211], v149 offset:21504
	ds_read_b128 v[212:215], v149 offset:22528
	ds_read_b128 v[216:219], v149 offset:23552
	global_load_lds_dwordx4 v[146:147], off
	s_add_i32 m0, s63, 0x2000
	v_lshl_add_u64 v[194:195], s[64:65], 0, v[130:131]
	s_add_u32 s64, s64, s0
	s_addc_u32 s65, s65, s1
	s_add_i32 s15, s15, s49
	global_load_lds_dwordx4 v[194:195], off
	v_lshl_add_u64 v[200:201], s[64:65], 0, v[0:1]
	s_mov_b32 m0, s15
	v_lshl_add_u64 v[220:221], s[64:65], 0, v[130:131]
	global_load_lds_dwordx4 v[200:201], off
	s_add_i32 m0, s15, 0x2000
	v_lshl_add_u64 v[222:223], s[20:21], 0, v[134:135]
	global_load_lds_dwordx4 v[220:221], off
	s_mov_b32 m0, s50
	v_lshl_add_u64 v[224:225], s[20:21], 0, v[132:133]
	global_load_lds_dwordx4 v[222:223], off
	s_mov_b32 m0, s51
	s_nop 0
	global_load_lds_dwordx4 v[224:225], off
	s_waitcnt vmcnt(8)
	s_waitcnt lgkmcnt(0)
	s_barrier
; #define PG8_STAGE(bufoff, gbase, voff) do { _Pragma("unroll") for (int _i = 0; _i < 2; ++_i) \
;         __builtin_amdgcn_global_load_lds((const unsigned*)((const char*)(gbase) + (voff)[_i]), (PG8_LAS unsigned*)(lds + (bufoff) + ldsw + _i * 8192), 16, 0, 0); } while (0)
; #define PG8_LDA(dst, b, h) do { _Pragma("unroll") for (int m = 0; m < 4; ++m) _Pragma("unroll") for (int k = 0; k < 2; ++k) dst[m][k] = *(const PG8_LAS bf16x8*)(lds + PG8_SA(b, h) + aoff + m * 2048 + k * 1024); } while (0)
; #define PG8_LDB(dst, b, h) do { _Pragma("unroll") for (int n = 0; n < 2; ++n) _Pragma("unroll") for (int k = 0; k < 2; ++k) dst[n][k] = *(const PG8_LAS bf16x8*)(lds + PG8_SB(b, h) + boff + n * 2048 + k * 1024); } while (0)
; #define PG8_MMA(ai, bj, At, Bt) do { __builtin_amdgcn_s_setprio(1); _Pragma("unroll") for (int m = 0; m < 4; ++m) _Pragma("unroll") for (int n = 0; n < 2; ++n) _Pragma("unroll") for (int k = 0; k < 2; ++k) \
;         acc[ai][bj][m][n] = __builtin_amdgcn_mfma_f32_16x16x32_bf16(Bt[n][k], At[m][k], acc[ai][bj][m][n], 0, 0, 0); __builtin_amdgcn_s_setprio(0); } while (0)
; #define PG8_WAIT_V(n) asm volatile("s_waitcnt vmcnt(" #n ")" ::: "memory")
; #define PG8_WAIT_L(n) asm volatile("s_waitcnt lgkmcnt(" #n ")" ::: "memory")
; #define PG8_BAR __builtin_amdgcn_s_barrier()
; #define PG8_SCHED __builtin_amdgcn_sched_barrier(0)
; template <class Epi, class Sched, bool ALIGN_EPI = false, bool SP2 = false>
; __device__ __forceinline__ void gemm_phase(PG8_LAS unsigned char* lds, const Gemm g, const Sched& S, const Epi& E, int tid_in) {
;     ...
;             PG8_WAIT_V(8); PG8_WAIT_L(0); PG8_BAR; PG8_MMA(1, 0, At, B0); PG8_MMA(1, 1, At, B1); PG8_BAR; PG8_SCHED;
;             PG8_LDB(B0, 1, 0); PG8_LDB(B1, 1, 1); PG8_SCHED; PG8_LDA(At, 1, 0); PG8_STAGE(PG8_SA(0, 1), a2 + hstepA, voffA);
;             PG8_WAIT_V(8); PG8_WAIT_L(0); PG8_BAR; PG8_MMA(0, 0, At, B0); PG8_MMA(0, 1, At, B1); PG8_BAR; PG8_SCHED;
	s_waitcnt lgkmcnt(0)
	v_mfma_f32_16x16x32_bf16 v[62:65], v[140:143], v[178:181], v[62:65]
	v_mfma_f32_16x16x32_bf16 v[58:61], v[154:157], v[178:181], v[58:61]
	v_mfma_f32_16x16x32_bf16 v[46:49], v[140:143], v[186:189], v[46:49]
	v_mfma_f32_16x16x32_bf16 v[42:45], v[154:157], v[186:189], v[42:45]
	v_mfma_f32_16x16x32_bf16 v[30:33], v[140:143], v[204:207], v[30:33]
	v_mfma_f32_16x16x32_bf16 v[26:29], v[154:157], v[204:207], v[26:29]
	v_mfma_f32_16x16x32_bf16 v[14:17], v[140:143], v[212:215], v[14:17]
	v_mfma_f32_16x16x32_bf16 v[10:13], v[154:157], v[212:215], v[10:13]
	v_mfma_f32_16x16x32_bf16 v[62:65], v[150:153], v[182:185], v[62:65]
	v_mfma_f32_16x16x32_bf16 v[58:61], v[158:161], v[182:185], v[58:61]
	v_mfma_f32_16x16x32_bf16 v[46:49], v[150:153], v[190:193], v[46:49]
	v_mfma_f32_16x16x32_bf16 v[42:45], v[158:161], v[190:193], v[42:45]
	v_mfma_f32_16x16x32_bf16 v[30:33], v[150:153], v[208:211], v[30:33]
	v_mfma_f32_16x16x32_bf16 v[26:29], v[158:161], v[208:211], v[26:29]
	v_mfma_f32_16x16x32_bf16 v[14:17], v[150:153], v[216:219], v[14:17]
	v_mfma_f32_16x16x32_bf16 v[10:13], v[158:161], v[216:219], v[10:13]
	v_mfma_f32_16x16x32_bf16 v[54:57], v[162:165], v[178:181], v[54:57]
	v_mfma_f32_16x16x32_bf16 v[50:53], v[170:173], v[178:181], v[50:53]
	v_mfma_f32_16x16x32_bf16 v[38:41], v[162:165], v[186:189], v[38:41]
	v_mfma_f32_16x16x32_bf16 v[34:37], v[170:173], v[186:189], v[34:37]
	v_mfma_f32_16x16x32_bf16 v[22:25], v[162:165], v[204:207], v[22:25]
	v_mfma_f32_16x16x32_bf16 v[18:21], v[170:173], v[204:207], v[18:21]
	v_mfma_f32_16x16x32_bf16 v[6:9], v[162:165], v[212:215], v[6:9]
	v_mfma_f32_16x16x32_bf16 v[2:5], v[170:173], v[212:215], v[2:5]
	v_mfma_f32_16x16x32_bf16 v[54:57], v[166:169], v[182:185], v[54:57]
	v_mfma_f32_16x16x32_bf16 v[50:53], v[174:177], v[182:185], v[50:53]
	v_mfma_f32_16x16x32_bf16 v[38:41], v[166:169], v[190:193], v[38:41]
	v_mfma_f32_16x16x32_bf16 v[34:37], v[174:177], v[190:193], v[34:37]
	v_mfma_f32_16x16x32_bf16 v[22:25], v[166:169], v[208:211], v[22:25]
	v_mfma_f32_16x16x32_bf16 v[18:21], v[174:177], v[208:211], v[18:21]
	v_mfma_f32_16x16x32_bf16 v[6:9], v[166:169], v[216:219], v[6:9]
	v_mfma_f32_16x16x32_bf16 v[2:5], v[174:177], v[216:219], v[2:5]
	s_barrier
	s_add_i32 s15, 0, 0x18000
	s_add_i32 s63, 0, 0x1c000
	v_add_u32_e32 v158, s15, v145
	v_add_u32_e32 v174, s63, v145
	ds_read_b128 v[140:143], v158
	ds_read_b128 v[150:153], v158 offset:1024
	ds_read_b128 v[154:157], v158 offset:2048
	ds_read_b128 v[158:161], v158 offset:3072
	ds_read_b128 v[162:165], v174
	ds_read_b128 v[166:169], v174 offset:1024
	ds_read_b128 v[170:173], v174 offset:2048
	ds_read_b128 v[174:177], v174 offset:3072
	s_add_u32 s20, s20, s0
	s_addc_u32 s21, s21, s1
	s_mov_b32 m0, s52
	v_lshl_add_u64 v[226:227], s[20:21], 0, v[134:135]
	ds_read_b128 v[178:181], v149 offset:32768
	ds_read_b128 v[182:185], v149 offset:33792
	ds_read_b128 v[186:189], v149 offset:34816
	ds_read_b128 v[190:193], v149 offset:35840
	ds_read_b128 v[204:207], v149 offset:36864
	ds_read_b128 v[208:211], v149 offset:37888
	ds_read_b128 v[212:215], v149 offset:38912
	ds_read_b128 v[216:219], v149 offset:39936
	global_load_lds_dwordx4 v[226:227], off
	v_lshl_add_u64 v[226:227], s[20:21], 0, v[132:133]
	s_mov_b32 m0, s53
	s_nop 0
	global_load_lds_dwordx4 v[226:227], off
	s_waitcnt vmcnt(8)
	s_waitcnt lgkmcnt(0)
	s_barrier
	s_waitcnt lgkmcnt(0)
	v_mfma_f32_16x16x32_bf16 v[126:129], v[140:143], v[178:181], v[126:129]
	v_mfma_f32_16x16x32_bf16 v[122:125], v[154:157], v[178:181], v[122:125]
	v_mfma_f32_16x16x32_bf16 v[110:113], v[140:143], v[186:189], v[110:113]
	v_mfma_f32_16x16x32_bf16 v[106:109], v[154:157], v[186:189], v[106:109]
	v_mfma_f32_16x16x32_bf16 v[94:97], v[140:143], v[204:207], v[94:97]
	v_mfma_f32_16x16x32_bf16 v[90:93], v[154:157], v[204:207], v[90:93]
	v_mfma_f32_16x16x32_bf16 v[78:81], v[140:143], v[212:215], v[78:81]
	v_mfma_f32_16x16x32_bf16 v[74:77], v[154:157], v[212:215], v[74:77]
	v_mfma_f32_16x16x32_bf16 v[126:129], v[150:153], v[182:185], v[126:129]
	v_mfma_f32_16x16x32_bf16 v[122:125], v[158:161], v[182:185], v[122:125]
	v_mfma_f32_16x16x32_bf16 v[110:113], v[150:153], v[190:193], v[110:113]
	v_mfma_f32_16x16x32_bf16 v[106:109], v[158:161], v[190:193], v[106:109]
	v_mfma_f32_16x16x32_bf16 v[94:97], v[150:153], v[208:211], v[94:97]
	v_mfma_f32_16x16x32_bf16 v[90:93], v[158:161], v[208:211], v[90:93]
	v_mfma_f32_16x16x32_bf16 v[78:81], v[150:153], v[216:219], v[78:81]
	v_mfma_f32_16x16x32_bf16 v[74:77], v[158:161], v[216:219], v[74:77]
	v_mfma_f32_16x16x32_bf16 v[118:121], v[162:165], v[178:181], v[118:121]
	v_mfma_f32_16x16x32_bf16 v[114:117], v[170:173], v[178:181], v[114:117]
	v_mfma_f32_16x16x32_bf16 v[102:105], v[162:165], v[186:189], v[102:105]
	v_mfma_f32_16x16x32_bf16 v[98:101], v[170:173], v[186:189], v[98:101]
	v_mfma_f32_16x16x32_bf16 v[86:89], v[162:165], v[204:207], v[86:89]
	v_mfma_f32_16x16x32_bf16 v[82:85], v[170:173], v[204:207], v[82:85]
	v_mfma_f32_16x16x32_bf16 v[70:73], v[162:165], v[212:215], v[70:73]
	v_mfma_f32_16x16x32_bf16 v[66:69], v[170:173], v[212:215], v[66:69]
	v_mfma_f32_16x16x32_bf16 v[118:121], v[166:169], v[182:185], v[118:121]
	v_mfma_f32_16x16x32_bf16 v[114:117], v[174:177], v[182:185], v[114:117]
	v_mfma_f32_16x16x32_bf16 v[102:105], v[166:169], v[190:193], v[102:105]
	v_mfma_f32_16x16x32_bf16 v[98:101], v[174:177], v[190:193], v[98:101]
	v_mfma_f32_16x16x32_bf16 v[86:89], v[166:169], v[208:211], v[86:89]
	v_mfma_f32_16x16x32_bf16 v[82:85], v[174:177], v[208:211], v[82:85]
	v_mfma_f32_16x16x32_bf16 v[70:73], v[166:169], v[216:219], v[70:73]
	v_mfma_f32_16x16x32_bf16 v[66:69], v[174:177], v[216:219], v[66:69]
	s_barrier
; #define PG8_STAGE(bufoff, gbase, voff) do { _Pragma("unroll") for (int _i = 0; _i < 2; ++_i) \
;         __builtin_amdgcn_global_load_lds((const unsigned*)((const char*)(gbase) + (voff)[_i]), (PG8_LAS unsigned*)(lds + (bufoff) + ldsw + _i * 8192), 16, 0, 0); } while (0)
; #define PG8_LDA(dst, b, h) do { _Pragma("unroll") for (int m = 0; m < 4; ++m) _Pragma("unroll") for (int k = 0; k < 2; ++k) dst[m][k] = *(const PG8_LAS bf16x8*)(lds + PG8_SA(b, h) + aoff + m * 2048 + k * 1024); } while (0)
; #define PG8_MMA(ai, bj, At, Bt) do { __builtin_amdgcn_s_setprio(1); _Pragma("unroll") for (int m = 0; m < 4; ++m) _Pragma("unroll") for (int n = 0; n < 2; ++n) _Pragma("unroll") for (int k = 0; k < 2; ++k) \
;         acc[ai][bj][m][n] = __builtin_amdgcn_mfma_f32_16x16x32_bf16(Bt[n][k], At[m][k], acc[ai][bj][m][n], 0, 0, 0); __builtin_amdgcn_s_setprio(0); } while (0)
; #define PG8_WAIT_V(n) asm volatile("s_waitcnt vmcnt(" #n ")" ::: "memory")
; #define PG8_WAIT_L(n) asm volatile("s_waitcnt lgkmcnt(" #n ")" ::: "memory")
; #define PG8_BAR __builtin_amdgcn_s_barrier()
; #define PG8_SCHED __builtin_amdgcn_sched_barrier(0)
; template <class Epi, class Sched, bool ALIGN_EPI = false, bool SP2 = false>
; __device__ __forceinline__ void gemm_phase(PG8_LAS unsigned char* lds, const Gemm g, const Sched& S, const Epi& E, int tid_in) {
;     ...
;             PG8_LDA(At, 1, 1); PG8_STAGE(PG8_SB(1, 0), b3, voffB); PG8_STAGE(PG8_SB(1, 1), b3 + hstep, voffB); PG8_STAGE(PG8_SA(1, 0), a3, voffA);
;             PG8_WAIT_V(8); PG8_WAIT_L(0); PG8_BAR; PG8_MMA(1, 0, At, B0); PG8_MMA(1, 1, At, B1); PG8_BAR; PG8_SCHED;
	s_add_i32 s15, s15, s49
	v_lshl_add_u64 v[146:147], v[146:147], 0, s[28:29]
	s_mov_b32 m0, s15
	ds_read_b128 v[178:181], v149 offset:49152
	ds_read_b128 v[182:185], v149 offset:50176
	ds_read_b128 v[186:189], v149 offset:51200
	ds_read_b128 v[190:193], v149 offset:52224
	ds_read_b128 v[204:207], v149 offset:53248
	ds_read_b128 v[208:211], v149 offset:54272
	ds_read_b128 v[212:215], v149 offset:55296
	ds_read_b128 v[216:219], v149 offset:56320
	global_load_lds_dwordx4 v[146:147], off
	v_lshl_add_u64 v[146:147], v[194:195], 0, s[28:29]
	s_add_i32 m0, s15, 0x2000
	s_add_i32 s15, s63, s49
	global_load_lds_dwordx4 v[146:147], off
	v_lshl_add_u64 v[146:147], v[200:201], 0, s[28:29]
	s_mov_b32 m0, s15
	s_nop 0
	global_load_lds_dwordx4 v[146:147], off
	v_lshl_add_u64 v[146:147], v[220:221], 0, s[28:29]
	s_add_i32 m0, s15, 0x2000
	s_nop 0
	global_load_lds_dwordx4 v[146:147], off
	v_lshl_add_u64 v[146:147], v[222:223], 0, s[28:29]
	s_mov_b32 m0, s54
	s_nop 0
	global_load_lds_dwordx4 v[146:147], off
	v_lshl_add_u64 v[146:147], v[224:225], 0, s[28:29]
	s_mov_b32 m0, s55
	s_nop 0
	global_load_lds_dwordx4 v[146:147], off
	s_waitcnt vmcnt(8)
	s_waitcnt lgkmcnt(0)
	s_barrier
	s_waitcnt lgkmcnt(0)
	v_mfma_f32_16x16x32_bf16 v[62:65], v[140:143], v[178:181], v[62:65]
	v_mfma_f32_16x16x32_bf16 v[58:61], v[154:157], v[178:181], v[58:61]
	v_mfma_f32_16x16x32_bf16 v[46:49], v[140:143], v[186:189], v[46:49]
	v_mfma_f32_16x16x32_bf16 v[42:45], v[154:157], v[186:189], v[42:45]
	v_mfma_f32_16x16x32_bf16 v[30:33], v[140:143], v[204:207], v[30:33]
	v_mfma_f32_16x16x32_bf16 v[26:29], v[154:157], v[204:207], v[26:29]
	v_mfma_f32_16x16x32_bf16 v[14:17], v[140:143], v[212:215], v[14:17]
	v_mfma_f32_16x16x32_bf16 v[10:13], v[154:157], v[212:215], v[10:13]
	v_mfma_f32_16x16x32_bf16 v[62:65], v[150:153], v[182:185], v[62:65]
	v_mfma_f32_16x16x32_bf16 v[58:61], v[158:161], v[182:185], v[58:61]
	v_mfma_f32_16x16x32_bf16 v[46:49], v[150:153], v[190:193], v[46:49]
	v_mfma_f32_16x16x32_bf16 v[42:45], v[158:161], v[190:193], v[42:45]
	v_mfma_f32_16x16x32_bf16 v[30:33], v[150:153], v[208:211], v[30:33]
	v_mfma_f32_16x16x32_bf16 v[26:29], v[158:161], v[208:211], v[26:29]
	v_mfma_f32_16x16x32_bf16 v[14:17], v[150:153], v[216:219], v[14:17]
	v_mfma_f32_16x16x32_bf16 v[10:13], v[158:161], v[216:219], v[10:13]
	v_mfma_f32_16x16x32_bf16 v[54:57], v[162:165], v[178:181], v[54:57]
	v_mfma_f32_16x16x32_bf16 v[50:53], v[170:173], v[178:181], v[50:53]
	v_mfma_f32_16x16x32_bf16 v[38:41], v[162:165], v[186:189], v[38:41]
	v_mfma_f32_16x16x32_bf16 v[34:37], v[170:173], v[186:189], v[34:37]
	v_mfma_f32_16x16x32_bf16 v[22:25], v[162:165], v[204:207], v[22:25]
	v_mfma_f32_16x16x32_bf16 v[18:21], v[170:173], v[204:207], v[18:21]
	v_mfma_f32_16x16x32_bf16 v[6:9], v[162:165], v[212:215], v[6:9]
	v_mfma_f32_16x16x32_bf16 v[2:5], v[170:173], v[212:215], v[2:5]
	v_mfma_f32_16x16x32_bf16 v[54:57], v[166:169], v[182:185], v[54:57]
	v_mfma_f32_16x16x32_bf16 v[50:53], v[174:177], v[182:185], v[50:53]
	v_mfma_f32_16x16x32_bf16 v[38:41], v[166:169], v[190:193], v[38:41]
	v_mfma_f32_16x16x32_bf16 v[34:37], v[174:177], v[190:193], v[34:37]
	v_mfma_f32_16x16x32_bf16 v[22:25], v[166:169], v[208:211], v[22:25]
	v_mfma_f32_16x16x32_bf16 v[18:21], v[174:177], v[208:211], v[18:21]
	v_mfma_f32_16x16x32_bf16 v[6:9], v[166:169], v[216:219], v[6:9]
	v_mfma_f32_16x16x32_bf16 v[2:5], v[174:177], v[216:219], v[2:5]
	s_barrier
	s_add_u32 s18, s18, 0x100
	s_addc_u32 s19, s19, 0
	s_add_u32 s12, s12, 0x100
	s_addc_u32 s13, s13, 0
	s_cmp_ge_i32 s62, s56
	s_mov_b32 s15, s62
	s_cbranch_scc0 .LBB0_108
	s_setprio 0
	v_readlane_b32 s62, v254, 62
	v_readlane_b32 s63, v254, 63
	s_movk_i32 s64, 0x6000
	v_readlane_b32 s65, v255, 9

; template <class Epi, class Sched, bool ALIGN_EPI = false, bool SP2 = false>
; __device__ __forceinline__ void gemm_phase(PG8_LAS unsigned char* lds, const Gemm g, const Sched& S, const Epi& E, int tid_in) {
;     ...
;     f32x4 acc[2][2][4][2];
; #pragma unroll
;     for (int a = 0; a < 2; ++a)
; #pragma unroll
;         for (int b = 0; b < 2; ++b)
; #pragma unroll
;             for (int m = 0; m < 4; ++m)
; #pragma unroll
;                 for (int n = 0; n < 2; ++n) acc[a][b][m][n] = (f32x4){0.f, 0.f, 0.f, 0.f};
;     bf16x8 At[4][2], B0[2][2], B1[2][2];
;     const char* cA = (const char*)g.A + (size_t)cur.pm * tstepA + a_unit_off(g, cur.pn); const char* cB = (const char*)g.Bt + (size_t)cur.pn * tstepB;
.LBB0_274:
	s_ashr_i32 s49, s48, 31
	s_lshl_b64 s[12:13], s[48:49], 20
	s_add_u32 s52, s16, s12
	v_mov_b32_e32 v129, 0
	s_addc_u32 s53, s17, s13
	s_andn2_b64 vcc, exec, s[44:45]
	v_mov_b32_e32 v128, v129
	v_mov_b32_e32 v127, v129
	v_mov_b32_e32 v126, v129
	v_mov_b32_e32 v125, v129
	v_mov_b32_e32 v124, v129
	v_mov_b32_e32 v123, v129
	v_mov_b32_e32 v122, v129
	v_mov_b32_e32 v113, v129
	v_mov_b32_e32 v112, v129
	v_mov_b32_e32 v111, v129
	v_mov_b32_e32 v110, v129
	v_mov_b32_e32 v109, v129
	v_mov_b32_e32 v108, v129
	v_mov_b32_e32 v107, v129
	v_mov_b32_e32 v106, v129
	v_mov_b32_e32 v97, v129
	v_mov_b32_e32 v96, v129
	v_mov_b32_e32 v95, v129
	v_mov_b32_e32 v94, v129
	v_mov_b32_e32 v93, v129
	v_mov_b32_e32 v92, v129
	v_mov_b32_e32 v91, v129
	v_mov_b32_e32 v90, v129
	v_mov_b32_e32 v81, v129
	v_mov_b32_e32 v80, v129
	v_mov_b32_e32 v79, v129
	v_mov_b32_e32 v78, v129
	v_mov_b32_e32 v77, v129
	v_mov_b32_e32 v76, v129
	v_mov_b32_e32 v75, v129
	v_mov_b32_e32 v74, v129
	v_mov_b32_e32 v121, v129
	v_mov_b32_e32 v120, v129
	v_mov_b32_e32 v119, v129
	v_mov_b32_e32 v118, v129
	v_mov_b32_e32 v117, v129
	v_mov_b32_e32 v116, v129
	v_mov_b32_e32 v115, v129
	v_mov_b32_e32 v114, v129
	v_mov_b32_e32 v105, v129
	v_mov_b32_e32 v104, v129
	v_mov_b32_e32 v103, v129
	v_mov_b32_e32 v102, v129
	v_mov_b32_e32 v101, v129
	v_mov_b32_e32 v100, v129
	v_mov_b32_e32 v99, v129
	v_mov_b32_e32 v98, v129
	v_mov_b32_e32 v89, v129
	v_mov_b32_e32 v88, v129
	v_mov_b32_e32 v87, v129
	v_mov_b32_e32 v86, v129
	v_mov_b32_e32 v85, v129
	v_mov_b32_e32 v84, v129
	v_mov_b32_e32 v83, v129
	v_mov_b32_e32 v82, v129
	v_mov_b32_e32 v73, v129
	v_mov_b32_e32 v72, v129
	v_mov_b32_e32 v71, v129
	v_mov_b32_e32 v70, v129
	v_mov_b32_e32 v69, v129
	v_mov_b32_e32 v68, v129
	v_mov_b32_e32 v67, v129
	v_mov_b32_e32 v66, v129
	v_mov_b32_e32 v65, v129
	v_mov_b32_e32 v64, v129
	v_mov_b32_e32 v63, v129
	v_mov_b32_e32 v62, v129
	v_mov_b32_e32 v61, v129
	v_mov_b32_e32 v60, v129
	v_mov_b32_e32 v59, v129
	v_mov_b32_e32 v58, v129
	v_mov_b32_e32 v49, v129
	v_mov_b32_e32 v48, v129
	v_mov_b32_e32 v47, v129
	v_mov_b32_e32 v46, v129
	v_mov_b32_e32 v45, v129
	v_mov_b32_e32 v44, v129
	v_mov_b32_e32 v43, v129
	v_mov_b32_e32 v42, v129
	v_mov_b32_e32 v33, v129
	v_mov_b32_e32 v32, v129
	v_mov_b32_e32 v31, v129
	v_mov_b32_e32 v30, v129
	v_mov_b32_e32 v29, v129
	v_mov_b32_e32 v28, v129
	v_mov_b32_e32 v27, v129
	v_mov_b32_e32 v26, v129
	v_mov_b32_e32 v17, v129
	v_mov_b32_e32 v16, v129
	v_mov_b32_e32 v15, v129
	v_mov_b32_e32 v14, v129
	v_mov_b32_e32 v13, v129
	v_mov_b32_e32 v12, v129
	v_mov_b32_e32 v11, v129
	v_mov_b32_e32 v10, v129
	v_mov_b32_e32 v57, v129
	v_mov_b32_e32 v56, v129
	v_mov_b32_e32 v55, v129
	v_mov_b32_e32 v54, v129
	v_mov_b32_e32 v53, v129
	v_mov_b32_e32 v52, v129
	v_mov_b32_e32 v51, v129
	v_mov_b32_e32 v50, v129
	v_mov_b32_e32 v41, v129
	v_mov_b32_e32 v40, v129
	v_mov_b32_e32 v39, v129
	v_mov_b32_e32 v38, v129
	v_mov_b32_e32 v37, v129
	v_mov_b32_e32 v36, v129
	v_mov_b32_e32 v35, v129
	v_mov_b32_e32 v34, v129
	v_mov_b32_e32 v25, v129
	v_mov_b32_e32 v24, v129
	v_mov_b32_e32 v23, v129
	v_mov_b32_e32 v22, v129
	v_mov_b32_e32 v21, v129
	v_mov_b32_e32 v20, v129
	v_mov_b32_e32 v19, v129
	v_mov_b32_e32 v18, v129
	v_mov_b32_e32 v9, v129
	v_mov_b32_e32 v8, v129
	v_mov_b32_e32 v7, v129
	v_mov_b32_e32 v6, v129
	v_mov_b32_e32 v5, v129
	v_mov_b32_e32 v4, v129
	v_mov_b32_e32 v3, v129
	v_mov_b32_e32 v2, v129
	s_cbranch_vccnz .LBB0_277
	s_and_b64 s[12:13], s[56:57], exec
	s_cselect_b32 s12, s53, s39
	s_cselect_b32 s13, s52, s38
	s_add_u32 s38, s38, 0x80080
	s_addc_u32 s39, s39, 0
	s_add_u32 s21, s54, 0x100
	v_mov_b32_e32 v2, 0
	s_addc_u32 s49, s55, 0
	s_mov_b32 s15, 0
	v_mov_b32_e32 v3, v2
	v_mov_b32_e32 v4, v2
	v_mov_b32_e32 v5, v2
	v_mov_b32_e32 v6, v2
	v_mov_b32_e32 v7, v2
	v_mov_b32_e32 v8, v2
	v_mov_b32_e32 v9, v2
	v_mov_b32_e32 v18, v2
	v_mov_b32_e32 v19, v2
	v_mov_b32_e32 v20, v2
	v_mov_b32_e32 v21, v2
	v_mov_b32_e32 v22, v2
	v_mov_b32_e32 v23, v2
	v_mov_b32_e32 v24, v2
	v_mov_b32_e32 v25, v2
	v_mov_b32_e32 v34, v2
	v_mov_b32_e32 v35, v2
	v_mov_b32_e32 v36, v2
	v_mov_b32_e32 v37, v2
	v_mov_b32_e32 v38, v2
	v_mov_b32_e32 v39, v2
	v_mov_b32_e32 v40, v2
	v_mov_b32_e32 v41, v2
	v_mov_b32_e32 v50, v2
	v_mov_b32_e32 v51, v2
	v_mov_b32_e32 v52, v2
	v_mov_b32_e32 v53, v2
	v_mov_b32_e32 v54, v2
	v_mov_b32_e32 v55, v2
	v_mov_b32_e32 v56, v2
	v_mov_b32_e32 v57, v2
	v_mov_b32_e32 v10, v2
	v_mov_b32_e32 v11, v2
	v_mov_b32_e32 v12, v2
	v_mov_b32_e32 v13, v2
	v_mov_b32_e32 v14, v2
	v_mov_b32_e32 v15, v2
	v_mov_b32_e32 v16, v2
	v_mov_b32_e32 v17, v2
	v_mov_b32_e32 v26, v2
	v_mov_b32_e32 v27, v2
	v_mov_b32_e32 v28, v2
	v_mov_b32_e32 v29, v2
	v_mov_b32_e32 v30, v2
	v_mov_b32_e32 v31, v2
	v_mov_b32_e32 v32, v2
	v_mov_b32_e32 v33, v2
	v_mov_b32_e32 v42, v2
	v_mov_b32_e32 v43, v2
	v_mov_b32_e32 v44, v2
	v_mov_b32_e32 v45, v2
	v_mov_b32_e32 v46, v2
	v_mov_b32_e32 v47, v2
	v_mov_b32_e32 v48, v2
	v_mov_b32_e32 v49, v2
	v_mov_b32_e32 v58, v2
	v_mov_b32_e32 v59, v2
	v_mov_b32_e32 v60, v2
	v_mov_b32_e32 v61, v2
	v_mov_b32_e32 v62, v2
	v_mov_b32_e32 v63, v2
	v_mov_b32_e32 v64, v2
	v_mov_b32_e32 v65, v2
	v_mov_b32_e32 v66, v2
	v_mov_b32_e32 v67, v2
	v_mov_b32_e32 v68, v2
	v_mov_b32_e32 v69, v2
	v_mov_b32_e32 v70, v2
	v_mov_b32_e32 v71, v2
	v_mov_b32_e32 v72, v2
	v_mov_b32_e32 v73, v2
	v_mov_b32_e32 v82, v2
	v_mov_b32_e32 v83, v2
	v_mov_b32_e32 v84, v2
	v_mov_b32_e32 v85, v2
	v_mov_b32_e32 v86, v2
	v_mov_b32_e32 v87, v2
	v_mov_b32_e32 v88, v2
	v_mov_b32_e32 v89, v2
	v_mov_b32_e32 v98, v2
	v_mov_b32_e32 v99, v2
	v_mov_b32_e32 v100, v2
	v_mov_b32_e32 v101, v2
	v_mov_b32_e32 v102, v2
	v_mov_b32_e32 v103, v2
	v_mov_b32_e32 v104, v2
	v_mov_b32_e32 v105, v2
	v_mov_b32_e32 v114, v2
	v_mov_b32_e32 v115, v2
	v_mov_b32_e32 v116, v2
	v_mov_b32_e32 v117, v2
	v_mov_b32_e32 v118, v2
	v_mov_b32_e32 v119, v2
	v_mov_b32_e32 v120, v2
	v_mov_b32_e32 v121, v2
	v_mov_b32_e32 v74, v2
	v_mov_b32_e32 v75, v2
	v_mov_b32_e32 v76, v2
	v_mov_b32_e32 v77, v2
	v_mov_b32_e32 v78, v2
	v_mov_b32_e32 v79, v2
	v_mov_b32_e32 v80, v2
	v_mov_b32_e32 v81, v2
	v_mov_b32_e32 v90, v2
	v_mov_b32_e32 v91, v2
	v_mov_b32_e32 v92, v2
	v_mov_b32_e32 v93, v2
	v_mov_b32_e32 v94, v2
	v_mov_b32_e32 v95, v2
	v_mov_b32_e32 v96, v2
	v_mov_b32_e32 v97, v2
	v_mov_b32_e32 v106, v2
	v_mov_b32_e32 v107, v2
	v_mov_b32_e32 v108, v2
	v_mov_b32_e32 v109, v2
	v_mov_b32_e32 v110, v2
	v_mov_b32_e32 v111, v2
	v_mov_b32_e32 v112, v2
	v_mov_b32_e32 v113, v2
	v_mov_b32_e32 v122, v2
	v_mov_b32_e32 v123, v2
	v_mov_b32_e32 v124, v2
	v_mov_b32_e32 v125, v2
	v_mov_b32_e32 v126, v2
	v_mov_b32_e32 v127, v2
	v_mov_b32_e32 v128, v2
	v_mov_b32_e32 v129, v2
	s_cmp_ge_u32 s84, 0x100
	s_cbranch_scc0 .Lprio_skip276
	s_setprio 1
; #define PG8_STAGE(bufoff, gbase, voff) do { _Pragma("unroll") for (int _i = 0; _i < 2; ++_i) \
;         __builtin_amdgcn_global_load_lds((const unsigned*)((const char*)(gbase) + (voff)[_i]), (PG8_LAS unsigned*)(lds + (bufoff) + ldsw + _i * 8192), 16, 0, 0); } while (0)
; #define PG8_LDA(dst, b, h) do { _Pragma("unroll") for (int m = 0; m < 4; ++m) _Pragma("unroll") for (int k = 0; k < 2; ++k) dst[m][k] = *(const PG8_LAS bf16x8*)(lds + PG8_SA(b, h) + aoff + m * 2048 + k * 1024); } while (0)
; #define PG8_LDB(dst, b, h) do { _Pragma("unroll") for (int n = 0; n < 2; ++n) _Pragma("unroll") for (int k = 0; k < 2; ++k) dst[n][k] = *(const PG8_LAS bf16x8*)(lds + PG8_SB(b, h) + boff + n * 2048 + k * 1024); } while (0)
; #define PG8_MMA(ai, bj, At, Bt) do { __builtin_amdgcn_s_setprio(1); _Pragma("unroll") for (int m = 0; m < 4; ++m) _Pragma("unroll") for (int n = 0; n < 2; ++n) _Pragma("unroll") for (int k = 0; k < 2; ++k) \
;         acc[ai][bj][m][n] = __builtin_amdgcn_mfma_f32_16x16x32_bf16(Bt[n][k], At[m][k], acc[ai][bj][m][n], 0, 0, 0); __builtin_amdgcn_s_setprio(0); } while (0)
; #define PG8_WAIT_V(n) asm volatile("s_waitcnt vmcnt(" #n ")" ::: "memory")
; #define PG8_BAR __builtin_amdgcn_s_barrier()
; template <class Epi, class Sched, bool ALIGN_EPI = false, bool SP2 = false>
; __device__ __forceinline__ void gemm_phase(PG8_LAS unsigned char* lds, const Gemm g, const Sched& S, const Epi& E, int tid_in) {
;     ...
;         for (int t = 0; t < nt; t += 2) {
;             const bool last = (t == nt - 2);
;             const char* a1 = cA + (size_t)(t + 1) * kstep;
;             const char* a2 = last ? nA : cA + (size_t)(t + 2) * kstep; const char* b2 = last ? nB : cB + (size_t)(t + 2) * kstep;
;             const char* a3 = a2 + kstep; const char* b3 = b2 + kstep;
;             if (last && has_next) S.a_ready(nxt);
;             if constexpr (SP2) {
;             PG8_LDB(B0, 0, 0); PG8_LDB(B1, 0, 1); PG8_SCHED; PG8_LDA(At, 0, 0); PG8_STAGE(PG8_SA(1, 1), a1 + hstepA, voffA);
;             PG8_WAIT_V(8); PG8_WAIT_L(0); PG8_BAR; PG8_MMA(0, 0, At, B0); PG8_MMA(0, 1, At, B1); PG8_BAR; PG8_SCHED;
;             PG8_LDA(At, 0, 1); PG8_STAGE(PG8_SB(0, 0), b2, voffB); PG8_STAGE(PG8_SB(0, 1), b2 + hstep, voffB); PG8_STAGE(PG8_SA(0, 0), a2, voffA);
;             PG8_WAIT_V(8); PG8_WAIT_L(0); PG8_BAR; PG8_MMA(1, 0, At, B0); PG8_MMA(1, 1, At, B1); PG8_BAR; PG8_SCHED;
.Lprio_skip276:
.LBB0_276:
	s_add_i32 s56, s15, 2
	s_add_u32 s54, s38, 0xfff80080
	s_addc_u32 s55, s39, -1
	s_add_i32 s57, 0, 0x10000
	s_cmp_eq_u32 s68, s15
	s_cselect_b32 s55, s12, s55
	s_cselect_b32 s54, s13, s54
	v_add_u32_e32 v0, s57, v170
	s_cselect_b32 s75, s51, s49
	s_cselect_b32 s74, s50, s21
	s_add_i32 s15, 0, 0x14000
	ds_read_b128 v[130:133], v0
	ds_read_b128 v[152:155], v0 offset:1024
	ds_read_b128 v[178:181], v0 offset:2048
	ds_read_b128 v[182:185], v0 offset:3072
	v_add_u32_e32 v0, s15, v170
	ds_read_b128 v[186:189], v0
	ds_read_b128 v[190:193], v0 offset:1024
	ds_read_b128 v[204:207], v0 offset:2048
	ds_read_b128 v[208:211], v0 offset:3072
	v_lshl_add_u64 v[146:147], s[38:39], 0, v[148:149]
	s_add_i32 m0, s61, 0xc000
	ds_read_b128 v[212:215], v176
	ds_read_b128 v[216:219], v176 offset:1024
	ds_read_b128 v[220:223], v176 offset:2048
	ds_read_b128 v[224:227], v176 offset:3072
	ds_read_b128 v[228:231], v176 offset:4096
	ds_read_b128 v[232:235], v176 offset:5120
	ds_read_b128 v[236:239], v176 offset:6144
	ds_read_b128 v[240:243], v176 offset:7168
	global_load_lds_dwordx4 v[146:147], off
	v_lshl_add_u64 v[146:147], s[38:39], 0, v[150:151]
	s_add_i32 m0, s61, 0xe000
	s_nop 0
	global_load_lds_dwordx4 v[146:147], off
	s_waitcnt vmcnt(8)
	s_waitcnt lgkmcnt(0)
	s_barrier
	s_waitcnt lgkmcnt(0)
	v_mfma_f32_16x16x32_bf16 v[126:129], v[130:133], v[212:215], v[126:129]
	v_mfma_f32_16x16x32_bf16 v[122:125], v[178:181], v[212:215], v[122:125]
	v_mfma_f32_16x16x32_bf16 v[110:113], v[130:133], v[220:223], v[110:113]
	v_mfma_f32_16x16x32_bf16 v[106:109], v[178:181], v[220:223], v[106:109]
	v_mfma_f32_16x16x32_bf16 v[94:97], v[130:133], v[228:231], v[94:97]
	v_mfma_f32_16x16x32_bf16 v[90:93], v[178:181], v[228:231], v[90:93]
	v_mfma_f32_16x16x32_bf16 v[78:81], v[130:133], v[236:239], v[78:81]
	v_mfma_f32_16x16x32_bf16 v[74:77], v[178:181], v[236:239], v[74:77]
	v_mfma_f32_16x16x32_bf16 v[126:129], v[152:155], v[216:219], v[126:129]
	v_mfma_f32_16x16x32_bf16 v[122:125], v[182:185], v[216:219], v[122:125]
	v_mfma_f32_16x16x32_bf16 v[110:113], v[152:155], v[224:227], v[110:113]
	v_mfma_f32_16x16x32_bf16 v[106:109], v[182:185], v[224:227], v[106:109]
	v_mfma_f32_16x16x32_bf16 v[94:97], v[152:155], v[232:235], v[94:97]
	v_mfma_f32_16x16x32_bf16 v[90:93], v[182:185], v[232:235], v[90:93]
	v_mfma_f32_16x16x32_bf16 v[78:81], v[152:155], v[240:243], v[78:81]
	v_mfma_f32_16x16x32_bf16 v[74:77], v[182:185], v[240:243], v[74:77]
	v_mfma_f32_16x16x32_bf16 v[118:121], v[186:189], v[212:215], v[118:121]
	v_mfma_f32_16x16x32_bf16 v[114:117], v[204:207], v[212:215], v[114:117]
	v_mfma_f32_16x16x32_bf16 v[102:105], v[186:189], v[220:223], v[102:105]
	v_mfma_f32_16x16x32_bf16 v[98:101], v[204:207], v[220:223], v[98:101]
	v_mfma_f32_16x16x32_bf16 v[86:89], v[186:189], v[228:231], v[86:89]
	v_mfma_f32_16x16x32_bf16 v[82:85], v[204:207], v[228:231], v[82:85]
	v_mfma_f32_16x16x32_bf16 v[70:73], v[186:189], v[236:239], v[70:73]
	v_mfma_f32_16x16x32_bf16 v[66:69], v[204:207], v[236:239], v[66:69]
	v_mfma_f32_16x16x32_bf16 v[118:121], v[190:193], v[216:219], v[118:121]
	v_mfma_f32_16x16x32_bf16 v[114:117], v[208:211], v[216:219], v[114:117]
	v_mfma_f32_16x16x32_bf16 v[102:105], v[190:193], v[224:227], v[102:105]
	v_mfma_f32_16x16x32_bf16 v[98:101], v[208:211], v[224:227], v[98:101]
	v_mfma_f32_16x16x32_bf16 v[86:89], v[190:193], v[232:235], v[86:89]
	v_mfma_f32_16x16x32_bf16 v[82:85], v[208:211], v[232:235], v[82:85]
	v_mfma_f32_16x16x32_bf16 v[70:73], v[190:193], v[240:243], v[70:73]
	v_mfma_f32_16x16x32_bf16 v[66:69], v[208:211], v[240:243], v[66:69]
	s_barrier
	s_add_i32 s57, s57, s60
	v_lshl_add_u64 v[146:147], s[74:75], 0, v[138:139]
	s_mov_b32 m0, s57
	ds_read_b128 v[212:215], v176 offset:16384
	ds_read_b128 v[216:219], v176 offset:17408
	ds_read_b128 v[220:223], v176 offset:18432
	ds_read_b128 v[224:227], v176 offset:19456
	ds_read_b128 v[228:231], v176 offset:20480
	ds_read_b128 v[232:235], v176 offset:21504
	ds_read_b128 v[236:239], v176 offset:22528
	ds_read_b128 v[240:243], v176 offset:23552
	global_load_lds_dwordx4 v[146:147], off
	s_add_i32 m0, s57, 0x2000
	v_lshl_add_u64 v[194:195], s[74:75], 0, v[140:141]
	s_add_u32 s74, s74, s0
	s_addc_u32 s75, s75, s1
	s_add_i32 s15, s15, s60
	global_load_lds_dwordx4 v[194:195], off
	v_lshl_add_u64 v[244:245], s[74:75], 0, v[138:139]
	s_mov_b32 m0, s15
	v_lshl_add_u64 v[246:247], s[74:75], 0, v[140:141]
	global_load_lds_dwordx4 v[244:245], off
	s_add_i32 m0, s15, 0x2000
	v_lshl_add_u64 v[248:249], s[54:55], 0, v[134:135]
	global_load_lds_dwordx4 v[246:247], off
	s_mov_b32 m0, s61
	v_lshl_add_u64 v[250:251], s[54:55], 0, v[136:137]
	global_load_lds_dwordx4 v[248:249], off
	s_mov_b32 m0, s62
	s_nop 0
	global_load_lds_dwordx4 v[250:251], off
	s_waitcnt vmcnt(8)
	s_waitcnt lgkmcnt(0)
	s_barrier
; #define PG8_STAGE(bufoff, gbase, voff) do { _Pragma("unroll") for (int _i = 0; _i < 2; ++_i) \
;         __builtin_amdgcn_global_load_lds((const unsigned*)((const char*)(gbase) + (voff)[_i]), (PG8_LAS unsigned*)(lds + (bufoff) + ldsw + _i * 8192), 16, 0, 0); } while (0)
; #define PG8_LDA(dst, b, h) do { _Pragma("unroll") for (int m = 0; m < 4; ++m) _Pragma("unroll") for (int k = 0; k < 2; ++k) dst[m][k] = *(const PG8_LAS bf16x8*)(lds + PG8_SA(b, h) + aoff + m * 2048 + k * 1024); } while (0)
; #define PG8_LDB(dst, b, h) do { _Pragma("unroll") for (int n = 0; n < 2; ++n) _Pragma("unroll") for (int k = 0; k < 2; ++k) dst[n][k] = *(const PG8_LAS bf16x8*)(lds + PG8_SB(b, h) + boff + n * 2048 + k * 1024); } while (0)
; #define PG8_MMA(ai, bj, At, Bt) do { __builtin_amdgcn_s_setprio(1); _Pragma("unroll") for (int m = 0; m < 4; ++m) _Pragma("unroll") for (int n = 0; n < 2; ++n) _Pragma("unroll") for (int k = 0; k < 2; ++k) \
;         acc[ai][bj][m][n] = __builtin_amdgcn_mfma_f32_16x16x32_bf16(Bt[n][k], At[m][k], acc[ai][bj][m][n], 0, 0, 0); __builtin_amdgcn_s_setprio(0); } while (0)
; #define PG8_WAIT_V(n) asm volatile("s_waitcnt vmcnt(" #n ")" ::: "memory")
; #define PG8_WAIT_L(n) asm volatile("s_waitcnt lgkmcnt(" #n ")" ::: "memory")
; #define PG8_BAR __builtin_amdgcn_s_barrier()
; #define PG8_SCHED __builtin_amdgcn_sched_barrier(0)
; template <class Epi, class Sched, bool ALIGN_EPI = false, bool SP2 = false>
; __device__ __forceinline__ void gemm_phase(PG8_LAS unsigned char* lds, const Gemm g, const Sched& S, const Epi& E, int tid_in) {
;     ...
;             PG8_WAIT_V(8); PG8_WAIT_L(0); PG8_BAR; PG8_MMA(1, 0, At, B0); PG8_MMA(1, 1, At, B1); PG8_BAR; PG8_SCHED;
;             PG8_LDB(B0, 1, 0); PG8_LDB(B1, 1, 1); PG8_SCHED; PG8_LDA(At, 1, 0); PG8_STAGE(PG8_SA(0, 1), a2 + hstepA, voffA);
;             PG8_WAIT_V(8); PG8_WAIT_L(0); PG8_BAR; PG8_MMA(0, 0, At, B0); PG8_MMA(0, 1, At, B1); PG8_BAR; PG8_SCHED;
	s_waitcnt lgkmcnt(0)
	v_mfma_f32_16x16x32_bf16 v[62:65], v[130:133], v[212:215], v[62:65]
	v_mfma_f32_16x16x32_bf16 v[58:61], v[178:181], v[212:215], v[58:61]
	v_mfma_f32_16x16x32_bf16 v[46:49], v[130:133], v[220:223], v[46:49]
	v_mfma_f32_16x16x32_bf16 v[42:45], v[178:181], v[220:223], v[42:45]
	v_mfma_f32_16x16x32_bf16 v[30:33], v[130:133], v[228:231], v[30:33]
	v_mfma_f32_16x16x32_bf16 v[26:29], v[178:181], v[228:231], v[26:29]
	v_mfma_f32_16x16x32_bf16 v[14:17], v[130:133], v[236:239], v[14:17]
	v_mfma_f32_16x16x32_bf16 v[10:13], v[178:181], v[236:239], v[10:13]
	v_mfma_f32_16x16x32_bf16 v[62:65], v[152:155], v[216:219], v[62:65]
	v_mfma_f32_16x16x32_bf16 v[58:61], v[182:185], v[216:219], v[58:61]
	v_mfma_f32_16x16x32_bf16 v[46:49], v[152:155], v[224:227], v[46:49]
	v_mfma_f32_16x16x32_bf16 v[42:45], v[182:185], v[224:227], v[42:45]
	v_mfma_f32_16x16x32_bf16 v[30:33], v[152:155], v[232:235], v[30:33]
	v_mfma_f32_16x16x32_bf16 v[26:29], v[182:185], v[232:235], v[26:29]
	v_mfma_f32_16x16x32_bf16 v[14:17], v[152:155], v[240:243], v[14:17]
	v_mfma_f32_16x16x32_bf16 v[10:13], v[182:185], v[240:243], v[10:13]
	v_mfma_f32_16x16x32_bf16 v[54:57], v[186:189], v[212:215], v[54:57]
	v_mfma_f32_16x16x32_bf16 v[50:53], v[204:207], v[212:215], v[50:53]
	v_mfma_f32_16x16x32_bf16 v[38:41], v[186:189], v[220:223], v[38:41]
	v_mfma_f32_16x16x32_bf16 v[34:37], v[204:207], v[220:223], v[34:37]
	v_mfma_f32_16x16x32_bf16 v[22:25], v[186:189], v[228:231], v[22:25]
	v_mfma_f32_16x16x32_bf16 v[18:21], v[204:207], v[228:231], v[18:21]
	v_mfma_f32_16x16x32_bf16 v[6:9], v[186:189], v[236:239], v[6:9]
	v_mfma_f32_16x16x32_bf16 v[2:5], v[204:207], v[236:239], v[2:5]
	v_mfma_f32_16x16x32_bf16 v[54:57], v[190:193], v[216:219], v[54:57]
	v_mfma_f32_16x16x32_bf16 v[50:53], v[208:211], v[216:219], v[50:53]
	v_mfma_f32_16x16x32_bf16 v[38:41], v[190:193], v[224:227], v[38:41]
	v_mfma_f32_16x16x32_bf16 v[34:37], v[208:211], v[224:227], v[34:37]
	v_mfma_f32_16x16x32_bf16 v[22:25], v[190:193], v[232:235], v[22:25]
	v_mfma_f32_16x16x32_bf16 v[18:21], v[208:211], v[232:235], v[18:21]
	v_mfma_f32_16x16x32_bf16 v[6:9], v[190:193], v[240:243], v[6:9]
	v_mfma_f32_16x16x32_bf16 v[2:5], v[208:211], v[240:243], v[2:5]
	s_barrier
	s_add_i32 s15, 0, 0x18000
	v_add_u32_e32 v0, s15, v170
	s_add_i32 s57, 0, 0x1c000
	ds_read_b128 v[130:133], v0
	ds_read_b128 v[152:155], v0 offset:1024
	ds_read_b128 v[178:181], v0 offset:2048
	ds_read_b128 v[182:185], v0 offset:3072
	v_add_u32_e32 v0, s57, v170
	ds_read_b128 v[186:189], v0
	ds_read_b128 v[190:193], v0 offset:1024
	ds_read_b128 v[204:207], v0 offset:2048
	ds_read_b128 v[208:211], v0 offset:3072
	s_add_u32 s54, s54, 0x80000
	s_addc_u32 s55, s55, 0
	s_mov_b32 m0, s63
	v_lshl_add_u64 v[200:201], s[54:55], 0, v[134:135]
	ds_read_b128 v[212:215], v176 offset:32768
	ds_read_b128 v[216:219], v176 offset:33792
	ds_read_b128 v[220:223], v176 offset:34816
	ds_read_b128 v[224:227], v176 offset:35840
	ds_read_b128 v[228:231], v176 offset:36864
	ds_read_b128 v[232:235], v176 offset:37888
	ds_read_b128 v[236:239], v176 offset:38912
	ds_read_b128 v[240:243], v176 offset:39936
	global_load_lds_dwordx4 v[200:201], off
	v_lshl_add_u64 v[200:201], s[54:55], 0, v[136:137]
	s_mov_b32 m0, s64
	s_nop 0
	global_load_lds_dwordx4 v[200:201], off
	s_waitcnt vmcnt(8)
	s_waitcnt lgkmcnt(0)
	s_barrier
	s_waitcnt lgkmcnt(0)
	v_mfma_f32_16x16x32_bf16 v[126:129], v[130:133], v[212:215], v[126:129]
	v_mfma_f32_16x16x32_bf16 v[122:125], v[178:181], v[212:215], v[122:125]
	v_mfma_f32_16x16x32_bf16 v[110:113], v[130:133], v[220:223], v[110:113]
	v_mfma_f32_16x16x32_bf16 v[106:109], v[178:181], v[220:223], v[106:109]
	v_mfma_f32_16x16x32_bf16 v[94:97], v[130:133], v[228:231], v[94:97]
	v_mfma_f32_16x16x32_bf16 v[90:93], v[178:181], v[228:231], v[90:93]
	v_mfma_f32_16x16x32_bf16 v[78:81], v[130:133], v[236:239], v[78:81]
	v_mfma_f32_16x16x32_bf16 v[74:77], v[178:181], v[236:239], v[74:77]
	v_mfma_f32_16x16x32_bf16 v[126:129], v[152:155], v[216:219], v[126:129]
	v_mfma_f32_16x16x32_bf16 v[122:125], v[182:185], v[216:219], v[122:125]
	v_mfma_f32_16x16x32_bf16 v[110:113], v[152:155], v[224:227], v[110:113]
	v_mfma_f32_16x16x32_bf16 v[106:109], v[182:185], v[224:227], v[106:109]
	v_mfma_f32_16x16x32_bf16 v[94:97], v[152:155], v[232:235], v[94:97]
	v_mfma_f32_16x16x32_bf16 v[90:93], v[182:185], v[232:235], v[90:93]
	v_mfma_f32_16x16x32_bf16 v[78:81], v[152:155], v[240:243], v[78:81]
	v_mfma_f32_16x16x32_bf16 v[74:77], v[182:185], v[240:243], v[74:77]
	v_mfma_f32_16x16x32_bf16 v[118:121], v[186:189], v[212:215], v[118:121]
	v_mfma_f32_16x16x32_bf16 v[114:117], v[204:207], v[212:215], v[114:117]
	v_mfma_f32_16x16x32_bf16 v[102:105], v[186:189], v[220:223], v[102:105]
	v_mfma_f32_16x16x32_bf16 v[98:101], v[204:207], v[220:223], v[98:101]
	v_mfma_f32_16x16x32_bf16 v[86:89], v[186:189], v[228:231], v[86:89]
	v_mfma_f32_16x16x32_bf16 v[82:85], v[204:207], v[228:231], v[82:85]
	v_mfma_f32_16x16x32_bf16 v[70:73], v[186:189], v[236:239], v[70:73]
	v_mfma_f32_16x16x32_bf16 v[66:69], v[204:207], v[236:239], v[66:69]
	v_mfma_f32_16x16x32_bf16 v[118:121], v[190:193], v[216:219], v[118:121]
	v_mfma_f32_16x16x32_bf16 v[114:117], v[208:211], v[216:219], v[114:117]
	v_mfma_f32_16x16x32_bf16 v[102:105], v[190:193], v[224:227], v[102:105]
	v_mfma_f32_16x16x32_bf16 v[98:101], v[208:211], v[224:227], v[98:101]
	v_mfma_f32_16x16x32_bf16 v[86:89], v[190:193], v[232:235], v[86:89]
	v_mfma_f32_16x16x32_bf16 v[82:85], v[208:211], v[232:235], v[82:85]
	v_mfma_f32_16x16x32_bf16 v[70:73], v[190:193], v[240:243], v[70:73]
	v_mfma_f32_16x16x32_bf16 v[66:69], v[208:211], v[240:243], v[66:69]
	s_barrier
; #define PG8_STAGE(bufoff, gbase, voff) do { _Pragma("unroll") for (int _i = 0; _i < 2; ++_i) \
;         __builtin_amdgcn_global_load_lds((const unsigned*)((const char*)(gbase) + (voff)[_i]), (PG8_LAS unsigned*)(lds + (bufoff) + ldsw + _i * 8192), 16, 0, 0); } while (0)
; #define PG8_LDA(dst, b, h) do { _Pragma("unroll") for (int m = 0; m < 4; ++m) _Pragma("unroll") for (int k = 0; k < 2; ++k) dst[m][k] = *(const PG8_LAS bf16x8*)(lds + PG8_SA(b, h) + aoff + m * 2048 + k * 1024); } while (0)
; #define PG8_MMA(ai, bj, At, Bt) do { __builtin_amdgcn_s_setprio(1); _Pragma("unroll") for (int m = 0; m < 4; ++m) _Pragma("unroll") for (int n = 0; n < 2; ++n) _Pragma("unroll") for (int k = 0; k < 2; ++k) \
;         acc[ai][bj][m][n] = __builtin_amdgcn_mfma_f32_16x16x32_bf16(Bt[n][k], At[m][k], acc[ai][bj][m][n], 0, 0, 0); __builtin_amdgcn_s_setprio(0); } while (0)
; #define PG8_WAIT_V(n) asm volatile("s_waitcnt vmcnt(" #n ")" ::: "memory")
; #define PG8_WAIT_L(n) asm volatile("s_waitcnt lgkmcnt(" #n ")" ::: "memory")
; #define PG8_BAR __builtin_amdgcn_s_barrier()
; #define PG8_SCHED __builtin_amdgcn_sched_barrier(0)
; template <class Epi, class Sched, bool ALIGN_EPI = false, bool SP2 = false>
; __device__ __forceinline__ void gemm_phase(PG8_LAS unsigned char* lds, const Gemm g, const Sched& S, const Epi& E, int tid_in) {
;     ...
;         for (int t = 0; t < nt; t += 2) {
;             const bool last = (t == nt - 2);
;             const char* a1 = cA + (size_t)(t + 1) * kstep;
;             const char* a2 = last ? nA : cA + (size_t)(t + 2) * kstep; const char* b2 = last ? nB : cB + (size_t)(t + 2) * kstep;
;             const char* a3 = a2 + kstep; const char* b3 = b2 + kstep;
;     ...
;             PG8_LDA(At, 1, 1); PG8_STAGE(PG8_SB(1, 0), b3, voffB); PG8_STAGE(PG8_SB(1, 1), b3 + hstep, voffB); PG8_STAGE(PG8_SA(1, 0), a3, voffA);
;             PG8_WAIT_V(8); PG8_WAIT_L(0); PG8_BAR; PG8_MMA(1, 0, At, B0); PG8_MMA(1, 1, At, B1); PG8_BAR; PG8_SCHED;
	s_add_i32 s15, s15, s60
	v_lshl_add_u64 v[146:147], v[146:147], 0, s[28:29]
	s_mov_b32 m0, s15
	ds_read_b128 v[212:215], v176 offset:49152
	ds_read_b128 v[216:219], v176 offset:50176
	ds_read_b128 v[220:223], v176 offset:51200
	ds_read_b128 v[224:227], v176 offset:52224
	ds_read_b128 v[228:231], v176 offset:53248
	ds_read_b128 v[232:235], v176 offset:54272
	ds_read_b128 v[236:239], v176 offset:55296
	ds_read_b128 v[240:243], v176 offset:56320
	global_load_lds_dwordx4 v[146:147], off
	v_lshl_add_u64 v[146:147], v[194:195], 0, s[28:29]
	s_add_i32 m0, s15, 0x2000
	s_add_i32 s15, s57, s60
	global_load_lds_dwordx4 v[146:147], off
	v_lshl_add_u64 v[146:147], v[244:245], 0, s[28:29]
	s_mov_b32 m0, s15
	s_nop 0
	global_load_lds_dwordx4 v[146:147], off
	v_lshl_add_u64 v[146:147], v[246:247], 0, s[28:29]
	s_add_i32 m0, s15, 0x2000
	s_nop 0
	global_load_lds_dwordx4 v[146:147], off
	v_lshl_add_u64 v[146:147], v[248:249], 0, s[28:29]
	s_mov_b32 m0, s65
	s_nop 0
	global_load_lds_dwordx4 v[146:147], off
	v_lshl_add_u64 v[146:147], v[250:251], 0, s[28:29]
	s_mov_b32 m0, s66
	s_nop 0
	global_load_lds_dwordx4 v[146:147], off
	s_waitcnt vmcnt(8)
	s_waitcnt lgkmcnt(0)
	s_barrier
	s_waitcnt lgkmcnt(0)
	v_mfma_f32_16x16x32_bf16 v[62:65], v[130:133], v[212:215], v[62:65]
	v_mfma_f32_16x16x32_bf16 v[58:61], v[178:181], v[212:215], v[58:61]
	v_mfma_f32_16x16x32_bf16 v[46:49], v[130:133], v[220:223], v[46:49]
	v_mfma_f32_16x16x32_bf16 v[42:45], v[178:181], v[220:223], v[42:45]
	v_mfma_f32_16x16x32_bf16 v[30:33], v[130:133], v[228:231], v[30:33]
	v_mfma_f32_16x16x32_bf16 v[26:29], v[178:181], v[228:231], v[26:29]
	v_mfma_f32_16x16x32_bf16 v[14:17], v[130:133], v[236:239], v[14:17]
	v_mfma_f32_16x16x32_bf16 v[10:13], v[178:181], v[236:239], v[10:13]
	v_mfma_f32_16x16x32_bf16 v[62:65], v[152:155], v[216:219], v[62:65]
	v_mfma_f32_16x16x32_bf16 v[58:61], v[182:185], v[216:219], v[58:61]
	v_mfma_f32_16x16x32_bf16 v[46:49], v[152:155], v[224:227], v[46:49]
	v_mfma_f32_16x16x32_bf16 v[42:45], v[182:185], v[224:227], v[42:45]
	v_mfma_f32_16x16x32_bf16 v[30:33], v[152:155], v[232:235], v[30:33]
	v_mfma_f32_16x16x32_bf16 v[26:29], v[182:185], v[232:235], v[26:29]
	v_mfma_f32_16x16x32_bf16 v[14:17], v[152:155], v[240:243], v[14:17]
	v_mfma_f32_16x16x32_bf16 v[10:13], v[182:185], v[240:243], v[10:13]
	v_mfma_f32_16x16x32_bf16 v[54:57], v[186:189], v[212:215], v[54:57]
	v_mfma_f32_16x16x32_bf16 v[50:53], v[204:207], v[212:215], v[50:53]
	v_mfma_f32_16x16x32_bf16 v[38:41], v[186:189], v[220:223], v[38:41]
	v_mfma_f32_16x16x32_bf16 v[34:37], v[204:207], v[220:223], v[34:37]
	v_mfma_f32_16x16x32_bf16 v[22:25], v[186:189], v[228:231], v[22:25]
	v_mfma_f32_16x16x32_bf16 v[18:21], v[204:207], v[228:231], v[18:21]
	v_mfma_f32_16x16x32_bf16 v[6:9], v[186:189], v[236:239], v[6:9]
	v_mfma_f32_16x16x32_bf16 v[2:5], v[204:207], v[236:239], v[2:5]
	v_mfma_f32_16x16x32_bf16 v[54:57], v[190:193], v[216:219], v[54:57]
	v_mfma_f32_16x16x32_bf16 v[50:53], v[208:211], v[216:219], v[50:53]
	v_mfma_f32_16x16x32_bf16 v[38:41], v[190:193], v[224:227], v[38:41]
	v_mfma_f32_16x16x32_bf16 v[34:37], v[208:211], v[224:227], v[34:37]
	v_mfma_f32_16x16x32_bf16 v[22:25], v[190:193], v[232:235], v[22:25]
	v_mfma_f32_16x16x32_bf16 v[18:21], v[208:211], v[232:235], v[18:21]
	v_mfma_f32_16x16x32_bf16 v[6:9], v[190:193], v[240:243], v[6:9]
	v_mfma_f32_16x16x32_bf16 v[2:5], v[208:211], v[240:243], v[2:5]
	s_barrier
	s_add_u32 s38, s38, 0x100
	s_addc_u32 s39, s39, 0
	s_add_u32 s21, s21, 0x100
	s_addc_u32 s49, s49, 0
	s_cmp_ge_i32 s56, s67
	s_mov_b32 s15, s56
	s_cbranch_scc0 .LBB0_276
	s_setprio 0

; template <class Epi, class Sched, bool ALIGN_EPI = false, bool SP2 = false>
; __device__ __forceinline__ void gemm_phase(PG8_LAS unsigned char* lds, const Gemm g, const Sched& S, const Epi& E, int tid_in) {
;     ...
;         const bool has_next = S.next(ui + 1, nxt);
;         const char* nA = has_next ? (const char*)g.A + (size_t)nxt.pm * tstepA + a_unit_off(g, nxt.pn) : cA; const char* nB = has_next ? (const char*)g.Bt + (size_t)nxt.pn * tstepB : cB;
; #pragma unroll 1
;         for (int t = 0; t < nt; t += 2) {
;             const bool last = (t == nt - 2);
;             const char* a1 = cA + (size_t)(t + 1) * kstep;
;             const char* a2 = last ? nA : cA + (size_t)(t + 2) * kstep; const char* b2 = last ? nB : cB + (size_t)(t + 2) * kstep;
;             const char* a3 = a2 + kstep; const char* b3 = b2 + kstep;
;     ...
; #pragma unroll
;         for (int a = 0; a < 2; ++a)
; #pragma unroll
;             for (int b = 0; b < 2; ++b)
; #pragma unroll
;                 for (int m = 0; m < 4; ++m)
; #pragma unroll
;                     for (int n = 0; n < 2; ++n) acc[a][b][m][n] = (f32x4){0.f, 0.f, 0.f, 0.f};
;         cur = nxt; cA = nA; cB = nB; ++ui;
.LBB0_351:
	v_mov_b32_e32 v125, 0
	s_andn2_b64 vcc, exec, s[38:39]
	v_mov_b32_e32 v124, v125
	v_mov_b32_e32 v123, v125
	v_mov_b32_e32 v122, v125
	v_mov_b32_e32 v129, v125
	v_mov_b32_e32 v128, v125
	v_mov_b32_e32 v127, v125
	v_mov_b32_e32 v126, v125
	v_mov_b32_e32 v113, v125
	v_mov_b32_e32 v112, v125
	v_mov_b32_e32 v111, v125
	v_mov_b32_e32 v110, v125
	v_mov_b32_e32 v109, v125
	v_mov_b32_e32 v108, v125
	v_mov_b32_e32 v107, v125
	v_mov_b32_e32 v106, v125
	v_mov_b32_e32 v97, v125
	v_mov_b32_e32 v96, v125
	v_mov_b32_e32 v95, v125
	v_mov_b32_e32 v94, v125
	v_mov_b32_e32 v93, v125
	v_mov_b32_e32 v92, v125
	v_mov_b32_e32 v91, v125
	v_mov_b32_e32 v90, v125
	v_mov_b32_e32 v81, v125
	v_mov_b32_e32 v80, v125
	v_mov_b32_e32 v79, v125
	v_mov_b32_e32 v78, v125
	v_mov_b32_e32 v77, v125
	v_mov_b32_e32 v76, v125
	v_mov_b32_e32 v75, v125
	v_mov_b32_e32 v74, v125
	v_mov_b32_e32 v121, v125
	v_mov_b32_e32 v120, v125
	v_mov_b32_e32 v119, v125
	v_mov_b32_e32 v118, v125
	v_mov_b32_e32 v117, v125
	v_mov_b32_e32 v116, v125
	v_mov_b32_e32 v115, v125
	v_mov_b32_e32 v114, v125
	v_mov_b32_e32 v105, v125
	v_mov_b32_e32 v104, v125
	v_mov_b32_e32 v103, v125
	v_mov_b32_e32 v102, v125
	v_mov_b32_e32 v101, v125
	v_mov_b32_e32 v100, v125
	v_mov_b32_e32 v99, v125
	v_mov_b32_e32 v98, v125
	v_mov_b32_e32 v89, v125
	v_mov_b32_e32 v88, v125
	v_mov_b32_e32 v87, v125
	v_mov_b32_e32 v86, v125
	v_mov_b32_e32 v85, v125
	v_mov_b32_e32 v84, v125
	v_mov_b32_e32 v83, v125
	v_mov_b32_e32 v82, v125
	v_mov_b32_e32 v73, v125
	v_mov_b32_e32 v72, v125
	v_mov_b32_e32 v71, v125
	v_mov_b32_e32 v70, v125
	v_mov_b32_e32 v69, v125
	v_mov_b32_e32 v68, v125
	v_mov_b32_e32 v67, v125
	v_mov_b32_e32 v66, v125
	v_mov_b32_e32 v65, v125
	v_mov_b32_e32 v64, v125
	v_mov_b32_e32 v63, v125
	v_mov_b32_e32 v62, v125
	v_mov_b32_e32 v61, v125
	v_mov_b32_e32 v60, v125
	v_mov_b32_e32 v59, v125
	v_mov_b32_e32 v58, v125
	v_mov_b32_e32 v49, v125
	v_mov_b32_e32 v48, v125
	v_mov_b32_e32 v47, v125
	v_mov_b32_e32 v46, v125
	v_mov_b32_e32 v45, v125
	v_mov_b32_e32 v44, v125
	v_mov_b32_e32 v43, v125
	v_mov_b32_e32 v42, v125
	v_mov_b32_e32 v33, v125
	v_mov_b32_e32 v32, v125
	v_mov_b32_e32 v31, v125
	v_mov_b32_e32 v30, v125
	v_mov_b32_e32 v29, v125
	v_mov_b32_e32 v28, v125
	v_mov_b32_e32 v27, v125
	v_mov_b32_e32 v26, v125
	v_mov_b32_e32 v17, v125
	v_mov_b32_e32 v16, v125
	v_mov_b32_e32 v15, v125
	v_mov_b32_e32 v14, v125
	v_mov_b32_e32 v13, v125
	v_mov_b32_e32 v12, v125
	v_mov_b32_e32 v11, v125
	v_mov_b32_e32 v10, v125
	v_mov_b32_e32 v57, v125
	v_mov_b32_e32 v56, v125
	v_mov_b32_e32 v55, v125
	v_mov_b32_e32 v54, v125
	v_mov_b32_e32 v53, v125
	v_mov_b32_e32 v52, v125
	v_mov_b32_e32 v51, v125
	v_mov_b32_e32 v50, v125
	v_mov_b32_e32 v41, v125
	v_mov_b32_e32 v40, v125
	v_mov_b32_e32 v39, v125
	v_mov_b32_e32 v38, v125
	v_mov_b32_e32 v37, v125
	v_mov_b32_e32 v36, v125
	v_mov_b32_e32 v35, v125
	v_mov_b32_e32 v34, v125
	v_mov_b32_e32 v25, v125
	v_mov_b32_e32 v24, v125
	v_mov_b32_e32 v23, v125
	v_mov_b32_e32 v22, v125
	v_mov_b32_e32 v21, v125
	v_mov_b32_e32 v20, v125
	v_mov_b32_e32 v19, v125
	v_mov_b32_e32 v18, v125
	v_mov_b32_e32 v9, v125
	v_mov_b32_e32 v8, v125
	v_mov_b32_e32 v7, v125
	v_mov_b32_e32 v6, v125
	v_mov_b32_e32 v5, v125
	v_mov_b32_e32 v4, v125
	v_mov_b32_e32 v3, v125
	v_mov_b32_e32 v2, v125
	s_cbranch_vccnz .LBB0_354
	s_add_u32 s52, s52, 0x80080
	s_addc_u32 s53, s53, 0
	s_add_u32 s12, s54, 0x100
	v_mov_b32_e32 v2, 0
	s_addc_u32 s13, s55, 0
	s_mov_b32 s15, 0
	v_mov_b32_e32 v3, v2
	v_mov_b32_e32 v4, v2
	v_mov_b32_e32 v5, v2
	v_mov_b32_e32 v6, v2
	v_mov_b32_e32 v7, v2
	v_mov_b32_e32 v8, v2
	v_mov_b32_e32 v9, v2
	v_mov_b32_e32 v18, v2
	v_mov_b32_e32 v19, v2
	v_mov_b32_e32 v20, v2
	v_mov_b32_e32 v21, v2
	v_mov_b32_e32 v22, v2
	v_mov_b32_e32 v23, v2
	v_mov_b32_e32 v24, v2
	v_mov_b32_e32 v25, v2
	v_mov_b32_e32 v34, v2
	v_mov_b32_e32 v35, v2
	v_mov_b32_e32 v36, v2
	v_mov_b32_e32 v37, v2
	v_mov_b32_e32 v38, v2
	v_mov_b32_e32 v39, v2
	v_mov_b32_e32 v40, v2
	v_mov_b32_e32 v41, v2
	v_mov_b32_e32 v50, v2
	v_mov_b32_e32 v51, v2
	v_mov_b32_e32 v52, v2
	v_mov_b32_e32 v53, v2
	v_mov_b32_e32 v54, v2
	v_mov_b32_e32 v55, v2
	v_mov_b32_e32 v56, v2
	v_mov_b32_e32 v57, v2
	v_mov_b32_e32 v10, v2
	v_mov_b32_e32 v11, v2
	v_mov_b32_e32 v12, v2
	v_mov_b32_e32 v13, v2
	v_mov_b32_e32 v14, v2
	v_mov_b32_e32 v15, v2
	v_mov_b32_e32 v16, v2
	v_mov_b32_e32 v17, v2
	v_mov_b32_e32 v26, v2
	v_mov_b32_e32 v27, v2
	v_mov_b32_e32 v28, v2
	v_mov_b32_e32 v29, v2
	v_mov_b32_e32 v30, v2
	v_mov_b32_e32 v31, v2
	v_mov_b32_e32 v32, v2
	v_mov_b32_e32 v33, v2
	v_mov_b32_e32 v42, v2
	v_mov_b32_e32 v43, v2
	v_mov_b32_e32 v44, v2
	v_mov_b32_e32 v45, v2
	v_mov_b32_e32 v46, v2
	v_mov_b32_e32 v47, v2
	v_mov_b32_e32 v48, v2
	v_mov_b32_e32 v49, v2
	v_mov_b32_e32 v58, v2
	v_mov_b32_e32 v59, v2
	v_mov_b32_e32 v60, v2
	v_mov_b32_e32 v61, v2
	v_mov_b32_e32 v62, v2
	v_mov_b32_e32 v63, v2
	v_mov_b32_e32 v64, v2
	v_mov_b32_e32 v65, v2
	v_mov_b32_e32 v66, v2
	v_mov_b32_e32 v67, v2
	v_mov_b32_e32 v68, v2
	v_mov_b32_e32 v69, v2
	v_mov_b32_e32 v70, v2
	v_mov_b32_e32 v71, v2
	v_mov_b32_e32 v72, v2
	v_mov_b32_e32 v73, v2
	v_mov_b32_e32 v82, v2
	v_mov_b32_e32 v83, v2
	v_mov_b32_e32 v84, v2
	v_mov_b32_e32 v85, v2
	v_mov_b32_e32 v86, v2
	v_mov_b32_e32 v87, v2
	v_mov_b32_e32 v88, v2
	v_mov_b32_e32 v89, v2
	v_mov_b32_e32 v98, v2
	v_mov_b32_e32 v99, v2
	v_mov_b32_e32 v100, v2
	v_mov_b32_e32 v101, v2
	v_mov_b32_e32 v102, v2
	v_mov_b32_e32 v103, v2
	v_mov_b32_e32 v104, v2
	v_mov_b32_e32 v105, v2
	v_mov_b32_e32 v114, v2
	v_mov_b32_e32 v115, v2
	v_mov_b32_e32 v116, v2
	v_mov_b32_e32 v117, v2
	v_mov_b32_e32 v118, v2
	v_mov_b32_e32 v119, v2
	v_mov_b32_e32 v120, v2
	v_mov_b32_e32 v121, v2
	v_mov_b32_e32 v74, v2
	v_mov_b32_e32 v75, v2
	v_mov_b32_e32 v76, v2
	v_mov_b32_e32 v77, v2
	v_mov_b32_e32 v78, v2
	v_mov_b32_e32 v79, v2
	v_mov_b32_e32 v80, v2
	v_mov_b32_e32 v81, v2
	v_mov_b32_e32 v90, v2
	v_mov_b32_e32 v91, v2
	v_mov_b32_e32 v92, v2
	v_mov_b32_e32 v93, v2
	v_mov_b32_e32 v94, v2
	v_mov_b32_e32 v95, v2
	v_mov_b32_e32 v96, v2
	v_mov_b32_e32 v97, v2
	v_mov_b32_e32 v106, v2
	v_mov_b32_e32 v107, v2
	v_mov_b32_e32 v108, v2
	v_mov_b32_e32 v109, v2
	v_mov_b32_e32 v110, v2
	v_mov_b32_e32 v111, v2
	v_mov_b32_e32 v112, v2
	v_mov_b32_e32 v113, v2
	v_mov_b32_e32 v126, v2
	v_mov_b32_e32 v127, v2
	v_mov_b32_e32 v128, v2
	v_mov_b32_e32 v129, v2
	v_mov_b32_e32 v122, v2
	v_mov_b32_e32 v123, v2
	v_mov_b32_e32 v124, v2
	v_mov_b32_e32 v125, v2
	s_cmp_ge_u32 s84, 0x100
	s_cbranch_scc0 .Lprio_skip353
	s_setprio 1
; #define PG8_STAGE(bufoff, gbase, voff) do { _Pragma("unroll") for (int _i = 0; _i < 2; ++_i) \
;         __builtin_amdgcn_global_load_lds((const unsigned*)((const char*)(gbase) + (voff)[_i]), (PG8_LAS unsigned*)(lds + (bufoff) + ldsw + _i * 8192), 16, 0, 0); } while (0)
; #define PG8_LDA(dst, b, h) do { _Pragma("unroll") for (int m = 0; m < 4; ++m) _Pragma("unroll") for (int k = 0; k < 2; ++k) dst[m][k] = *(const PG8_LAS bf16x8*)(lds + PG8_SA(b, h) + aoff + m * 2048 + k * 1024); } while (0)
; #define PG8_LDB(dst, b, h) do { _Pragma("unroll") for (int n = 0; n < 2; ++n) _Pragma("unroll") for (int k = 0; k < 2; ++k) dst[n][k] = *(const PG8_LAS bf16x8*)(lds + PG8_SB(b, h) + boff + n * 2048 + k * 1024); } while (0)
; #define PG8_MMA(ai, bj, At, Bt) do { __builtin_amdgcn_s_setprio(1); _Pragma("unroll") for (int m = 0; m < 4; ++m) _Pragma("unroll") for (int n = 0; n < 2; ++n) _Pragma("unroll") for (int k = 0; k < 2; ++k) \
;         acc[ai][bj][m][n] = __builtin_amdgcn_mfma_f32_16x16x32_bf16(Bt[n][k], At[m][k], acc[ai][bj][m][n], 0, 0, 0); __builtin_amdgcn_s_setprio(0); } while (0)
; #define PG8_WAIT_V(n) asm volatile("s_waitcnt vmcnt(" #n ")" ::: "memory")
; #define PG8_BAR __builtin_amdgcn_s_barrier()
; template <class Epi, class Sched, bool ALIGN_EPI = false, bool SP2 = false>
; __device__ __forceinline__ void gemm_phase(PG8_LAS unsigned char* lds, const Gemm g, const Sched& S, const Epi& E, int tid_in) {
;     ...
;         for (int t = 0; t < nt; t += 2) {
;             const bool last = (t == nt - 2);
;             const char* a1 = cA + (size_t)(t + 1) * kstep;
;             const char* a2 = last ? nA : cA + (size_t)(t + 2) * kstep; const char* b2 = last ? nB : cB + (size_t)(t + 2) * kstep;
;             const char* a3 = a2 + kstep; const char* b3 = b2 + kstep;
;             if (last && has_next) S.a_ready(nxt);
;             if constexpr (SP2) {
;             PG8_LDB(B0, 0, 0); PG8_LDB(B1, 0, 1); PG8_SCHED; PG8_LDA(At, 0, 0); PG8_STAGE(PG8_SA(1, 1), a1 + hstepA, voffA);
;             PG8_WAIT_V(8); PG8_WAIT_L(0); PG8_BAR; PG8_MMA(0, 0, At, B0); PG8_MMA(0, 1, At, B1); PG8_BAR; PG8_SCHED;
;             PG8_LDA(At, 0, 1); PG8_STAGE(PG8_SB(0, 0), b2, voffB); PG8_STAGE(PG8_SB(0, 1), b2 + hstep, voffB); PG8_STAGE(PG8_SA(0, 0), a2, voffA);
;             PG8_WAIT_V(8); PG8_WAIT_L(0); PG8_BAR; PG8_MMA(1, 0, At, B0); PG8_MMA(1, 1, At, B1); PG8_BAR; PG8_SCHED;
.Lprio_skip353:
.LBB0_353:
	s_add_i32 s24, s15, 2
	s_add_u32 s47, s52, 0xfff80080
	s_addc_u32 s54, s53, -1
	s_add_i32 s76, 0, 0x10000
	s_cmp_eq_u32 s69, s15
	s_cselect_b32 s55, s49, s54
	s_cselect_b32 s54, s48, s47
	v_add_u32_e32 v145, s76, v144
	s_cselect_b32 s75, s51, s13
	s_cselect_b32 s74, s50, s12
	s_add_i32 s15, 0, 0x14000
	ds_read_b128 v[146:149], v145
	ds_read_b128 v[150:153], v145 offset:1024
	ds_read_b128 v[154:157], v145 offset:2048
	ds_read_b128 v[158:161], v145 offset:3072
	v_add_u32_e32 v145, s15, v144
	ds_read_b128 v[162:165], v145
	ds_read_b128 v[166:169], v145 offset:1024
	ds_read_b128 v[170:173], v145 offset:2048
	ds_read_b128 v[174:177], v145 offset:3072
	v_lshl_add_u64 v[194:195], s[52:53], 0, v[138:139]
	s_add_i32 m0, s23, 0xc000
	ds_read_b128 v[178:181], v143
	ds_read_b128 v[182:185], v143 offset:1024
	ds_read_b128 v[186:189], v143 offset:2048
	ds_read_b128 v[190:193], v143 offset:3072
	ds_read_b128 v[204:207], v143 offset:4096
	ds_read_b128 v[208:211], v143 offset:5120
	ds_read_b128 v[212:215], v143 offset:6144
	ds_read_b128 v[216:219], v143 offset:7168
	global_load_lds_dwordx4 v[194:195], off
	v_lshl_add_u64 v[194:195], s[52:53], 0, v[140:141]
	s_add_i32 m0, s23, 0xe000
	s_nop 0
	global_load_lds_dwordx4 v[194:195], off
	s_waitcnt vmcnt(8)
	s_waitcnt lgkmcnt(0)
	s_barrier
	s_waitcnt lgkmcnt(0)
	v_mfma_f32_16x16x32_bf16 v[122:125], v[146:149], v[178:181], v[122:125]
	v_mfma_f32_16x16x32_bf16 v[126:129], v[154:157], v[178:181], v[126:129]
	v_mfma_f32_16x16x32_bf16 v[110:113], v[146:149], v[186:189], v[110:113]
	v_mfma_f32_16x16x32_bf16 v[106:109], v[154:157], v[186:189], v[106:109]
	v_mfma_f32_16x16x32_bf16 v[94:97], v[146:149], v[204:207], v[94:97]
	v_mfma_f32_16x16x32_bf16 v[90:93], v[154:157], v[204:207], v[90:93]
	v_mfma_f32_16x16x32_bf16 v[78:81], v[146:149], v[212:215], v[78:81]
	v_mfma_f32_16x16x32_bf16 v[74:77], v[154:157], v[212:215], v[74:77]
	v_mfma_f32_16x16x32_bf16 v[122:125], v[150:153], v[182:185], v[122:125]
	v_mfma_f32_16x16x32_bf16 v[126:129], v[158:161], v[182:185], v[126:129]
	v_mfma_f32_16x16x32_bf16 v[110:113], v[150:153], v[190:193], v[110:113]
	v_mfma_f32_16x16x32_bf16 v[106:109], v[158:161], v[190:193], v[106:109]
	v_mfma_f32_16x16x32_bf16 v[94:97], v[150:153], v[208:211], v[94:97]
	v_mfma_f32_16x16x32_bf16 v[90:93], v[158:161], v[208:211], v[90:93]
	v_mfma_f32_16x16x32_bf16 v[78:81], v[150:153], v[216:219], v[78:81]
	v_mfma_f32_16x16x32_bf16 v[74:77], v[158:161], v[216:219], v[74:77]
	v_mfma_f32_16x16x32_bf16 v[118:121], v[162:165], v[178:181], v[118:121]
	v_mfma_f32_16x16x32_bf16 v[114:117], v[170:173], v[178:181], v[114:117]
	v_mfma_f32_16x16x32_bf16 v[102:105], v[162:165], v[186:189], v[102:105]
	v_mfma_f32_16x16x32_bf16 v[98:101], v[170:173], v[186:189], v[98:101]
	v_mfma_f32_16x16x32_bf16 v[86:89], v[162:165], v[204:207], v[86:89]
	v_mfma_f32_16x16x32_bf16 v[82:85], v[170:173], v[204:207], v[82:85]
	v_mfma_f32_16x16x32_bf16 v[70:73], v[162:165], v[212:215], v[70:73]
	v_mfma_f32_16x16x32_bf16 v[66:69], v[170:173], v[212:215], v[66:69]
	v_mfma_f32_16x16x32_bf16 v[118:121], v[166:169], v[182:185], v[118:121]
	v_mfma_f32_16x16x32_bf16 v[114:117], v[174:177], v[182:185], v[114:117]
	v_mfma_f32_16x16x32_bf16 v[102:105], v[166:169], v[190:193], v[102:105]
	v_mfma_f32_16x16x32_bf16 v[98:101], v[174:177], v[190:193], v[98:101]
	v_mfma_f32_16x16x32_bf16 v[86:89], v[166:169], v[208:211], v[86:89]
	v_mfma_f32_16x16x32_bf16 v[82:85], v[174:177], v[208:211], v[82:85]
	v_mfma_f32_16x16x32_bf16 v[70:73], v[166:169], v[216:219], v[70:73]
	v_mfma_f32_16x16x32_bf16 v[66:69], v[174:177], v[216:219], v[66:69]
	s_barrier
	s_add_i32 s47, s76, s57
	v_lshl_add_u64 v[194:195], s[74:75], 0, v[130:131]
	s_mov_b32 m0, s47
	ds_read_b128 v[178:181], v143 offset:16384
	ds_read_b128 v[182:185], v143 offset:17408
	ds_read_b128 v[186:189], v143 offset:18432
	ds_read_b128 v[190:193], v143 offset:19456
	ds_read_b128 v[204:207], v143 offset:20480
	ds_read_b128 v[208:211], v143 offset:21504
	ds_read_b128 v[212:215], v143 offset:22528
	ds_read_b128 v[216:219], v143 offset:23552
	global_load_lds_dwordx4 v[194:195], off
	s_add_i32 m0, s47, 0x2000
	v_lshl_add_u64 v[200:201], s[74:75], 0, v[132:133]
	s_add_u32 s74, s74, s0
	s_addc_u32 s75, s75, s1
	s_add_i32 s15, s15, s57
	global_load_lds_dwordx4 v[200:201], off
	v_lshl_add_u64 v[220:221], s[74:75], 0, v[130:131]
	s_mov_b32 m0, s15
	v_lshl_add_u64 v[222:223], s[74:75], 0, v[132:133]
	global_load_lds_dwordx4 v[220:221], off
	s_add_i32 m0, s15, 0x2000
	v_lshl_add_u64 v[224:225], s[54:55], 0, v[134:135]
	global_load_lds_dwordx4 v[222:223], off
	s_mov_b32 m0, s23
	v_lshl_add_u64 v[226:227], s[54:55], 0, v[136:137]
	global_load_lds_dwordx4 v[224:225], off
	s_mov_b32 m0, s60
	s_nop 0
	global_load_lds_dwordx4 v[226:227], off
	s_waitcnt vmcnt(8)
	s_waitcnt lgkmcnt(0)
	s_barrier
; #define PG8_STAGE(bufoff, gbase, voff) do { _Pragma("unroll") for (int _i = 0; _i < 2; ++_i) \
;         __builtin_amdgcn_global_load_lds((const unsigned*)((const char*)(gbase) + (voff)[_i]), (PG8_LAS unsigned*)(lds + (bufoff) + ldsw + _i * 8192), 16, 0, 0); } while (0)
; #define PG8_LDA(dst, b, h) do { _Pragma("unroll") for (int m = 0; m < 4; ++m) _Pragma("unroll") for (int k = 0; k < 2; ++k) dst[m][k] = *(const PG8_LAS bf16x8*)(lds + PG8_SA(b, h) + aoff + m * 2048 + k * 1024); } while (0)
; #define PG8_LDB(dst, b, h) do { _Pragma("unroll") for (int n = 0; n < 2; ++n) _Pragma("unroll") for (int k = 0; k < 2; ++k) dst[n][k] = *(const PG8_LAS bf16x8*)(lds + PG8_SB(b, h) + boff + n * 2048 + k * 1024); } while (0)
; #define PG8_MMA(ai, bj, At, Bt) do { __builtin_amdgcn_s_setprio(1); _Pragma("unroll") for (int m = 0; m < 4; ++m) _Pragma("unroll") for (int n = 0; n < 2; ++n) _Pragma("unroll") for (int k = 0; k < 2; ++k) \
;         acc[ai][bj][m][n] = __builtin_amdgcn_mfma_f32_16x16x32_bf16(Bt[n][k], At[m][k], acc[ai][bj][m][n], 0, 0, 0); __builtin_amdgcn_s_setprio(0); } while (0)
; #define PG8_WAIT_V(n) asm volatile("s_waitcnt vmcnt(" #n ")" ::: "memory")
; #define PG8_WAIT_L(n) asm volatile("s_waitcnt lgkmcnt(" #n ")" ::: "memory")
; #define PG8_BAR __builtin_amdgcn_s_barrier()
; #define PG8_SCHED __builtin_amdgcn_sched_barrier(0)
; template <class Epi, class Sched, bool ALIGN_EPI = false, bool SP2 = false>
; __device__ __forceinline__ void gemm_phase(PG8_LAS unsigned char* lds, const Gemm g, const Sched& S, const Epi& E, int tid_in) {
;     ...
;             PG8_WAIT_V(8); PG8_WAIT_L(0); PG8_BAR; PG8_MMA(1, 0, At, B0); PG8_MMA(1, 1, At, B1); PG8_BAR; PG8_SCHED;
;             PG8_LDB(B0, 1, 0); PG8_LDB(B1, 1, 1); PG8_SCHED; PG8_LDA(At, 1, 0); PG8_STAGE(PG8_SA(0, 1), a2 + hstepA, voffA);
;             PG8_WAIT_V(8); PG8_WAIT_L(0); PG8_BAR; PG8_MMA(0, 0, At, B0); PG8_MMA(0, 1, At, B1); PG8_BAR; PG8_SCHED;
	s_waitcnt lgkmcnt(0)
	v_mfma_f32_16x16x32_bf16 v[62:65], v[146:149], v[178:181], v[62:65]
	v_mfma_f32_16x16x32_bf16 v[58:61], v[154:157], v[178:181], v[58:61]
	v_mfma_f32_16x16x32_bf16 v[46:49], v[146:149], v[186:189], v[46:49]
	v_mfma_f32_16x16x32_bf16 v[42:45], v[154:157], v[186:189], v[42:45]
	v_mfma_f32_16x16x32_bf16 v[30:33], v[146:149], v[204:207], v[30:33]
	v_mfma_f32_16x16x32_bf16 v[26:29], v[154:157], v[204:207], v[26:29]
	v_mfma_f32_16x16x32_bf16 v[14:17], v[146:149], v[212:215], v[14:17]
	v_mfma_f32_16x16x32_bf16 v[10:13], v[154:157], v[212:215], v[10:13]
	v_mfma_f32_16x16x32_bf16 v[62:65], v[150:153], v[182:185], v[62:65]
	v_mfma_f32_16x16x32_bf16 v[58:61], v[158:161], v[182:185], v[58:61]
	v_mfma_f32_16x16x32_bf16 v[46:49], v[150:153], v[190:193], v[46:49]
	v_mfma_f32_16x16x32_bf16 v[42:45], v[158:161], v[190:193], v[42:45]
	v_mfma_f32_16x16x32_bf16 v[30:33], v[150:153], v[208:211], v[30:33]
	v_mfma_f32_16x16x32_bf16 v[26:29], v[158:161], v[208:211], v[26:29]
	v_mfma_f32_16x16x32_bf16 v[14:17], v[150:153], v[216:219], v[14:17]
	v_mfma_f32_16x16x32_bf16 v[10:13], v[158:161], v[216:219], v[10:13]
	v_mfma_f32_16x16x32_bf16 v[54:57], v[162:165], v[178:181], v[54:57]
	v_mfma_f32_16x16x32_bf16 v[50:53], v[170:173], v[178:181], v[50:53]
	v_mfma_f32_16x16x32_bf16 v[38:41], v[162:165], v[186:189], v[38:41]
	v_mfma_f32_16x16x32_bf16 v[34:37], v[170:173], v[186:189], v[34:37]
	v_mfma_f32_16x16x32_bf16 v[22:25], v[162:165], v[204:207], v[22:25]
	v_mfma_f32_16x16x32_bf16 v[18:21], v[170:173], v[204:207], v[18:21]
	v_mfma_f32_16x16x32_bf16 v[6:9], v[162:165], v[212:215], v[6:9]
	v_mfma_f32_16x16x32_bf16 v[2:5], v[170:173], v[212:215], v[2:5]
	v_mfma_f32_16x16x32_bf16 v[54:57], v[166:169], v[182:185], v[54:57]
	v_mfma_f32_16x16x32_bf16 v[50:53], v[174:177], v[182:185], v[50:53]
	v_mfma_f32_16x16x32_bf16 v[38:41], v[166:169], v[190:193], v[38:41]
	v_mfma_f32_16x16x32_bf16 v[34:37], v[174:177], v[190:193], v[34:37]
	v_mfma_f32_16x16x32_bf16 v[22:25], v[166:169], v[208:211], v[22:25]
	v_mfma_f32_16x16x32_bf16 v[18:21], v[174:177], v[208:211], v[18:21]
	v_mfma_f32_16x16x32_bf16 v[6:9], v[166:169], v[216:219], v[6:9]
	v_mfma_f32_16x16x32_bf16 v[2:5], v[174:177], v[216:219], v[2:5]
	s_barrier
	s_add_i32 s15, 0, 0x18000
	v_add_u32_e32 v145, s15, v144
	s_add_i32 s47, 0, 0x1c000
	ds_read_b128 v[146:149], v145
	ds_read_b128 v[150:153], v145 offset:1024
	ds_read_b128 v[154:157], v145 offset:2048
	ds_read_b128 v[158:161], v145 offset:3072
	v_add_u32_e32 v145, s47, v144
	ds_read_b128 v[162:165], v145
	ds_read_b128 v[166:169], v145 offset:1024
	ds_read_b128 v[170:173], v145 offset:2048
	ds_read_b128 v[174:177], v145 offset:3072
	s_add_u32 s54, s54, 0x80000
	s_addc_u32 s55, s55, 0
	s_mov_b32 m0, s61
	v_lshl_add_u64 v[228:229], s[54:55], 0, v[134:135]
	ds_read_b128 v[178:181], v143 offset:32768
	ds_read_b128 v[182:185], v143 offset:33792
	ds_read_b128 v[186:189], v143 offset:34816
	ds_read_b128 v[190:193], v143 offset:35840
	ds_read_b128 v[204:207], v143 offset:36864
	ds_read_b128 v[208:211], v143 offset:37888
	ds_read_b128 v[212:215], v143 offset:38912
	ds_read_b128 v[216:219], v143 offset:39936
	global_load_lds_dwordx4 v[228:229], off
	v_lshl_add_u64 v[228:229], s[54:55], 0, v[136:137]
	s_mov_b32 m0, s62
	s_nop 0
	global_load_lds_dwordx4 v[228:229], off
	s_waitcnt vmcnt(8)
	s_waitcnt lgkmcnt(0)
	s_barrier
	s_waitcnt lgkmcnt(0)
	v_mfma_f32_16x16x32_bf16 v[122:125], v[146:149], v[178:181], v[122:125]
	v_mfma_f32_16x16x32_bf16 v[126:129], v[154:157], v[178:181], v[126:129]
	v_mfma_f32_16x16x32_bf16 v[110:113], v[146:149], v[186:189], v[110:113]
	v_mfma_f32_16x16x32_bf16 v[106:109], v[154:157], v[186:189], v[106:109]
	v_mfma_f32_16x16x32_bf16 v[94:97], v[146:149], v[204:207], v[94:97]
	v_mfma_f32_16x16x32_bf16 v[90:93], v[154:157], v[204:207], v[90:93]
	v_mfma_f32_16x16x32_bf16 v[78:81], v[146:149], v[212:215], v[78:81]
	v_mfma_f32_16x16x32_bf16 v[74:77], v[154:157], v[212:215], v[74:77]
	v_mfma_f32_16x16x32_bf16 v[122:125], v[150:153], v[182:185], v[122:125]
	v_mfma_f32_16x16x32_bf16 v[126:129], v[158:161], v[182:185], v[126:129]
	v_mfma_f32_16x16x32_bf16 v[110:113], v[150:153], v[190:193], v[110:113]
	v_mfma_f32_16x16x32_bf16 v[106:109], v[158:161], v[190:193], v[106:109]
	v_mfma_f32_16x16x32_bf16 v[94:97], v[150:153], v[208:211], v[94:97]
	v_mfma_f32_16x16x32_bf16 v[90:93], v[158:161], v[208:211], v[90:93]
	v_mfma_f32_16x16x32_bf16 v[78:81], v[150:153], v[216:219], v[78:81]
	v_mfma_f32_16x16x32_bf16 v[74:77], v[158:161], v[216:219], v[74:77]
	v_mfma_f32_16x16x32_bf16 v[118:121], v[162:165], v[178:181], v[118:121]
	v_mfma_f32_16x16x32_bf16 v[114:117], v[170:173], v[178:181], v[114:117]
	v_mfma_f32_16x16x32_bf16 v[102:105], v[162:165], v[186:189], v[102:105]
	v_mfma_f32_16x16x32_bf16 v[98:101], v[170:173], v[186:189], v[98:101]
	v_mfma_f32_16x16x32_bf16 v[86:89], v[162:165], v[204:207], v[86:89]
	v_mfma_f32_16x16x32_bf16 v[82:85], v[170:173], v[204:207], v[82:85]
	v_mfma_f32_16x16x32_bf16 v[70:73], v[162:165], v[212:215], v[70:73]
	v_mfma_f32_16x16x32_bf16 v[66:69], v[170:173], v[212:215], v[66:69]
	v_mfma_f32_16x16x32_bf16 v[118:121], v[166:169], v[182:185], v[118:121]
	v_mfma_f32_16x16x32_bf16 v[114:117], v[174:177], v[182:185], v[114:117]
	v_mfma_f32_16x16x32_bf16 v[102:105], v[166:169], v[190:193], v[102:105]
	v_mfma_f32_16x16x32_bf16 v[98:101], v[174:177], v[190:193], v[98:101]
	v_mfma_f32_16x16x32_bf16 v[86:89], v[166:169], v[208:211], v[86:89]
	v_mfma_f32_16x16x32_bf16 v[82:85], v[174:177], v[208:211], v[82:85]
	v_mfma_f32_16x16x32_bf16 v[70:73], v[166:169], v[216:219], v[70:73]
	v_mfma_f32_16x16x32_bf16 v[66:69], v[174:177], v[216:219], v[66:69]
	s_barrier
; #define PG8_STAGE(bufoff, gbase, voff) do { _Pragma("unroll") for (int _i = 0; _i < 2; ++_i) \
;         __builtin_amdgcn_global_load_lds((const unsigned*)((const char*)(gbase) + (voff)[_i]), (PG8_LAS unsigned*)(lds + (bufoff) + ldsw + _i * 8192), 16, 0, 0); } while (0)
; #define PG8_LDA(dst, b, h) do { _Pragma("unroll") for (int m = 0; m < 4; ++m) _Pragma("unroll") for (int k = 0; k < 2; ++k) dst[m][k] = *(const PG8_LAS bf16x8*)(lds + PG8_SA(b, h) + aoff + m * 2048 + k * 1024); } while (0)
; #define PG8_MMA(ai, bj, At, Bt) do { __builtin_amdgcn_s_setprio(1); _Pragma("unroll") for (int m = 0; m < 4; ++m) _Pragma("unroll") for (int n = 0; n < 2; ++n) _Pragma("unroll") for (int k = 0; k < 2; ++k) \
;         acc[ai][bj][m][n] = __builtin_amdgcn_mfma_f32_16x16x32_bf16(Bt[n][k], At[m][k], acc[ai][bj][m][n], 0, 0, 0); __builtin_amdgcn_s_setprio(0); } while (0)
; #define PG8_WAIT_V(n) asm volatile("s_waitcnt vmcnt(" #n ")" ::: "memory")
; #define PG8_WAIT_L(n) asm volatile("s_waitcnt lgkmcnt(" #n ")" ::: "memory")
; #define PG8_BAR __builtin_amdgcn_s_barrier()
; #define PG8_SCHED __builtin_amdgcn_sched_barrier(0)
; template <class Epi, class Sched, bool ALIGN_EPI = false, bool SP2 = false>
; __device__ __forceinline__ void gemm_phase(PG8_LAS unsigned char* lds, const Gemm g, const Sched& S, const Epi& E, int tid_in) {
;     ...
;         for (int t = 0; t < nt; t += 2) {
;             const bool last = (t == nt - 2);
;             const char* a1 = cA + (size_t)(t + 1) * kstep;
;             const char* a2 = last ? nA : cA + (size_t)(t + 2) * kstep; const char* b2 = last ? nB : cB + (size_t)(t + 2) * kstep;
;             const char* a3 = a2 + kstep; const char* b3 = b2 + kstep;
;     ...
;             PG8_LDA(At, 1, 1); PG8_STAGE(PG8_SB(1, 0), b3, voffB); PG8_STAGE(PG8_SB(1, 1), b3 + hstep, voffB); PG8_STAGE(PG8_SA(1, 0), a3, voffA);
;             PG8_WAIT_V(8); PG8_WAIT_L(0); PG8_BAR; PG8_MMA(1, 0, At, B0); PG8_MMA(1, 1, At, B1); PG8_BAR; PG8_SCHED;
	s_add_i32 s15, s15, s57
	v_lshl_add_u64 v[194:195], v[194:195], 0, s[28:29]
	s_mov_b32 m0, s15
	ds_read_b128 v[178:181], v143 offset:49152
	ds_read_b128 v[182:185], v143 offset:50176
	ds_read_b128 v[186:189], v143 offset:51200
	ds_read_b128 v[190:193], v143 offset:52224
	ds_read_b128 v[204:207], v143 offset:53248
	ds_read_b128 v[208:211], v143 offset:54272
	ds_read_b128 v[212:215], v143 offset:55296
	ds_read_b128 v[216:219], v143 offset:56320
	global_load_lds_dwordx4 v[194:195], off
	v_lshl_add_u64 v[194:195], v[200:201], 0, s[28:29]
	s_add_i32 m0, s15, 0x2000
	s_add_i32 s15, s47, s57
	global_load_lds_dwordx4 v[194:195], off
	v_lshl_add_u64 v[194:195], v[220:221], 0, s[28:29]
	s_mov_b32 m0, s15
	s_nop 0
	global_load_lds_dwordx4 v[194:195], off
	v_lshl_add_u64 v[194:195], v[222:223], 0, s[28:29]
	s_add_i32 m0, s15, 0x2000
	s_nop 0
	global_load_lds_dwordx4 v[194:195], off
	v_lshl_add_u64 v[194:195], v[224:225], 0, s[28:29]
	s_mov_b32 m0, s65
	s_nop 0
	global_load_lds_dwordx4 v[194:195], off
	v_lshl_add_u64 v[194:195], v[226:227], 0, s[28:29]
	s_mov_b32 m0, s66
	s_nop 0
	global_load_lds_dwordx4 v[194:195], off
	s_waitcnt vmcnt(8)
	s_waitcnt lgkmcnt(0)
	s_barrier
	s_waitcnt lgkmcnt(0)
	v_mfma_f32_16x16x32_bf16 v[62:65], v[146:149], v[178:181], v[62:65]
	v_mfma_f32_16x16x32_bf16 v[58:61], v[154:157], v[178:181], v[58:61]
	v_mfma_f32_16x16x32_bf16 v[46:49], v[146:149], v[186:189], v[46:49]
	v_mfma_f32_16x16x32_bf16 v[42:45], v[154:157], v[186:189], v[42:45]
	v_mfma_f32_16x16x32_bf16 v[30:33], v[146:149], v[204:207], v[30:33]
	v_mfma_f32_16x16x32_bf16 v[26:29], v[154:157], v[204:207], v[26:29]
	v_mfma_f32_16x16x32_bf16 v[14:17], v[146:149], v[212:215], v[14:17]
	v_mfma_f32_16x16x32_bf16 v[10:13], v[154:157], v[212:215], v[10:13]
	v_mfma_f32_16x16x32_bf16 v[62:65], v[150:153], v[182:185], v[62:65]
	v_mfma_f32_16x16x32_bf16 v[58:61], v[158:161], v[182:185], v[58:61]
	v_mfma_f32_16x16x32_bf16 v[46:49], v[150:153], v[190:193], v[46:49]
	v_mfma_f32_16x16x32_bf16 v[42:45], v[158:161], v[190:193], v[42:45]
	v_mfma_f32_16x16x32_bf16 v[30:33], v[150:153], v[208:211], v[30:33]
	v_mfma_f32_16x16x32_bf16 v[26:29], v[158:161], v[208:211], v[26:29]
	v_mfma_f32_16x16x32_bf16 v[14:17], v[150:153], v[216:219], v[14:17]
	v_mfma_f32_16x16x32_bf16 v[10:13], v[158:161], v[216:219], v[10:13]
	v_mfma_f32_16x16x32_bf16 v[54:57], v[162:165], v[178:181], v[54:57]
	v_mfma_f32_16x16x32_bf16 v[50:53], v[170:173], v[178:181], v[50:53]
	v_mfma_f32_16x16x32_bf16 v[38:41], v[162:165], v[186:189], v[38:41]
	v_mfma_f32_16x16x32_bf16 v[34:37], v[170:173], v[186:189], v[34:37]
	v_mfma_f32_16x16x32_bf16 v[22:25], v[162:165], v[204:207], v[22:25]
	v_mfma_f32_16x16x32_bf16 v[18:21], v[170:173], v[204:207], v[18:21]
	v_mfma_f32_16x16x32_bf16 v[6:9], v[162:165], v[212:215], v[6:9]
	v_mfma_f32_16x16x32_bf16 v[2:5], v[170:173], v[212:215], v[2:5]
	v_mfma_f32_16x16x32_bf16 v[54:57], v[166:169], v[182:185], v[54:57]
	v_mfma_f32_16x16x32_bf16 v[50:53], v[174:177], v[182:185], v[50:53]
	v_mfma_f32_16x16x32_bf16 v[38:41], v[166:169], v[190:193], v[38:41]
	v_mfma_f32_16x16x32_bf16 v[34:37], v[174:177], v[190:193], v[34:37]
	v_mfma_f32_16x16x32_bf16 v[22:25], v[166:169], v[208:211], v[22:25]
	v_mfma_f32_16x16x32_bf16 v[18:21], v[174:177], v[208:211], v[18:21]
	v_mfma_f32_16x16x32_bf16 v[6:9], v[166:169], v[216:219], v[6:9]
	v_mfma_f32_16x16x32_bf16 v[2:5], v[174:177], v[216:219], v[2:5]
	s_barrier
	s_add_u32 s52, s52, 0x100
	s_addc_u32 s53, s53, 0
	s_add_u32 s12, s12, 0x100
	s_addc_u32 s13, s13, 0
	s_cmp_ge_i32 s24, s68
	s_mov_b32 s15, s24
	s_cbranch_scc0 .LBB0_353
	s_setprio 0

; template <class Epi, class Sched, bool ALIGN_EPI = false, bool SP2 = false>
; __device__ __forceinline__ void gemm_phase(PG8_LAS unsigned char* lds, const Gemm g, const Sched& S, const Epi& E, int tid_in) {
;     ...
;         const bool has_next = S.next(ui + 1, nxt);
;         const char* nA = has_next ? (const char*)g.A + (size_t)nxt.pm * tstepA + a_unit_off(g, nxt.pn) : cA; const char* nB = has_next ? (const char*)g.Bt + (size_t)nxt.pn * tstepB : cB;
; #pragma unroll 1
;         for (int t = 0; t < nt; t += 2) {
;             const bool last = (t == nt - 2);
;             const char* a1 = cA + (size_t)(t + 1) * kstep;
;             const char* a2 = last ? nA : cA + (size_t)(t + 2) * kstep; const char* b2 = last ? nB : cB + (size_t)(t + 2) * kstep;
;             const char* a3 = a2 + kstep; const char* b3 = b2 + kstep;
;     ...
; #pragma unroll
;         for (int a = 0; a < 2; ++a)
; #pragma unroll
;             for (int b = 0; b < 2; ++b)
; #pragma unroll
;                 for (int m = 0; m < 4; ++m)
; #pragma unroll
;                     for (int n = 0; n < 2; ++n) acc[a][b][m][n] = (f32x4){0.f, 0.f, 0.f, 0.f};
;         cur = nxt; cA = nA; cB = nB; ++ui;
.LBB0_411:
	v_readlane_b32 s12, v255, 22
	v_mov_b32_e32 v129, 0
	v_readlane_b32 s13, v255, 23
	s_andn2_b64 vcc, exec, s[12:13]
	v_mov_b32_e32 v128, v129
	v_mov_b32_e32 v127, v129
	v_mov_b32_e32 v126, v129
	v_mov_b32_e32 v105, v129
	v_mov_b32_e32 v104, v129
	v_mov_b32_e32 v103, v129
	v_mov_b32_e32 v102, v129
	s_waitcnt lgkmcnt(0)
	v_mov_b32_e32 v73, v129
	v_mov_b32_e32 v72, v129
	v_mov_b32_e32 v71, v129
	v_mov_b32_e32 v70, v129
	v_mov_b32_e32 v101, v129
	v_mov_b32_e32 v100, v129
	v_mov_b32_e32 v99, v129
	v_mov_b32_e32 v98, v129
	v_mov_b32_e32 v69, v129
	v_mov_b32_e32 v68, v129
	v_mov_b32_e32 v67, v129
	v_mov_b32_e32 v66, v129
	v_mov_b32_e32 v121, v129
	v_mov_b32_e32 v120, v129
	v_mov_b32_e32 v119, v129
	v_mov_b32_e32 v118, v129
	v_mov_b32_e32 v97, v129
	v_mov_b32_e32 v96, v129
	v_mov_b32_e32 v95, v129
	v_mov_b32_e32 v94, v129
	v_mov_b32_e32 v65, v129
	v_mov_b32_e32 v64, v129
	v_mov_b32_e32 v63, v129
	v_mov_b32_e32 v62, v129
	v_mov_b32_e32 v89, v129
	v_mov_b32_e32 v88, v129
	v_mov_b32_e32 v87, v129
	v_mov_b32_e32 v86, v129
	v_mov_b32_e32 v61, v129
	v_mov_b32_e32 v60, v129
	v_mov_b32_e32 v59, v129
	v_mov_b32_e32 v58, v129
	v_mov_b32_e32 v85, v129
	v_mov_b32_e32 v84, v129
	v_mov_b32_e32 v83, v129
	v_mov_b32_e32 v82, v129
	v_mov_b32_e32 v57, v129
	v_mov_b32_e32 v56, v129
	v_mov_b32_e32 v55, v129
	v_mov_b32_e32 v54, v129
	v_mov_b32_e32 v81, v129
	v_mov_b32_e32 v80, v129
	v_mov_b32_e32 v79, v129
	v_mov_b32_e32 v78, v129
	v_mov_b32_e32 v53, v129
	v_mov_b32_e32 v52, v129
	v_mov_b32_e32 v51, v129
	v_mov_b32_e32 v50, v129
	v_mov_b32_e32 v113, v129
	v_mov_b32_e32 v112, v129
	v_mov_b32_e32 v111, v129
	v_mov_b32_e32 v110, v129
	v_mov_b32_e32 v49, v129
	v_mov_b32_e32 v48, v129
	v_mov_b32_e32 v47, v129
	v_mov_b32_e32 v46, v129
	v_mov_b32_e32 v25, v129
	v_mov_b32_e32 v24, v129
	v_mov_b32_e32 v23, v129
	v_mov_b32_e32 v22, v129
	v_mov_b32_e32 v45, v129
	v_mov_b32_e32 v44, v129
	v_mov_b32_e32 v43, v129
	v_mov_b32_e32 v42, v129
	v_mov_b32_e32 v21, v129
	v_mov_b32_e32 v20, v129
	v_mov_b32_e32 v19, v129
	v_mov_b32_e32 v18, v129
	v_mov_b32_e32 v109, v129
	v_mov_b32_e32 v108, v129
	v_mov_b32_e32 v107, v129
	v_mov_b32_e32 v106, v129
	s_waitcnt vmcnt(0)
	v_mov_b32_e32 v41, v129
	v_mov_b32_e32 v40, v129
	v_mov_b32_e32 v39, v129
	v_mov_b32_e32 v38, v129
	v_mov_b32_e32 v17, v129
	v_mov_b32_e32 v16, v129
	v_mov_b32_e32 v15, v129
	v_mov_b32_e32 v14, v129
	v_mov_b32_e32 v37, v129
	v_mov_b32_e32 v36, v129
	v_mov_b32_e32 v35, v129
	v_mov_b32_e32 v34, v129
	v_mov_b32_e32 v13, v129
	v_mov_b32_e32 v12, v129
	v_mov_b32_e32 v11, v129
	v_mov_b32_e32 v10, v129
	v_mov_b32_e32 v33, v129
	v_mov_b32_e32 v32, v129
	v_mov_b32_e32 v31, v129
	v_mov_b32_e32 v30, v129
	v_mov_b32_e32 v9, v129
	v_mov_b32_e32 v8, v129
	v_mov_b32_e32 v7, v129
	v_mov_b32_e32 v6, v129
	v_mov_b32_e32 v29, v129
	v_mov_b32_e32 v28, v129
	v_mov_b32_e32 v27, v129
	v_mov_b32_e32 v26, v129
	v_mov_b32_e32 v5, v129
	v_mov_b32_e32 v4, v129
	v_mov_b32_e32 v3, v129
	v_mov_b32_e32 v2, v129
	v_mov_b32_e32 v77, v129
	v_mov_b32_e32 v76, v129
	v_mov_b32_e32 v75, v129
	v_mov_b32_e32 v74, v129
	v_mov_b32_e32 v93, v129
	v_mov_b32_e32 v92, v129
	v_mov_b32_e32 v91, v129
	v_mov_b32_e32 v90, v129
	v_mov_b32_e32 v117, v129
	v_mov_b32_e32 v116, v129
	v_mov_b32_e32 v115, v129
	v_mov_b32_e32 v114, v129
	v_mov_b32_e32 v125, v129
	v_mov_b32_e32 v124, v129
	v_mov_b32_e32 v123, v129
	v_mov_b32_e32 v122, v129
	s_cbranch_vccnz .LBB0_414
	s_add_u32 s58, s62, 0x80
	s_addc_u32 s59, s63, 0
	s_add_u32 s12, s60, 0x100
	v_mov_b32_e32 v122, 0
	s_addc_u32 s13, s61, 0
	s_mov_b32 s15, 0
	v_mov_b32_e32 v123, v122
	v_mov_b32_e32 v124, v122
	v_mov_b32_e32 v125, v122
	v_mov_b32_e32 v114, v122
	v_mov_b32_e32 v115, v122
	v_mov_b32_e32 v116, v122
	v_mov_b32_e32 v117, v122
	v_mov_b32_e32 v90, v122
	v_mov_b32_e32 v91, v122
	v_mov_b32_e32 v92, v122
	v_mov_b32_e32 v93, v122
	v_mov_b32_e32 v74, v122
	v_mov_b32_e32 v75, v122
	v_mov_b32_e32 v76, v122
	v_mov_b32_e32 v77, v122
	v_mov_b32_e32 v2, v122
	v_mov_b32_e32 v3, v122
	v_mov_b32_e32 v4, v122
	v_mov_b32_e32 v5, v122
	v_mov_b32_e32 v26, v122
	v_mov_b32_e32 v27, v122
	v_mov_b32_e32 v28, v122
	v_mov_b32_e32 v29, v122
	v_mov_b32_e32 v6, v122
	v_mov_b32_e32 v7, v122
	v_mov_b32_e32 v8, v122
	v_mov_b32_e32 v9, v122
	v_mov_b32_e32 v30, v122
	v_mov_b32_e32 v31, v122
	v_mov_b32_e32 v32, v122
	v_mov_b32_e32 v33, v122
	v_mov_b32_e32 v10, v122
	v_mov_b32_e32 v11, v122
	v_mov_b32_e32 v12, v122
	v_mov_b32_e32 v13, v122
	v_mov_b32_e32 v34, v122
	v_mov_b32_e32 v35, v122
	v_mov_b32_e32 v36, v122
	v_mov_b32_e32 v37, v122
	v_mov_b32_e32 v14, v122
	v_mov_b32_e32 v15, v122
	v_mov_b32_e32 v16, v122
	v_mov_b32_e32 v17, v122
	v_mov_b32_e32 v38, v122
	v_mov_b32_e32 v39, v122
	v_mov_b32_e32 v40, v122
	v_mov_b32_e32 v41, v122
	v_mov_b32_e32 v106, v122
	v_mov_b32_e32 v107, v122
	v_mov_b32_e32 v108, v122
	v_mov_b32_e32 v109, v122
	v_mov_b32_e32 v18, v122
	v_mov_b32_e32 v19, v122
	v_mov_b32_e32 v20, v122
	v_mov_b32_e32 v21, v122
	v_mov_b32_e32 v42, v122
	v_mov_b32_e32 v43, v122
	v_mov_b32_e32 v44, v122
	v_mov_b32_e32 v45, v122
	v_mov_b32_e32 v22, v122
	v_mov_b32_e32 v23, v122
	v_mov_b32_e32 v24, v122
	v_mov_b32_e32 v25, v122
	v_mov_b32_e32 v46, v122
	v_mov_b32_e32 v47, v122
	v_mov_b32_e32 v48, v122
	v_mov_b32_e32 v49, v122
	v_mov_b32_e32 v110, v122
	v_mov_b32_e32 v111, v122
	v_mov_b32_e32 v112, v122
	v_mov_b32_e32 v113, v122
	v_mov_b32_e32 v50, v122
	v_mov_b32_e32 v51, v122
	v_mov_b32_e32 v52, v122
	v_mov_b32_e32 v53, v122
	v_mov_b32_e32 v78, v122
	v_mov_b32_e32 v79, v122
	v_mov_b32_e32 v80, v122
	v_mov_b32_e32 v81, v122
	v_mov_b32_e32 v54, v122
	v_mov_b32_e32 v55, v122
	v_mov_b32_e32 v56, v122
	v_mov_b32_e32 v57, v122
	v_mov_b32_e32 v82, v122
	v_mov_b32_e32 v83, v122
	v_mov_b32_e32 v84, v122
	v_mov_b32_e32 v85, v122
	v_mov_b32_e32 v58, v122
	v_mov_b32_e32 v59, v122
	v_mov_b32_e32 v60, v122
	v_mov_b32_e32 v61, v122
	v_mov_b32_e32 v86, v122
	v_mov_b32_e32 v87, v122
	v_mov_b32_e32 v88, v122
	v_mov_b32_e32 v89, v122
	v_mov_b32_e32 v62, v122
	v_mov_b32_e32 v63, v122
	v_mov_b32_e32 v64, v122
	v_mov_b32_e32 v65, v122
	v_mov_b32_e32 v94, v122
	v_mov_b32_e32 v95, v122
	v_mov_b32_e32 v96, v122
	v_mov_b32_e32 v97, v122
	v_mov_b32_e32 v118, v122
	v_mov_b32_e32 v119, v122
	v_mov_b32_e32 v120, v122
	v_mov_b32_e32 v121, v122
	v_mov_b32_e32 v66, v122
	v_mov_b32_e32 v67, v122
	v_mov_b32_e32 v68, v122
	v_mov_b32_e32 v69, v122
	v_mov_b32_e32 v98, v122
	v_mov_b32_e32 v99, v122
	v_mov_b32_e32 v100, v122
	v_mov_b32_e32 v101, v122
	v_mov_b32_e32 v70, v122
	v_mov_b32_e32 v71, v122
	v_mov_b32_e32 v72, v122
	v_mov_b32_e32 v73, v122
	v_mov_b32_e32 v102, v122
	v_mov_b32_e32 v103, v122
	v_mov_b32_e32 v104, v122
	v_mov_b32_e32 v105, v122
	v_mov_b32_e32 v126, v122
	v_mov_b32_e32 v127, v122
	v_mov_b32_e32 v128, v122
	v_mov_b32_e32 v129, v122
	s_cmp_ge_u32 s84, 0x100
	s_cbranch_scc0 .Lprio_skip413
	s_setprio 1
; #define PG8_STAGE(bufoff, gbase, voff) do { _Pragma("unroll") for (int _i = 0; _i < 2; ++_i) \
;         __builtin_amdgcn_global_load_lds((const unsigned*)((const char*)(gbase) + (voff)[_i]), (PG8_LAS unsigned*)(lds + (bufoff) + ldsw + _i * 8192), 16, 0, 0); } while (0)
; #define PG8_LDA(dst, b, h) do { _Pragma("unroll") for (int m = 0; m < 4; ++m) _Pragma("unroll") for (int k = 0; k < 2; ++k) dst[m][k] = *(const PG8_LAS bf16x8*)(lds + PG8_SA(b, h) + aoff + m * 2048 + k * 1024); } while (0)
; #define PG8_LDB(dst, b, h) do { _Pragma("unroll") for (int n = 0; n < 2; ++n) _Pragma("unroll") for (int k = 0; k < 2; ++k) dst[n][k] = *(const PG8_LAS bf16x8*)(lds + PG8_SB(b, h) + boff + n * 2048 + k * 1024); } while (0)
; #define PG8_MMA(ai, bj, At, Bt) do { __builtin_amdgcn_s_setprio(1); _Pragma("unroll") for (int m = 0; m < 4; ++m) _Pragma("unroll") for (int n = 0; n < 2; ++n) _Pragma("unroll") for (int k = 0; k < 2; ++k) \
;         acc[ai][bj][m][n] = __builtin_amdgcn_mfma_f32_16x16x32_bf16(Bt[n][k], At[m][k], acc[ai][bj][m][n], 0, 0, 0); __builtin_amdgcn_s_setprio(0); } while (0)
; #define PG8_WAIT_V(n) asm volatile("s_waitcnt vmcnt(" #n ")" ::: "memory")
; #define PG8_BAR __builtin_amdgcn_s_barrier()
; template <class Epi, class Sched, bool ALIGN_EPI = false, bool SP2 = false>
; __device__ __forceinline__ void gemm_phase(PG8_LAS unsigned char* lds, const Gemm g, const Sched& S, const Epi& E, int tid_in) {
;     ...
;         for (int t = 0; t < nt; t += 2) {
;             const bool last = (t == nt - 2);
;             const char* a1 = cA + (size_t)(t + 1) * kstep;
;             const char* a2 = last ? nA : cA + (size_t)(t + 2) * kstep; const char* b2 = last ? nB : cB + (size_t)(t + 2) * kstep;
;             const char* a3 = a2 + kstep; const char* b3 = b2 + kstep;
;             if (last && has_next) S.a_ready(nxt);
;             if constexpr (SP2) {
;             PG8_LDB(B0, 0, 0); PG8_LDB(B1, 0, 1); PG8_SCHED; PG8_LDA(At, 0, 0); PG8_STAGE(PG8_SA(1, 1), a1 + hstepA, voffA);
;             PG8_WAIT_V(8); PG8_WAIT_L(0); PG8_BAR; PG8_MMA(0, 0, At, B0); PG8_MMA(0, 1, At, B1); PG8_BAR; PG8_SCHED;
;             PG8_LDA(At, 0, 1); PG8_STAGE(PG8_SB(0, 0), b2, voffB); PG8_STAGE(PG8_SB(0, 1), b2 + hstep, voffB); PG8_STAGE(PG8_SA(0, 0), a2, voffA);
;             PG8_WAIT_V(8); PG8_WAIT_L(0); PG8_BAR; PG8_MMA(1, 0, At, B0); PG8_MMA(1, 1, At, B1); PG8_BAR; PG8_SCHED;
.Lprio_skip413:
.LBB0_413:
	s_add_i32 s62, s15, 2
	s_add_u32 s60, s58, 0x80
	s_addc_u32 s61, s59, 0
	s_add_i32 s63, 0, 0x10000
	s_cmp_eq_u32 s93, s15
	s_cselect_b32 s61, s1, s61
	s_cselect_b32 s60, s0, s60
	s_cselect_b32 s65, s75, s13
	s_cselect_b32 s64, s74, s12
	s_add_i32 s15, 0, 0x14000
	v_add_u32_e32 v142, s63, v206
	v_add_u32_e32 v146, s15, v206
	ds_read_b128 v[130:133], v142
	ds_read_b128 v[134:137], v142 offset:1024
	ds_read_b128 v[138:141], v142 offset:2048
	ds_read_b128 v[142:145], v142 offset:3072
	ds_read_b128 v[160:163], v146
	ds_read_b128 v[164:167], v146 offset:1024
	ds_read_b128 v[168:171], v146 offset:2048
	ds_read_b128 v[172:175], v146 offset:3072
	v_lshl_add_u64 v[146:147], s[58:59], 0, v[156:157]
	s_add_i32 m0, s78, 0xc000
	ds_read_b128 v[176:179], v222
	ds_read_b128 v[180:183], v222 offset:1024
	ds_read_b128 v[184:187], v222 offset:2048
	ds_read_b128 v[188:191], v222 offset:3072
	ds_read_b128 v[192:195], v222 offset:4096
	ds_read_b128 v[224:227], v222 offset:5120
	ds_read_b128 v[228:231], v222 offset:6144
	ds_read_b128 v[232:235], v222 offset:7168
	global_load_lds_dwordx4 v[146:147], off
	v_lshl_add_u64 v[146:147], s[58:59], 0, v[158:159]
	s_add_i32 m0, s78, 0xe000
	s_nop 0
	global_load_lds_dwordx4 v[146:147], off
	s_waitcnt vmcnt(8)
	s_waitcnt lgkmcnt(0)
	s_barrier
	s_waitcnt lgkmcnt(0)
	v_mfma_f32_16x16x32_bf16 v[126:129], v[130:133], v[176:179], v[126:129]
	v_mfma_f32_16x16x32_bf16 v[122:125], v[138:141], v[176:179], v[122:125]
	v_mfma_f32_16x16x32_bf16 v[102:105], v[130:133], v[184:187], v[102:105]
	v_mfma_f32_16x16x32_bf16 v[70:73], v[138:141], v[184:187], v[70:73]
	v_mfma_f32_16x16x32_bf16 v[98:101], v[130:133], v[192:195], v[98:101]
	v_mfma_f32_16x16x32_bf16 v[66:69], v[138:141], v[192:195], v[66:69]
	v_mfma_f32_16x16x32_bf16 v[118:121], v[130:133], v[228:231], v[118:121]
	v_mfma_f32_16x16x32_bf16 v[114:117], v[138:141], v[228:231], v[114:117]
	v_mfma_f32_16x16x32_bf16 v[126:129], v[134:137], v[180:183], v[126:129]
	v_mfma_f32_16x16x32_bf16 v[122:125], v[142:145], v[180:183], v[122:125]
	v_mfma_f32_16x16x32_bf16 v[102:105], v[134:137], v[188:191], v[102:105]
	v_mfma_f32_16x16x32_bf16 v[70:73], v[142:145], v[188:191], v[70:73]
	v_mfma_f32_16x16x32_bf16 v[98:101], v[134:137], v[224:227], v[98:101]
	v_mfma_f32_16x16x32_bf16 v[66:69], v[142:145], v[224:227], v[66:69]
	v_mfma_f32_16x16x32_bf16 v[118:121], v[134:137], v[232:235], v[118:121]
	v_mfma_f32_16x16x32_bf16 v[114:117], v[142:145], v[232:235], v[114:117]
	v_mfma_f32_16x16x32_bf16 v[94:97], v[160:163], v[176:179], v[94:97]
	v_mfma_f32_16x16x32_bf16 v[62:65], v[168:171], v[176:179], v[62:65]
	v_mfma_f32_16x16x32_bf16 v[86:89], v[160:163], v[184:187], v[86:89]
	v_mfma_f32_16x16x32_bf16 v[58:61], v[168:171], v[184:187], v[58:61]
	v_mfma_f32_16x16x32_bf16 v[82:85], v[160:163], v[192:195], v[82:85]
	v_mfma_f32_16x16x32_bf16 v[54:57], v[168:171], v[192:195], v[54:57]
	v_mfma_f32_16x16x32_bf16 v[78:81], v[160:163], v[228:231], v[78:81]
	v_mfma_f32_16x16x32_bf16 v[50:53], v[168:171], v[228:231], v[50:53]
	v_mfma_f32_16x16x32_bf16 v[94:97], v[164:167], v[180:183], v[94:97]
	v_mfma_f32_16x16x32_bf16 v[62:65], v[172:175], v[180:183], v[62:65]
	v_mfma_f32_16x16x32_bf16 v[86:89], v[164:167], v[188:191], v[86:89]
	v_mfma_f32_16x16x32_bf16 v[58:61], v[172:175], v[188:191], v[58:61]
	v_mfma_f32_16x16x32_bf16 v[82:85], v[164:167], v[224:227], v[82:85]
	v_mfma_f32_16x16x32_bf16 v[54:57], v[172:175], v[224:227], v[54:57]
	v_mfma_f32_16x16x32_bf16 v[78:81], v[164:167], v[232:235], v[78:81]
	v_mfma_f32_16x16x32_bf16 v[50:53], v[172:175], v[232:235], v[50:53]
	s_barrier
	s_add_i32 s63, s63, s91
	v_lshl_add_u64 v[146:147], s[64:65], 0, v[0:1]
	s_mov_b32 m0, s63
	ds_read_b128 v[176:179], v222 offset:16384
	ds_read_b128 v[180:183], v222 offset:17408
	ds_read_b128 v[184:187], v222 offset:18432
	ds_read_b128 v[188:191], v222 offset:19456
	ds_read_b128 v[192:195], v222 offset:20480
	ds_read_b128 v[224:227], v222 offset:21504
	ds_read_b128 v[228:231], v222 offset:22528
	ds_read_b128 v[232:235], v222 offset:23552
	global_load_lds_dwordx4 v[146:147], off
	s_add_i32 m0, s63, 0x2000
	v_lshl_add_u64 v[236:237], s[64:65], 0, v[152:153]
	s_add_u32 s64, s64, s18
	s_addc_u32 s65, s65, s19
	s_add_i32 s15, s15, s91
	global_load_lds_dwordx4 v[236:237], off
	v_lshl_add_u64 v[238:239], s[64:65], 0, v[0:1]
	s_mov_b32 m0, s15
	v_lshl_add_u64 v[240:241], s[64:65], 0, v[152:153]
	global_load_lds_dwordx4 v[238:239], off
	s_add_i32 m0, s15, 0x2000
	v_lshl_add_u64 v[242:243], s[60:61], 0, v[148:149]
	global_load_lds_dwordx4 v[240:241], off
	s_mov_b32 m0, s78
	v_lshl_add_u64 v[244:245], s[60:61], 0, v[150:151]
	global_load_lds_dwordx4 v[242:243], off
	s_mov_b32 m0, s79
	s_nop 0
	global_load_lds_dwordx4 v[244:245], off
	s_waitcnt vmcnt(8)
	s_waitcnt lgkmcnt(0)
	s_barrier
; #define PG8_STAGE(bufoff, gbase, voff) do { _Pragma("unroll") for (int _i = 0; _i < 2; ++_i) \
;         __builtin_amdgcn_global_load_lds((const unsigned*)((const char*)(gbase) + (voff)[_i]), (PG8_LAS unsigned*)(lds + (bufoff) + ldsw + _i * 8192), 16, 0, 0); } while (0)
; #define PG8_LDA(dst, b, h) do { _Pragma("unroll") for (int m = 0; m < 4; ++m) _Pragma("unroll") for (int k = 0; k < 2; ++k) dst[m][k] = *(const PG8_LAS bf16x8*)(lds + PG8_SA(b, h) + aoff + m * 2048 + k * 1024); } while (0)
; #define PG8_LDB(dst, b, h) do { _Pragma("unroll") for (int n = 0; n < 2; ++n) _Pragma("unroll") for (int k = 0; k < 2; ++k) dst[n][k] = *(const PG8_LAS bf16x8*)(lds + PG8_SB(b, h) + boff + n * 2048 + k * 1024); } while (0)
; #define PG8_MMA(ai, bj, At, Bt) do { __builtin_amdgcn_s_setprio(1); _Pragma("unroll") for (int m = 0; m < 4; ++m) _Pragma("unroll") for (int n = 0; n < 2; ++n) _Pragma("unroll") for (int k = 0; k < 2; ++k) \
;         acc[ai][bj][m][n] = __builtin_amdgcn_mfma_f32_16x16x32_bf16(Bt[n][k], At[m][k], acc[ai][bj][m][n], 0, 0, 0); __builtin_amdgcn_s_setprio(0); } while (0)
; #define PG8_WAIT_V(n) asm volatile("s_waitcnt vmcnt(" #n ")" ::: "memory")
; #define PG8_WAIT_L(n) asm volatile("s_waitcnt lgkmcnt(" #n ")" ::: "memory")
; #define PG8_BAR __builtin_amdgcn_s_barrier()
; #define PG8_SCHED __builtin_amdgcn_sched_barrier(0)
; template <class Epi, class Sched, bool ALIGN_EPI = false, bool SP2 = false>
; __device__ __forceinline__ void gemm_phase(PG8_LAS unsigned char* lds, const Gemm g, const Sched& S, const Epi& E, int tid_in) {
;     ...
;             PG8_WAIT_V(8); PG8_WAIT_L(0); PG8_BAR; PG8_MMA(1, 0, At, B0); PG8_MMA(1, 1, At, B1); PG8_BAR; PG8_SCHED;
;             PG8_LDB(B0, 1, 0); PG8_LDB(B1, 1, 1); PG8_SCHED; PG8_LDA(At, 1, 0); PG8_STAGE(PG8_SA(0, 1), a2 + hstepA, voffA);
;             PG8_WAIT_V(8); PG8_WAIT_L(0); PG8_BAR; PG8_MMA(0, 0, At, B0); PG8_MMA(0, 1, At, B1); PG8_BAR; PG8_SCHED;
	s_waitcnt lgkmcnt(0)
	v_mfma_f32_16x16x32_bf16 v[110:113], v[130:133], v[176:179], v[110:113]
	v_mfma_f32_16x16x32_bf16 v[90:93], v[138:141], v[176:179], v[90:93]
	v_mfma_f32_16x16x32_bf16 v[46:49], v[130:133], v[184:187], v[46:49]
	v_mfma_f32_16x16x32_bf16 v[22:25], v[138:141], v[184:187], v[22:25]
	v_mfma_f32_16x16x32_bf16 v[42:45], v[130:133], v[192:195], v[42:45]
	v_mfma_f32_16x16x32_bf16 v[18:21], v[138:141], v[192:195], v[18:21]
	v_mfma_f32_16x16x32_bf16 v[106:109], v[130:133], v[228:231], v[106:109]
	v_mfma_f32_16x16x32_bf16 v[74:77], v[138:141], v[228:231], v[74:77]
	v_mfma_f32_16x16x32_bf16 v[110:113], v[134:137], v[180:183], v[110:113]
	v_mfma_f32_16x16x32_bf16 v[90:93], v[142:145], v[180:183], v[90:93]
	v_mfma_f32_16x16x32_bf16 v[46:49], v[134:137], v[188:191], v[46:49]
	v_mfma_f32_16x16x32_bf16 v[22:25], v[142:145], v[188:191], v[22:25]
	v_mfma_f32_16x16x32_bf16 v[42:45], v[134:137], v[224:227], v[42:45]
	v_mfma_f32_16x16x32_bf16 v[18:21], v[142:145], v[224:227], v[18:21]
	v_mfma_f32_16x16x32_bf16 v[106:109], v[134:137], v[232:235], v[106:109]
	v_mfma_f32_16x16x32_bf16 v[74:77], v[142:145], v[232:235], v[74:77]
	v_mfma_f32_16x16x32_bf16 v[38:41], v[160:163], v[176:179], v[38:41]
	v_mfma_f32_16x16x32_bf16 v[14:17], v[168:171], v[176:179], v[14:17]
	v_mfma_f32_16x16x32_bf16 v[34:37], v[160:163], v[184:187], v[34:37]
	v_mfma_f32_16x16x32_bf16 v[10:13], v[168:171], v[184:187], v[10:13]
	v_mfma_f32_16x16x32_bf16 v[30:33], v[160:163], v[192:195], v[30:33]
	v_mfma_f32_16x16x32_bf16 v[6:9], v[168:171], v[192:195], v[6:9]
	v_mfma_f32_16x16x32_bf16 v[26:29], v[160:163], v[228:231], v[26:29]
	v_mfma_f32_16x16x32_bf16 v[2:5], v[168:171], v[228:231], v[2:5]
	v_mfma_f32_16x16x32_bf16 v[38:41], v[164:167], v[180:183], v[38:41]
	v_mfma_f32_16x16x32_bf16 v[14:17], v[172:175], v[180:183], v[14:17]
	v_mfma_f32_16x16x32_bf16 v[34:37], v[164:167], v[188:191], v[34:37]
	v_mfma_f32_16x16x32_bf16 v[10:13], v[172:175], v[188:191], v[10:13]
	v_mfma_f32_16x16x32_bf16 v[30:33], v[164:167], v[224:227], v[30:33]
	v_mfma_f32_16x16x32_bf16 v[6:9], v[172:175], v[224:227], v[6:9]
	v_mfma_f32_16x16x32_bf16 v[26:29], v[164:167], v[232:235], v[26:29]
	v_mfma_f32_16x16x32_bf16 v[2:5], v[172:175], v[232:235], v[2:5]
	s_barrier
	s_add_i32 s15, 0, 0x18000
	s_add_i32 s63, 0, 0x1c000
	v_add_u32_e32 v142, s15, v206
	v_add_u32_e32 v172, s63, v206
	ds_read_b128 v[130:133], v142
	ds_read_b128 v[134:137], v142 offset:1024
	ds_read_b128 v[138:141], v142 offset:2048
	ds_read_b128 v[142:145], v142 offset:3072
	ds_read_b128 v[160:163], v172
	ds_read_b128 v[164:167], v172 offset:1024
	ds_read_b128 v[168:171], v172 offset:2048
	ds_read_b128 v[172:175], v172 offset:3072
	s_add_u32 s60, s60, s18
	s_addc_u32 s61, s61, s19
	s_mov_b32 m0, s80
	v_lshl_add_u64 v[246:247], s[60:61], 0, v[148:149]
	ds_read_b128 v[176:179], v222 offset:32768
	ds_read_b128 v[180:183], v222 offset:33792
	ds_read_b128 v[184:187], v222 offset:34816
	ds_read_b128 v[188:191], v222 offset:35840
	ds_read_b128 v[192:195], v222 offset:36864
	ds_read_b128 v[224:227], v222 offset:37888
	ds_read_b128 v[228:231], v222 offset:38912
	ds_read_b128 v[232:235], v222 offset:39936
	global_load_lds_dwordx4 v[246:247], off
	v_lshl_add_u64 v[246:247], s[60:61], 0, v[150:151]
	s_mov_b32 m0, s81
	s_nop 0
	global_load_lds_dwordx4 v[246:247], off
	s_waitcnt vmcnt(8)
	s_waitcnt lgkmcnt(0)
	s_barrier
	s_waitcnt lgkmcnt(0)
	v_mfma_f32_16x16x32_bf16 v[126:129], v[130:133], v[176:179], v[126:129]
	v_mfma_f32_16x16x32_bf16 v[122:125], v[138:141], v[176:179], v[122:125]
	v_mfma_f32_16x16x32_bf16 v[102:105], v[130:133], v[184:187], v[102:105]
	v_mfma_f32_16x16x32_bf16 v[70:73], v[138:141], v[184:187], v[70:73]
	v_mfma_f32_16x16x32_bf16 v[98:101], v[130:133], v[192:195], v[98:101]
	v_mfma_f32_16x16x32_bf16 v[66:69], v[138:141], v[192:195], v[66:69]
	v_mfma_f32_16x16x32_bf16 v[118:121], v[130:133], v[228:231], v[118:121]
	v_mfma_f32_16x16x32_bf16 v[114:117], v[138:141], v[228:231], v[114:117]
	v_mfma_f32_16x16x32_bf16 v[126:129], v[134:137], v[180:183], v[126:129]
	v_mfma_f32_16x16x32_bf16 v[122:125], v[142:145], v[180:183], v[122:125]
	v_mfma_f32_16x16x32_bf16 v[102:105], v[134:137], v[188:191], v[102:105]
	v_mfma_f32_16x16x32_bf16 v[70:73], v[142:145], v[188:191], v[70:73]
	v_mfma_f32_16x16x32_bf16 v[98:101], v[134:137], v[224:227], v[98:101]
	v_mfma_f32_16x16x32_bf16 v[66:69], v[142:145], v[224:227], v[66:69]
	v_mfma_f32_16x16x32_bf16 v[118:121], v[134:137], v[232:235], v[118:121]
	v_mfma_f32_16x16x32_bf16 v[114:117], v[142:145], v[232:235], v[114:117]
	v_mfma_f32_16x16x32_bf16 v[94:97], v[160:163], v[176:179], v[94:97]
	v_mfma_f32_16x16x32_bf16 v[62:65], v[168:171], v[176:179], v[62:65]
	v_mfma_f32_16x16x32_bf16 v[86:89], v[160:163], v[184:187], v[86:89]
	v_mfma_f32_16x16x32_bf16 v[58:61], v[168:171], v[184:187], v[58:61]
	v_mfma_f32_16x16x32_bf16 v[82:85], v[160:163], v[192:195], v[82:85]
	v_mfma_f32_16x16x32_bf16 v[54:57], v[168:171], v[192:195], v[54:57]
	v_mfma_f32_16x16x32_bf16 v[78:81], v[160:163], v[228:231], v[78:81]
	v_mfma_f32_16x16x32_bf16 v[50:53], v[168:171], v[228:231], v[50:53]
	v_mfma_f32_16x16x32_bf16 v[94:97], v[164:167], v[180:183], v[94:97]
	v_mfma_f32_16x16x32_bf16 v[62:65], v[172:175], v[180:183], v[62:65]
	v_mfma_f32_16x16x32_bf16 v[86:89], v[164:167], v[188:191], v[86:89]
	v_mfma_f32_16x16x32_bf16 v[58:61], v[172:175], v[188:191], v[58:61]
	v_mfma_f32_16x16x32_bf16 v[82:85], v[164:167], v[224:227], v[82:85]
	v_mfma_f32_16x16x32_bf16 v[54:57], v[172:175], v[224:227], v[54:57]
	v_mfma_f32_16x16x32_bf16 v[78:81], v[164:167], v[232:235], v[78:81]
	v_mfma_f32_16x16x32_bf16 v[50:53], v[172:175], v[232:235], v[50:53]
	s_barrier
; #define PG8_STAGE(bufoff, gbase, voff) do { _Pragma("unroll") for (int _i = 0; _i < 2; ++_i) \
;         __builtin_amdgcn_global_load_lds((const unsigned*)((const char*)(gbase) + (voff)[_i]), (PG8_LAS unsigned*)(lds + (bufoff) + ldsw + _i * 8192), 16, 0, 0); } while (0)
; #define PG8_LDA(dst, b, h) do { _Pragma("unroll") for (int m = 0; m < 4; ++m) _Pragma("unroll") for (int k = 0; k < 2; ++k) dst[m][k] = *(const PG8_LAS bf16x8*)(lds + PG8_SA(b, h) + aoff + m * 2048 + k * 1024); } while (0)
; #define PG8_MMA(ai, bj, At, Bt) do { __builtin_amdgcn_s_setprio(1); _Pragma("unroll") for (int m = 0; m < 4; ++m) _Pragma("unroll") for (int n = 0; n < 2; ++n) _Pragma("unroll") for (int k = 0; k < 2; ++k) \
;         acc[ai][bj][m][n] = __builtin_amdgcn_mfma_f32_16x16x32_bf16(Bt[n][k], At[m][k], acc[ai][bj][m][n], 0, 0, 0); __builtin_amdgcn_s_setprio(0); } while (0)
; #define PG8_WAIT_V(n) asm volatile("s_waitcnt vmcnt(" #n ")" ::: "memory")
; #define PG8_WAIT_L(n) asm volatile("s_waitcnt lgkmcnt(" #n ")" ::: "memory")
; #define PG8_BAR __builtin_amdgcn_s_barrier()
; #define PG8_SCHED __builtin_amdgcn_sched_barrier(0)
; template <class Epi, class Sched, bool ALIGN_EPI = false, bool SP2 = false>
; __device__ __forceinline__ void gemm_phase(PG8_LAS unsigned char* lds, const Gemm g, const Sched& S, const Epi& E, int tid_in) {
;     ...
;         for (int t = 0; t < nt; t += 2) {
;             const bool last = (t == nt - 2);
;             const char* a1 = cA + (size_t)(t + 1) * kstep;
;             const char* a2 = last ? nA : cA + (size_t)(t + 2) * kstep; const char* b2 = last ? nB : cB + (size_t)(t + 2) * kstep;
;             const char* a3 = a2 + kstep; const char* b3 = b2 + kstep;
;     ...
;             PG8_LDA(At, 1, 1); PG8_STAGE(PG8_SB(1, 0), b3, voffB); PG8_STAGE(PG8_SB(1, 1), b3 + hstep, voffB); PG8_STAGE(PG8_SA(1, 0), a3, voffA);
;             PG8_WAIT_V(8); PG8_WAIT_L(0); PG8_BAR; PG8_MMA(1, 0, At, B0); PG8_MMA(1, 1, At, B1); PG8_BAR; PG8_SCHED;
	s_add_i32 s15, s15, s91
	v_lshl_add_u64 v[146:147], v[146:147], 0, s[28:29]
	s_mov_b32 m0, s15
	ds_read_b128 v[176:179], v222 offset:49152
	ds_read_b128 v[180:183], v222 offset:50176
	ds_read_b128 v[184:187], v222 offset:51200
	ds_read_b128 v[188:191], v222 offset:52224
	ds_read_b128 v[192:195], v222 offset:53248
	ds_read_b128 v[224:227], v222 offset:54272
	ds_read_b128 v[228:231], v222 offset:55296
	ds_read_b128 v[232:235], v222 offset:56320
	global_load_lds_dwordx4 v[146:147], off
	v_lshl_add_u64 v[146:147], v[236:237], 0, s[28:29]
	s_add_i32 m0, s15, 0x2000
	s_add_i32 s15, s63, s91
	global_load_lds_dwordx4 v[146:147], off
	v_lshl_add_u64 v[146:147], v[238:239], 0, s[28:29]
	s_mov_b32 m0, s15
	s_nop 0
	global_load_lds_dwordx4 v[146:147], off
	v_lshl_add_u64 v[146:147], v[240:241], 0, s[28:29]
	s_add_i32 m0, s15, 0x2000
	s_nop 0
	global_load_lds_dwordx4 v[146:147], off
	v_lshl_add_u64 v[146:147], v[242:243], 0, s[28:29]
	s_mov_b32 m0, s11
	s_nop 0
	global_load_lds_dwordx4 v[146:147], off
	v_lshl_add_u64 v[146:147], v[244:245], 0, s[28:29]
	s_mov_b32 m0, s92
	s_nop 0
	global_load_lds_dwordx4 v[146:147], off
	s_waitcnt vmcnt(8)
	s_waitcnt lgkmcnt(0)
	s_barrier
	s_waitcnt lgkmcnt(0)
	v_mfma_f32_16x16x32_bf16 v[110:113], v[130:133], v[176:179], v[110:113]
	v_mfma_f32_16x16x32_bf16 v[90:93], v[138:141], v[176:179], v[90:93]
	v_mfma_f32_16x16x32_bf16 v[46:49], v[130:133], v[184:187], v[46:49]
	v_mfma_f32_16x16x32_bf16 v[22:25], v[138:141], v[184:187], v[22:25]
	v_mfma_f32_16x16x32_bf16 v[42:45], v[130:133], v[192:195], v[42:45]
	v_mfma_f32_16x16x32_bf16 v[18:21], v[138:141], v[192:195], v[18:21]
	v_mfma_f32_16x16x32_bf16 v[106:109], v[130:133], v[228:231], v[106:109]
	v_mfma_f32_16x16x32_bf16 v[74:77], v[138:141], v[228:231], v[74:77]
	v_mfma_f32_16x16x32_bf16 v[110:113], v[134:137], v[180:183], v[110:113]
	v_mfma_f32_16x16x32_bf16 v[90:93], v[142:145], v[180:183], v[90:93]
	v_mfma_f32_16x16x32_bf16 v[46:49], v[134:137], v[188:191], v[46:49]
	v_mfma_f32_16x16x32_bf16 v[22:25], v[142:145], v[188:191], v[22:25]
	v_mfma_f32_16x16x32_bf16 v[42:45], v[134:137], v[224:227], v[42:45]
	v_mfma_f32_16x16x32_bf16 v[18:21], v[142:145], v[224:227], v[18:21]
	v_mfma_f32_16x16x32_bf16 v[106:109], v[134:137], v[232:235], v[106:109]
	v_mfma_f32_16x16x32_bf16 v[74:77], v[142:145], v[232:235], v[74:77]
	v_mfma_f32_16x16x32_bf16 v[38:41], v[160:163], v[176:179], v[38:41]
	v_mfma_f32_16x16x32_bf16 v[14:17], v[168:171], v[176:179], v[14:17]
	v_mfma_f32_16x16x32_bf16 v[34:37], v[160:163], v[184:187], v[34:37]
	v_mfma_f32_16x16x32_bf16 v[10:13], v[168:171], v[184:187], v[10:13]
	v_mfma_f32_16x16x32_bf16 v[30:33], v[160:163], v[192:195], v[30:33]
	v_mfma_f32_16x16x32_bf16 v[6:9], v[168:171], v[192:195], v[6:9]
	v_mfma_f32_16x16x32_bf16 v[26:29], v[160:163], v[228:231], v[26:29]
	v_mfma_f32_16x16x32_bf16 v[2:5], v[168:171], v[228:231], v[2:5]
	v_mfma_f32_16x16x32_bf16 v[38:41], v[164:167], v[180:183], v[38:41]
	v_mfma_f32_16x16x32_bf16 v[14:17], v[172:175], v[180:183], v[14:17]
	v_mfma_f32_16x16x32_bf16 v[34:37], v[164:167], v[188:191], v[34:37]
	v_mfma_f32_16x16x32_bf16 v[10:13], v[172:175], v[188:191], v[10:13]
	v_mfma_f32_16x16x32_bf16 v[30:33], v[164:167], v[224:227], v[30:33]
	v_mfma_f32_16x16x32_bf16 v[6:9], v[172:175], v[224:227], v[6:9]
	v_mfma_f32_16x16x32_bf16 v[26:29], v[164:167], v[232:235], v[26:29]
	v_mfma_f32_16x16x32_bf16 v[2:5], v[172:175], v[232:235], v[2:5]
	s_barrier
	s_add_u32 s58, s58, 0x100
	s_addc_u32 s59, s59, 0
	s_add_u32 s12, s12, 0x100
	s_addc_u32 s13, s13, 0
	s_cmp_ge_i32 s62, s10
	s_mov_b32 s15, s62
	s_cbranch_scc0 .LBB0_413
	s_setprio 0

; template <class Epi, class Sched, bool ALIGN_EPI = false, bool SP2 = false>
; __device__ __forceinline__ void gemm_phase(PG8_LAS unsigned char* lds, const Gemm g, const Sched& S, const Epi& E, int tid_in) {
;     ...
;         const bool has_next = S.next(ui + 1, nxt);
;         const char* nA = has_next ? (const char*)g.A + (size_t)nxt.pm * tstepA + a_unit_off(g, nxt.pn) : cA; const char* nB = has_next ? (const char*)g.Bt + (size_t)nxt.pn * tstepB : cB;
; #pragma unroll 1
;         for (int t = 0; t < nt; t += 2) {
;             const bool last = (t == nt - 2);
;             const char* a1 = cA + (size_t)(t + 1) * kstep;
;             const char* a2 = last ? nA : cA + (size_t)(t + 2) * kstep; const char* b2 = last ? nB : cB + (size_t)(t + 2) * kstep;
;             const char* a3 = a2 + kstep; const char* b3 = b2 + kstep;
;     ...
; #pragma unroll
;         for (int a = 0; a < 2; ++a)
; #pragma unroll
;             for (int b = 0; b < 2; ++b)
; #pragma unroll
;                 for (int m = 0; m < 4; ++m)
; #pragma unroll
;                     for (int n = 0; n < 2; ++n) acc[a][b][m][n] = (f32x4){0.f, 0.f, 0.f, 0.f};
;         cur = nxt; cA = nA; cB = nB; ++ui;
.LBB0_540:
	v_mov_b32_e32 v129, 0
	s_andn2_b64 vcc, exec, s[46:47]
	v_mov_b32_e32 v128, v129
	v_mov_b32_e32 v127, v129
	v_mov_b32_e32 v126, v129
	v_mov_b32_e32 v125, v129
	v_mov_b32_e32 v124, v129
	v_mov_b32_e32 v123, v129
	v_mov_b32_e32 v122, v129
	v_mov_b32_e32 v113, v129
	v_mov_b32_e32 v112, v129
	v_mov_b32_e32 v111, v129
	v_mov_b32_e32 v110, v129
	v_mov_b32_e32 v109, v129
	v_mov_b32_e32 v108, v129
	v_mov_b32_e32 v107, v129
	v_mov_b32_e32 v106, v129
	v_mov_b32_e32 v97, v129
	v_mov_b32_e32 v96, v129
	v_mov_b32_e32 v95, v129
	v_mov_b32_e32 v94, v129
	v_mov_b32_e32 v93, v129
	v_mov_b32_e32 v92, v129
	v_mov_b32_e32 v91, v129
	v_mov_b32_e32 v90, v129
	v_mov_b32_e32 v81, v129
	v_mov_b32_e32 v80, v129
	v_mov_b32_e32 v79, v129
	v_mov_b32_e32 v78, v129
	v_mov_b32_e32 v77, v129
	v_mov_b32_e32 v76, v129
	v_mov_b32_e32 v75, v129
	v_mov_b32_e32 v74, v129
	v_mov_b32_e32 v121, v129
	v_mov_b32_e32 v120, v129
	v_mov_b32_e32 v119, v129
	v_mov_b32_e32 v118, v129
	v_mov_b32_e32 v117, v129
	v_mov_b32_e32 v116, v129
	v_mov_b32_e32 v115, v129
	v_mov_b32_e32 v114, v129
	v_mov_b32_e32 v105, v129
	v_mov_b32_e32 v104, v129
	v_mov_b32_e32 v103, v129
	v_mov_b32_e32 v102, v129
	v_mov_b32_e32 v101, v129
	v_mov_b32_e32 v100, v129
	v_mov_b32_e32 v99, v129
	v_mov_b32_e32 v98, v129
	v_mov_b32_e32 v89, v129
	v_mov_b32_e32 v88, v129
	v_mov_b32_e32 v87, v129
	v_mov_b32_e32 v86, v129
	v_mov_b32_e32 v85, v129
	v_mov_b32_e32 v84, v129
	v_mov_b32_e32 v83, v129
	v_mov_b32_e32 v82, v129
	v_mov_b32_e32 v73, v129
	v_mov_b32_e32 v72, v129
	v_mov_b32_e32 v71, v129
	v_mov_b32_e32 v70, v129
	v_mov_b32_e32 v69, v129
	v_mov_b32_e32 v68, v129
	v_mov_b32_e32 v67, v129
	v_mov_b32_e32 v66, v129
	v_mov_b32_e32 v65, v129
	v_mov_b32_e32 v64, v129
	v_mov_b32_e32 v63, v129
	v_mov_b32_e32 v62, v129
	v_mov_b32_e32 v61, v129
	v_mov_b32_e32 v60, v129
	v_mov_b32_e32 v59, v129
	v_mov_b32_e32 v58, v129
	s_waitcnt vmcnt(0)
	v_mov_b32_e32 v49, v129
	v_mov_b32_e32 v48, v129
	v_mov_b32_e32 v47, v129
	v_mov_b32_e32 v46, v129
	v_mov_b32_e32 v45, v129
	v_mov_b32_e32 v44, v129
	v_mov_b32_e32 v43, v129
	v_mov_b32_e32 v42, v129
	s_waitcnt vmcnt(0)
	v_mov_b32_e32 v33, v129
	v_mov_b32_e32 v32, v129
	v_mov_b32_e32 v31, v129
	v_mov_b32_e32 v30, v129
	v_mov_b32_e32 v29, v129
	v_mov_b32_e32 v28, v129
	v_mov_b32_e32 v27, v129
	v_mov_b32_e32 v26, v129
	v_mov_b32_e32 v17, v129
	v_mov_b32_e32 v16, v129
	v_mov_b32_e32 v15, v129
	v_mov_b32_e32 v14, v129
	v_mov_b32_e32 v13, v129
	v_mov_b32_e32 v12, v129
	v_mov_b32_e32 v11, v129
	v_mov_b32_e32 v10, v129
	v_mov_b32_e32 v57, v129
	v_mov_b32_e32 v56, v129
	v_mov_b32_e32 v55, v129
	v_mov_b32_e32 v54, v129
	v_mov_b32_e32 v53, v129
	v_mov_b32_e32 v52, v129
	v_mov_b32_e32 v51, v129
	v_mov_b32_e32 v50, v129
	v_mov_b32_e32 v41, v129
	v_mov_b32_e32 v40, v129
	v_mov_b32_e32 v39, v129
	v_mov_b32_e32 v38, v129
	v_mov_b32_e32 v37, v129
	v_mov_b32_e32 v36, v129
	v_mov_b32_e32 v35, v129
	v_mov_b32_e32 v34, v129
	v_mov_b32_e32 v25, v129
	v_mov_b32_e32 v24, v129
	v_mov_b32_e32 v23, v129
	v_mov_b32_e32 v22, v129
	v_mov_b32_e32 v21, v129
	v_mov_b32_e32 v20, v129
	v_mov_b32_e32 v19, v129
	v_mov_b32_e32 v18, v129
	v_mov_b32_e32 v9, v129
	v_mov_b32_e32 v8, v129
	v_mov_b32_e32 v7, v129
	v_mov_b32_e32 v6, v129
	v_mov_b32_e32 v5, v129
	v_mov_b32_e32 v4, v129
	v_mov_b32_e32 v3, v129
	v_mov_b32_e32 v2, v129
	s_cbranch_vccnz .LBB0_544
	s_add_u32 s52, s52, 0x80
	s_addc_u32 s53, s53, 0
	s_add_u32 s12, s54, 0x100
	v_mov_b32_e32 v2, 0
	s_addc_u32 s13, s55, 0
	s_mov_b32 s15, 0
	v_mov_b32_e32 v3, v2
	v_mov_b32_e32 v4, v2
	v_mov_b32_e32 v5, v2
	v_mov_b32_e32 v6, v2
	v_mov_b32_e32 v7, v2
	v_mov_b32_e32 v8, v2
	v_mov_b32_e32 v9, v2
	v_mov_b32_e32 v18, v2
	v_mov_b32_e32 v19, v2
	v_mov_b32_e32 v20, v2
	v_mov_b32_e32 v21, v2
	v_mov_b32_e32 v22, v2
	v_mov_b32_e32 v23, v2
	v_mov_b32_e32 v24, v2
	v_mov_b32_e32 v25, v2
	v_mov_b32_e32 v34, v2
	v_mov_b32_e32 v35, v2
	v_mov_b32_e32 v36, v2
	v_mov_b32_e32 v37, v2
	v_mov_b32_e32 v38, v2
	v_mov_b32_e32 v39, v2
	v_mov_b32_e32 v40, v2
	v_mov_b32_e32 v41, v2
	v_mov_b32_e32 v50, v2
	v_mov_b32_e32 v51, v2
	v_mov_b32_e32 v52, v2
	v_mov_b32_e32 v53, v2
	v_mov_b32_e32 v54, v2
	v_mov_b32_e32 v55, v2
	v_mov_b32_e32 v56, v2
	v_mov_b32_e32 v57, v2
	v_mov_b32_e32 v10, v2
	v_mov_b32_e32 v11, v2
	v_mov_b32_e32 v12, v2
	v_mov_b32_e32 v13, v2
	v_mov_b32_e32 v14, v2
	v_mov_b32_e32 v15, v2
	v_mov_b32_e32 v16, v2
	v_mov_b32_e32 v17, v2
	v_mov_b32_e32 v26, v2
	v_mov_b32_e32 v27, v2
	v_mov_b32_e32 v28, v2
	v_mov_b32_e32 v29, v2
	v_mov_b32_e32 v30, v2
	v_mov_b32_e32 v31, v2
	v_mov_b32_e32 v32, v2
	v_mov_b32_e32 v33, v2
	v_mov_b32_e32 v42, v2
	v_mov_b32_e32 v43, v2
	v_mov_b32_e32 v44, v2
	v_mov_b32_e32 v45, v2
	v_mov_b32_e32 v46, v2
	v_mov_b32_e32 v47, v2
	v_mov_b32_e32 v48, v2
	v_mov_b32_e32 v49, v2
	v_mov_b32_e32 v58, v2
	v_mov_b32_e32 v59, v2
	v_mov_b32_e32 v60, v2
	v_mov_b32_e32 v61, v2
	v_mov_b32_e32 v62, v2
	v_mov_b32_e32 v63, v2
	v_mov_b32_e32 v64, v2
	v_mov_b32_e32 v65, v2
	v_mov_b32_e32 v66, v2
	v_mov_b32_e32 v67, v2
	v_mov_b32_e32 v68, v2
	v_mov_b32_e32 v69, v2
	v_mov_b32_e32 v70, v2
	v_mov_b32_e32 v71, v2
	v_mov_b32_e32 v72, v2
	v_mov_b32_e32 v73, v2
	v_mov_b32_e32 v82, v2
	v_mov_b32_e32 v83, v2
	v_mov_b32_e32 v84, v2
	v_mov_b32_e32 v85, v2
	v_mov_b32_e32 v86, v2
	v_mov_b32_e32 v87, v2
	v_mov_b32_e32 v88, v2
	v_mov_b32_e32 v89, v2
	v_mov_b32_e32 v98, v2
	v_mov_b32_e32 v99, v2
	v_mov_b32_e32 v100, v2
	v_mov_b32_e32 v101, v2
	v_mov_b32_e32 v102, v2
	v_mov_b32_e32 v103, v2
	v_mov_b32_e32 v104, v2
	v_mov_b32_e32 v105, v2
	v_mov_b32_e32 v114, v2
	v_mov_b32_e32 v115, v2
	v_mov_b32_e32 v116, v2
	v_mov_b32_e32 v117, v2
	v_mov_b32_e32 v118, v2
	v_mov_b32_e32 v119, v2
	v_mov_b32_e32 v120, v2
	v_mov_b32_e32 v121, v2
	v_mov_b32_e32 v74, v2
	v_mov_b32_e32 v75, v2
	v_mov_b32_e32 v76, v2
	v_mov_b32_e32 v77, v2
	v_mov_b32_e32 v78, v2
	v_mov_b32_e32 v79, v2
	v_mov_b32_e32 v80, v2
	v_mov_b32_e32 v81, v2
	v_mov_b32_e32 v90, v2
	v_mov_b32_e32 v91, v2
	v_mov_b32_e32 v92, v2
	v_mov_b32_e32 v93, v2
	v_mov_b32_e32 v94, v2
	v_mov_b32_e32 v95, v2
	v_mov_b32_e32 v96, v2
	v_mov_b32_e32 v97, v2
	v_mov_b32_e32 v106, v2
	v_mov_b32_e32 v107, v2
	v_mov_b32_e32 v108, v2
	v_mov_b32_e32 v109, v2
	v_mov_b32_e32 v110, v2
	v_mov_b32_e32 v111, v2
	v_mov_b32_e32 v112, v2
	v_mov_b32_e32 v113, v2
	v_mov_b32_e32 v122, v2
	v_mov_b32_e32 v123, v2
	v_mov_b32_e32 v124, v2
	v_mov_b32_e32 v125, v2
	v_mov_b32_e32 v126, v2
	v_mov_b32_e32 v127, v2
	v_mov_b32_e32 v128, v2
	v_mov_b32_e32 v129, v2
	s_cmp_ge_u32 s84, 0x100
	s_cbranch_scc0 .Lprio_skip542
	s_setprio 1
; #define PG8_STAGE(bufoff, gbase, voff) do { _Pragma("unroll") for (int _i = 0; _i < 2; ++_i) \
;         __builtin_amdgcn_global_load_lds((const unsigned*)((const char*)(gbase) + (voff)[_i]), (PG8_LAS unsigned*)(lds + (bufoff) + ldsw + _i * 8192), 16, 0, 0); } while (0)
; #define PG8_LDA(dst, b, h) do { _Pragma("unroll") for (int m = 0; m < 4; ++m) _Pragma("unroll") for (int k = 0; k < 2; ++k) dst[m][k] = *(const PG8_LAS bf16x8*)(lds + PG8_SA(b, h) + aoff + m * 2048 + k * 1024); } while (0)
; #define PG8_LDB(dst, b, h) do { _Pragma("unroll") for (int n = 0; n < 2; ++n) _Pragma("unroll") for (int k = 0; k < 2; ++k) dst[n][k] = *(const PG8_LAS bf16x8*)(lds + PG8_SB(b, h) + boff + n * 2048 + k * 1024); } while (0)
; #define PG8_MMA(ai, bj, At, Bt) do { __builtin_amdgcn_s_setprio(1); _Pragma("unroll") for (int m = 0; m < 4; ++m) _Pragma("unroll") for (int n = 0; n < 2; ++n) _Pragma("unroll") for (int k = 0; k < 2; ++k) \
;         acc[ai][bj][m][n] = __builtin_amdgcn_mfma_f32_16x16x32_bf16(Bt[n][k], At[m][k], acc[ai][bj][m][n], 0, 0, 0); __builtin_amdgcn_s_setprio(0); } while (0)
; #define PG8_WAIT_V(n) asm volatile("s_waitcnt vmcnt(" #n ")" ::: "memory")
; #define PG8_BAR __builtin_amdgcn_s_barrier()
; template <class Epi, class Sched, bool ALIGN_EPI = false, bool SP2 = false>
; __device__ __forceinline__ void gemm_phase(PG8_LAS unsigned char* lds, const Gemm g, const Sched& S, const Epi& E, int tid_in) {
;     ...
;         for (int t = 0; t < nt; t += 2) {
;             const bool last = (t == nt - 2);
;             const char* a1 = cA + (size_t)(t + 1) * kstep;
;             const char* a2 = last ? nA : cA + (size_t)(t + 2) * kstep; const char* b2 = last ? nB : cB + (size_t)(t + 2) * kstep;
;             const char* a3 = a2 + kstep; const char* b3 = b2 + kstep;
;             if (last && has_next) S.a_ready(nxt);
;             if constexpr (SP2) {
;             PG8_LDB(B0, 0, 0); PG8_LDB(B1, 0, 1); PG8_SCHED; PG8_LDA(At, 0, 0); PG8_STAGE(PG8_SA(1, 1), a1 + hstepA, voffA);
;             PG8_WAIT_V(8); PG8_WAIT_L(0); PG8_BAR; PG8_MMA(0, 0, At, B0); PG8_MMA(0, 1, At, B1); PG8_BAR; PG8_SCHED;
;             PG8_LDA(At, 0, 1); PG8_STAGE(PG8_SB(0, 0), b2, voffB); PG8_STAGE(PG8_SB(0, 1), b2 + hstep, voffB); PG8_STAGE(PG8_SA(0, 0), a2, voffA);
;             PG8_WAIT_V(8); PG8_WAIT_L(0); PG8_BAR; PG8_MMA(1, 0, At, B0); PG8_MMA(1, 1, At, B1); PG8_BAR; PG8_SCHED;
.Lprio_skip542:
.LBB0_542:
	s_add_i32 s57, s15, 2
	s_add_u32 s54, s52, 0x80
	s_addc_u32 s55, s53, 0
	s_add_i32 s81, 0, 0x10000
	s_cmp_eq_u32 s70, s15
	s_cselect_b32 s55, s41, s55
	s_cselect_b32 s54, s40, s54
	v_add_u32_e32 v148, s81, v151
	s_cselect_b32 s59, s51, s13
	s_cselect_b32 s58, s50, s12
	s_add_i32 s15, 0, 0x14000
	ds_read_b128 v[140:143], v148
	ds_read_b128 v[144:147], v148 offset:1024
	ds_read_b128 v[154:157], v148 offset:2048
	ds_read_b128 v[158:161], v148 offset:3072
	v_add_u32_e32 v148, s15, v151
	ds_read_b128 v[162:165], v148
	ds_read_b128 v[166:169], v148 offset:1024
	ds_read_b128 v[170:173], v148 offset:2048
	ds_read_b128 v[174:177], v148 offset:3072
	v_lshl_add_u64 v[148:149], s[52:53], 0, v[136:137]
	s_add_i32 m0, s62, 0xc000
	ds_read_b128 v[178:181], v153
	ds_read_b128 v[182:185], v153 offset:1024
	ds_read_b128 v[186:189], v153 offset:2048
	ds_read_b128 v[190:193], v153 offset:3072
	ds_read_b128 v[204:207], v153 offset:4096
	ds_read_b128 v[208:211], v153 offset:5120
	ds_read_b128 v[212:215], v153 offset:6144
	ds_read_b128 v[216:219], v153 offset:7168
	global_load_lds_dwordx4 v[148:149], off
	v_lshl_add_u64 v[148:149], s[52:53], 0, v[138:139]
	s_add_i32 m0, s62, 0xe000
	s_nop 0
	global_load_lds_dwordx4 v[148:149], off
	s_waitcnt vmcnt(8)
	s_waitcnt lgkmcnt(0)
	s_barrier
	s_waitcnt lgkmcnt(0)
	v_mfma_f32_16x16x32_bf16 v[126:129], v[140:143], v[178:181], v[126:129]
	v_mfma_f32_16x16x32_bf16 v[122:125], v[154:157], v[178:181], v[122:125]
	v_mfma_f32_16x16x32_bf16 v[110:113], v[140:143], v[186:189], v[110:113]
	v_mfma_f32_16x16x32_bf16 v[106:109], v[154:157], v[186:189], v[106:109]
	v_mfma_f32_16x16x32_bf16 v[94:97], v[140:143], v[204:207], v[94:97]
	v_mfma_f32_16x16x32_bf16 v[90:93], v[154:157], v[204:207], v[90:93]
	v_mfma_f32_16x16x32_bf16 v[78:81], v[140:143], v[212:215], v[78:81]
	v_mfma_f32_16x16x32_bf16 v[74:77], v[154:157], v[212:215], v[74:77]
	v_mfma_f32_16x16x32_bf16 v[126:129], v[144:147], v[182:185], v[126:129]
	v_mfma_f32_16x16x32_bf16 v[122:125], v[158:161], v[182:185], v[122:125]
	v_mfma_f32_16x16x32_bf16 v[110:113], v[144:147], v[190:193], v[110:113]
	v_mfma_f32_16x16x32_bf16 v[106:109], v[158:161], v[190:193], v[106:109]
	v_mfma_f32_16x16x32_bf16 v[94:97], v[144:147], v[208:211], v[94:97]
	v_mfma_f32_16x16x32_bf16 v[90:93], v[158:161], v[208:211], v[90:93]
	v_mfma_f32_16x16x32_bf16 v[78:81], v[144:147], v[216:219], v[78:81]
	v_mfma_f32_16x16x32_bf16 v[74:77], v[158:161], v[216:219], v[74:77]
	v_mfma_f32_16x16x32_bf16 v[118:121], v[162:165], v[178:181], v[118:121]
	v_mfma_f32_16x16x32_bf16 v[114:117], v[170:173], v[178:181], v[114:117]
	v_mfma_f32_16x16x32_bf16 v[102:105], v[162:165], v[186:189], v[102:105]
	v_mfma_f32_16x16x32_bf16 v[98:101], v[170:173], v[186:189], v[98:101]
	v_mfma_f32_16x16x32_bf16 v[86:89], v[162:165], v[204:207], v[86:89]
	v_mfma_f32_16x16x32_bf16 v[82:85], v[170:173], v[204:207], v[82:85]
	v_mfma_f32_16x16x32_bf16 v[70:73], v[162:165], v[212:215], v[70:73]
	v_mfma_f32_16x16x32_bf16 v[66:69], v[170:173], v[212:215], v[66:69]
	v_mfma_f32_16x16x32_bf16 v[118:121], v[166:169], v[182:185], v[118:121]
	v_mfma_f32_16x16x32_bf16 v[114:117], v[174:177], v[182:185], v[114:117]
	v_mfma_f32_16x16x32_bf16 v[102:105], v[166:169], v[190:193], v[102:105]
	v_mfma_f32_16x16x32_bf16 v[98:101], v[174:177], v[190:193], v[98:101]
	v_mfma_f32_16x16x32_bf16 v[86:89], v[166:169], v[208:211], v[86:89]
	v_mfma_f32_16x16x32_bf16 v[82:85], v[174:177], v[208:211], v[82:85]
	v_mfma_f32_16x16x32_bf16 v[70:73], v[166:169], v[216:219], v[70:73]
	v_mfma_f32_16x16x32_bf16 v[66:69], v[174:177], v[216:219], v[66:69]
	s_barrier
	s_add_i32 s81, s81, s2
	v_lshl_add_u64 v[148:149], s[58:59], 0, v[0:1]
	s_mov_b32 m0, s81
	ds_read_b128 v[178:181], v153 offset:16384
	ds_read_b128 v[182:185], v153 offset:17408
	ds_read_b128 v[186:189], v153 offset:18432
	ds_read_b128 v[190:193], v153 offset:19456
	ds_read_b128 v[204:207], v153 offset:20480
	ds_read_b128 v[208:211], v153 offset:21504
	ds_read_b128 v[212:215], v153 offset:22528
	ds_read_b128 v[216:219], v153 offset:23552
	global_load_lds_dwordx4 v[148:149], off
	s_add_i32 m0, s81, 0x2000
	v_lshl_add_u64 v[194:195], s[58:59], 0, v[134:135]
	s_add_u32 s58, s58, s22
	s_addc_u32 s59, s59, s23
	s_add_i32 s15, s15, s2
	global_load_lds_dwordx4 v[194:195], off
	v_lshl_add_u64 v[220:221], s[58:59], 0, v[0:1]
	s_mov_b32 m0, s15
	v_lshl_add_u64 v[222:223], s[58:59], 0, v[134:135]
	global_load_lds_dwordx4 v[220:221], off
	s_add_i32 m0, s15, 0x2000
	v_lshl_add_u64 v[224:225], s[54:55], 0, v[130:131]
	global_load_lds_dwordx4 v[222:223], off
	s_mov_b32 m0, s62
	v_lshl_add_u64 v[226:227], s[54:55], 0, v[132:133]
	global_load_lds_dwordx4 v[224:225], off
	s_mov_b32 m0, s63
	s_nop 0
	global_load_lds_dwordx4 v[226:227], off
	s_waitcnt vmcnt(8)
	s_waitcnt lgkmcnt(0)
	s_barrier
; #define PG8_STAGE(bufoff, gbase, voff) do { _Pragma("unroll") for (int _i = 0; _i < 2; ++_i) \
;         __builtin_amdgcn_global_load_lds((const unsigned*)((const char*)(gbase) + (voff)[_i]), (PG8_LAS unsigned*)(lds + (bufoff) + ldsw + _i * 8192), 16, 0, 0); } while (0)
; #define PG8_LDA(dst, b, h) do { _Pragma("unroll") for (int m = 0; m < 4; ++m) _Pragma("unroll") for (int k = 0; k < 2; ++k) dst[m][k] = *(const PG8_LAS bf16x8*)(lds + PG8_SA(b, h) + aoff + m * 2048 + k * 1024); } while (0)
; #define PG8_LDB(dst, b, h) do { _Pragma("unroll") for (int n = 0; n < 2; ++n) _Pragma("unroll") for (int k = 0; k < 2; ++k) dst[n][k] = *(const PG8_LAS bf16x8*)(lds + PG8_SB(b, h) + boff + n * 2048 + k * 1024); } while (0)
; #define PG8_MMA(ai, bj, At, Bt) do { __builtin_amdgcn_s_setprio(1); _Pragma("unroll") for (int m = 0; m < 4; ++m) _Pragma("unroll") for (int n = 0; n < 2; ++n) _Pragma("unroll") for (int k = 0; k < 2; ++k) \
;         acc[ai][bj][m][n] = __builtin_amdgcn_mfma_f32_16x16x32_bf16(Bt[n][k], At[m][k], acc[ai][bj][m][n], 0, 0, 0); __builtin_amdgcn_s_setprio(0); } while (0)
; #define PG8_WAIT_V(n) asm volatile("s_waitcnt vmcnt(" #n ")" ::: "memory")
; #define PG8_WAIT_L(n) asm volatile("s_waitcnt lgkmcnt(" #n ")" ::: "memory")
; #define PG8_BAR __builtin_amdgcn_s_barrier()
; #define PG8_SCHED __builtin_amdgcn_sched_barrier(0)
; template <class Epi, class Sched, bool ALIGN_EPI = false, bool SP2 = false>
; __device__ __forceinline__ void gemm_phase(PG8_LAS unsigned char* lds, const Gemm g, const Sched& S, const Epi& E, int tid_in) {
;     ...
;             PG8_WAIT_V(8); PG8_WAIT_L(0); PG8_BAR; PG8_MMA(1, 0, At, B0); PG8_MMA(1, 1, At, B1); PG8_BAR; PG8_SCHED;
;             PG8_LDB(B0, 1, 0); PG8_LDB(B1, 1, 1); PG8_SCHED; PG8_LDA(At, 1, 0); PG8_STAGE(PG8_SA(0, 1), a2 + hstepA, voffA);
;             PG8_WAIT_V(8); PG8_WAIT_L(0); PG8_BAR; PG8_MMA(0, 0, At, B0); PG8_MMA(0, 1, At, B1); PG8_BAR; PG8_SCHED;
	s_waitcnt lgkmcnt(0)
	v_mfma_f32_16x16x32_bf16 v[62:65], v[140:143], v[178:181], v[62:65]
	v_mfma_f32_16x16x32_bf16 v[58:61], v[154:157], v[178:181], v[58:61]
	v_mfma_f32_16x16x32_bf16 v[46:49], v[140:143], v[186:189], v[46:49]
	v_mfma_f32_16x16x32_bf16 v[42:45], v[154:157], v[186:189], v[42:45]
	v_mfma_f32_16x16x32_bf16 v[30:33], v[140:143], v[204:207], v[30:33]
	v_mfma_f32_16x16x32_bf16 v[26:29], v[154:157], v[204:207], v[26:29]
	v_mfma_f32_16x16x32_bf16 v[14:17], v[140:143], v[212:215], v[14:17]
	v_mfma_f32_16x16x32_bf16 v[10:13], v[154:157], v[212:215], v[10:13]
	v_mfma_f32_16x16x32_bf16 v[62:65], v[144:147], v[182:185], v[62:65]
	v_mfma_f32_16x16x32_bf16 v[58:61], v[158:161], v[182:185], v[58:61]
	v_mfma_f32_16x16x32_bf16 v[46:49], v[144:147], v[190:193], v[46:49]
	v_mfma_f32_16x16x32_bf16 v[42:45], v[158:161], v[190:193], v[42:45]
	v_mfma_f32_16x16x32_bf16 v[30:33], v[144:147], v[208:211], v[30:33]
	v_mfma_f32_16x16x32_bf16 v[26:29], v[158:161], v[208:211], v[26:29]
	v_mfma_f32_16x16x32_bf16 v[14:17], v[144:147], v[216:219], v[14:17]
	v_mfma_f32_16x16x32_bf16 v[10:13], v[158:161], v[216:219], v[10:13]
	v_mfma_f32_16x16x32_bf16 v[54:57], v[162:165], v[178:181], v[54:57]
	v_mfma_f32_16x16x32_bf16 v[50:53], v[170:173], v[178:181], v[50:53]
	v_mfma_f32_16x16x32_bf16 v[38:41], v[162:165], v[186:189], v[38:41]
	v_mfma_f32_16x16x32_bf16 v[34:37], v[170:173], v[186:189], v[34:37]
	v_mfma_f32_16x16x32_bf16 v[22:25], v[162:165], v[204:207], v[22:25]
	v_mfma_f32_16x16x32_bf16 v[18:21], v[170:173], v[204:207], v[18:21]
	v_mfma_f32_16x16x32_bf16 v[6:9], v[162:165], v[212:215], v[6:9]
	v_mfma_f32_16x16x32_bf16 v[2:5], v[170:173], v[212:215], v[2:5]
	v_mfma_f32_16x16x32_bf16 v[54:57], v[166:169], v[182:185], v[54:57]
	v_mfma_f32_16x16x32_bf16 v[50:53], v[174:177], v[182:185], v[50:53]
	v_mfma_f32_16x16x32_bf16 v[38:41], v[166:169], v[190:193], v[38:41]
	v_mfma_f32_16x16x32_bf16 v[34:37], v[174:177], v[190:193], v[34:37]
	v_mfma_f32_16x16x32_bf16 v[22:25], v[166:169], v[208:211], v[22:25]
	v_mfma_f32_16x16x32_bf16 v[18:21], v[174:177], v[208:211], v[18:21]
	v_mfma_f32_16x16x32_bf16 v[6:9], v[166:169], v[216:219], v[6:9]
	v_mfma_f32_16x16x32_bf16 v[2:5], v[174:177], v[216:219], v[2:5]
	s_barrier
	s_add_i32 s15, 0, 0x18000
	s_add_i32 s58, 0, 0x1c000
	v_add_u32_e32 v158, s15, v151
	v_add_u32_e32 v174, s58, v151
	ds_read_b128 v[140:143], v158
	ds_read_b128 v[144:147], v158 offset:1024
	ds_read_b128 v[154:157], v158 offset:2048
	ds_read_b128 v[158:161], v158 offset:3072
	ds_read_b128 v[162:165], v174
	ds_read_b128 v[166:169], v174 offset:1024
	ds_read_b128 v[170:173], v174 offset:2048
	ds_read_b128 v[174:177], v174 offset:3072
	s_add_u32 s54, s54, s22
	s_addc_u32 s55, s55, s23
	s_mov_b32 m0, s64
	v_lshl_add_u64 v[228:229], s[54:55], 0, v[130:131]
	ds_read_b128 v[178:181], v153 offset:32768
	ds_read_b128 v[182:185], v153 offset:33792
	ds_read_b128 v[186:189], v153 offset:34816
	ds_read_b128 v[190:193], v153 offset:35840
	ds_read_b128 v[204:207], v153 offset:36864
	ds_read_b128 v[208:211], v153 offset:37888
	ds_read_b128 v[212:215], v153 offset:38912
	ds_read_b128 v[216:219], v153 offset:39936
	global_load_lds_dwordx4 v[228:229], off
	v_lshl_add_u64 v[228:229], s[54:55], 0, v[132:133]
	s_mov_b32 m0, s65
	s_nop 0
	global_load_lds_dwordx4 v[228:229], off
	s_waitcnt vmcnt(8)
	s_waitcnt lgkmcnt(0)
	s_barrier
	s_waitcnt lgkmcnt(0)
	v_mfma_f32_16x16x32_bf16 v[126:129], v[140:143], v[178:181], v[126:129]
	v_mfma_f32_16x16x32_bf16 v[122:125], v[154:157], v[178:181], v[122:125]
	v_mfma_f32_16x16x32_bf16 v[110:113], v[140:143], v[186:189], v[110:113]
	v_mfma_f32_16x16x32_bf16 v[106:109], v[154:157], v[186:189], v[106:109]
	v_mfma_f32_16x16x32_bf16 v[94:97], v[140:143], v[204:207], v[94:97]
	v_mfma_f32_16x16x32_bf16 v[90:93], v[154:157], v[204:207], v[90:93]
	v_mfma_f32_16x16x32_bf16 v[78:81], v[140:143], v[212:215], v[78:81]
	v_mfma_f32_16x16x32_bf16 v[74:77], v[154:157], v[212:215], v[74:77]
	v_mfma_f32_16x16x32_bf16 v[126:129], v[144:147], v[182:185], v[126:129]
	v_mfma_f32_16x16x32_bf16 v[122:125], v[158:161], v[182:185], v[122:125]
	v_mfma_f32_16x16x32_bf16 v[110:113], v[144:147], v[190:193], v[110:113]
	v_mfma_f32_16x16x32_bf16 v[106:109], v[158:161], v[190:193], v[106:109]
	v_mfma_f32_16x16x32_bf16 v[94:97], v[144:147], v[208:211], v[94:97]
	v_mfma_f32_16x16x32_bf16 v[90:93], v[158:161], v[208:211], v[90:93]
	v_mfma_f32_16x16x32_bf16 v[78:81], v[144:147], v[216:219], v[78:81]
	v_mfma_f32_16x16x32_bf16 v[74:77], v[158:161], v[216:219], v[74:77]
	v_mfma_f32_16x16x32_bf16 v[118:121], v[162:165], v[178:181], v[118:121]
	v_mfma_f32_16x16x32_bf16 v[114:117], v[170:173], v[178:181], v[114:117]
	v_mfma_f32_16x16x32_bf16 v[102:105], v[162:165], v[186:189], v[102:105]
	v_mfma_f32_16x16x32_bf16 v[98:101], v[170:173], v[186:189], v[98:101]
	v_mfma_f32_16x16x32_bf16 v[86:89], v[162:165], v[204:207], v[86:89]
	v_mfma_f32_16x16x32_bf16 v[82:85], v[170:173], v[204:207], v[82:85]
	v_mfma_f32_16x16x32_bf16 v[70:73], v[162:165], v[212:215], v[70:73]
	v_mfma_f32_16x16x32_bf16 v[66:69], v[170:173], v[212:215], v[66:69]
	v_mfma_f32_16x16x32_bf16 v[118:121], v[166:169], v[182:185], v[118:121]
	v_mfma_f32_16x16x32_bf16 v[114:117], v[174:177], v[182:185], v[114:117]
	v_mfma_f32_16x16x32_bf16 v[102:105], v[166:169], v[190:193], v[102:105]
	v_mfma_f32_16x16x32_bf16 v[98:101], v[174:177], v[190:193], v[98:101]
	v_mfma_f32_16x16x32_bf16 v[86:89], v[166:169], v[208:211], v[86:89]
	v_mfma_f32_16x16x32_bf16 v[82:85], v[174:177], v[208:211], v[82:85]
	v_mfma_f32_16x16x32_bf16 v[70:73], v[166:169], v[216:219], v[70:73]
	v_mfma_f32_16x16x32_bf16 v[66:69], v[174:177], v[216:219], v[66:69]
	s_barrier
; #define PG8_STAGE(bufoff, gbase, voff) do { _Pragma("unroll") for (int _i = 0; _i < 2; ++_i) \
;         __builtin_amdgcn_global_load_lds((const unsigned*)((const char*)(gbase) + (voff)[_i]), (PG8_LAS unsigned*)(lds + (bufoff) + ldsw + _i * 8192), 16, 0, 0); } while (0)
; #define PG8_LDA(dst, b, h) do { _Pragma("unroll") for (int m = 0; m < 4; ++m) _Pragma("unroll") for (int k = 0; k < 2; ++k) dst[m][k] = *(const PG8_LAS bf16x8*)(lds + PG8_SA(b, h) + aoff + m * 2048 + k * 1024); } while (0)
; #define PG8_MMA(ai, bj, At, Bt) do { __builtin_amdgcn_s_setprio(1); _Pragma("unroll") for (int m = 0; m < 4; ++m) _Pragma("unroll") for (int n = 0; n < 2; ++n) _Pragma("unroll") for (int k = 0; k < 2; ++k) \
;         acc[ai][bj][m][n] = __builtin_amdgcn_mfma_f32_16x16x32_bf16(Bt[n][k], At[m][k], acc[ai][bj][m][n], 0, 0, 0); __builtin_amdgcn_s_setprio(0); } while (0)
; #define PG8_WAIT_V(n) asm volatile("s_waitcnt vmcnt(" #n ")" ::: "memory")
; #define PG8_WAIT_L(n) asm volatile("s_waitcnt lgkmcnt(" #n ")" ::: "memory")
; #define PG8_BAR __builtin_amdgcn_s_barrier()
; #define PG8_SCHED __builtin_amdgcn_sched_barrier(0)
; template <class Epi, class Sched, bool ALIGN_EPI = false, bool SP2 = false>
; __device__ __forceinline__ void gemm_phase(PG8_LAS unsigned char* lds, const Gemm g, const Sched& S, const Epi& E, int tid_in) {
;     ...
;         for (int t = 0; t < nt; t += 2) {
;             const bool last = (t == nt - 2);
;             const char* a1 = cA + (size_t)(t + 1) * kstep;
;             const char* a2 = last ? nA : cA + (size_t)(t + 2) * kstep; const char* b2 = last ? nB : cB + (size_t)(t + 2) * kstep;
;             const char* a3 = a2 + kstep; const char* b3 = b2 + kstep;
;     ...
;             PG8_LDA(At, 1, 1); PG8_STAGE(PG8_SB(1, 0), b3, voffB); PG8_STAGE(PG8_SB(1, 1), b3 + hstep, voffB); PG8_STAGE(PG8_SA(1, 0), a3, voffA);
;             PG8_WAIT_V(8); PG8_WAIT_L(0); PG8_BAR; PG8_MMA(1, 0, At, B0); PG8_MMA(1, 1, At, B1); PG8_BAR; PG8_SCHED;
	s_add_i32 s15, s15, s2
	v_lshl_add_u64 v[148:149], v[148:149], 0, s[28:29]
	s_mov_b32 m0, s15
	ds_read_b128 v[178:181], v153 offset:49152
	ds_read_b128 v[182:185], v153 offset:50176
	ds_read_b128 v[186:189], v153 offset:51200
	ds_read_b128 v[190:193], v153 offset:52224
	ds_read_b128 v[204:207], v153 offset:53248
	ds_read_b128 v[208:211], v153 offset:54272
	ds_read_b128 v[212:215], v153 offset:55296
	ds_read_b128 v[216:219], v153 offset:56320
	global_load_lds_dwordx4 v[148:149], off
	v_lshl_add_u64 v[148:149], v[194:195], 0, s[28:29]
	s_add_i32 m0, s15, 0x2000
	s_add_i32 s15, s58, s2
	global_load_lds_dwordx4 v[148:149], off
	v_lshl_add_u64 v[148:149], v[220:221], 0, s[28:29]
	s_mov_b32 m0, s15
	s_nop 0
	global_load_lds_dwordx4 v[148:149], off
	v_lshl_add_u64 v[148:149], v[222:223], 0, s[28:29]
	s_add_i32 m0, s15, 0x2000
	s_nop 0
	global_load_lds_dwordx4 v[148:149], off
	v_lshl_add_u64 v[148:149], v[224:225], 0, s[28:29]
	s_mov_b32 m0, s66
	s_nop 0
	global_load_lds_dwordx4 v[148:149], off
	v_lshl_add_u64 v[148:149], v[226:227], 0, s[28:29]
	s_mov_b32 m0, s67
	s_nop 0
	global_load_lds_dwordx4 v[148:149], off
	s_waitcnt vmcnt(8)
	s_waitcnt lgkmcnt(0)
	s_barrier
	s_waitcnt lgkmcnt(0)
	v_mfma_f32_16x16x32_bf16 v[62:65], v[140:143], v[178:181], v[62:65]
	v_mfma_f32_16x16x32_bf16 v[58:61], v[154:157], v[178:181], v[58:61]
	v_mfma_f32_16x16x32_bf16 v[46:49], v[140:143], v[186:189], v[46:49]
	v_mfma_f32_16x16x32_bf16 v[42:45], v[154:157], v[186:189], v[42:45]
	v_mfma_f32_16x16x32_bf16 v[30:33], v[140:143], v[204:207], v[30:33]
	v_mfma_f32_16x16x32_bf16 v[26:29], v[154:157], v[204:207], v[26:29]
	v_mfma_f32_16x16x32_bf16 v[14:17], v[140:143], v[212:215], v[14:17]
	v_mfma_f32_16x16x32_bf16 v[10:13], v[154:157], v[212:215], v[10:13]
	v_mfma_f32_16x16x32_bf16 v[62:65], v[144:147], v[182:185], v[62:65]
	v_mfma_f32_16x16x32_bf16 v[58:61], v[158:161], v[182:185], v[58:61]
	v_mfma_f32_16x16x32_bf16 v[46:49], v[144:147], v[190:193], v[46:49]
	v_mfma_f32_16x16x32_bf16 v[42:45], v[158:161], v[190:193], v[42:45]
	v_mfma_f32_16x16x32_bf16 v[30:33], v[144:147], v[208:211], v[30:33]
	v_mfma_f32_16x16x32_bf16 v[26:29], v[158:161], v[208:211], v[26:29]
	v_mfma_f32_16x16x32_bf16 v[14:17], v[144:147], v[216:219], v[14:17]
	v_mfma_f32_16x16x32_bf16 v[10:13], v[158:161], v[216:219], v[10:13]
	v_mfma_f32_16x16x32_bf16 v[54:57], v[162:165], v[178:181], v[54:57]
	v_mfma_f32_16x16x32_bf16 v[50:53], v[170:173], v[178:181], v[50:53]
	v_mfma_f32_16x16x32_bf16 v[38:41], v[162:165], v[186:189], v[38:41]
	v_mfma_f32_16x16x32_bf16 v[34:37], v[170:173], v[186:189], v[34:37]
	v_mfma_f32_16x16x32_bf16 v[22:25], v[162:165], v[204:207], v[22:25]
	v_mfma_f32_16x16x32_bf16 v[18:21], v[170:173], v[204:207], v[18:21]
	v_mfma_f32_16x16x32_bf16 v[6:9], v[162:165], v[212:215], v[6:9]
	v_mfma_f32_16x16x32_bf16 v[2:5], v[170:173], v[212:215], v[2:5]
	v_mfma_f32_16x16x32_bf16 v[54:57], v[166:169], v[182:185], v[54:57]
	v_mfma_f32_16x16x32_bf16 v[50:53], v[174:177], v[182:185], v[50:53]
	v_mfma_f32_16x16x32_bf16 v[38:41], v[166:169], v[190:193], v[38:41]
	v_mfma_f32_16x16x32_bf16 v[34:37], v[174:177], v[190:193], v[34:37]
	v_mfma_f32_16x16x32_bf16 v[22:25], v[166:169], v[208:211], v[22:25]
	v_mfma_f32_16x16x32_bf16 v[18:21], v[174:177], v[208:211], v[18:21]
	v_mfma_f32_16x16x32_bf16 v[6:9], v[166:169], v[216:219], v[6:9]
	v_mfma_f32_16x16x32_bf16 v[2:5], v[174:177], v[216:219], v[2:5]
	s_barrier
	s_add_u32 s52, s52, 0x100
	s_addc_u32 s53, s53, 0
	s_add_u32 s12, s12, 0x100
	s_addc_u32 s13, s13, 0
	s_cmp_ge_i32 s57, s69
	s_mov_b32 s15, s57
	s_cbranch_scc0 .LBB0_542
	s_setprio 0
	s_movk_i32 s81, 0x4040

; template <class Epi, class Sched, bool ALIGN_EPI = false, bool SP2 = false>
; __device__ __forceinline__ void gemm_phase(PG8_LAS unsigned char* lds, const Gemm g, const Sched& S, const Epi& E, int tid_in) {
;     ...
;         const bool has_next = S.next(ui + 1, nxt);
;         const char* nA = has_next ? (const char*)g.A + (size_t)nxt.pm * tstepA + a_unit_off(g, nxt.pn) : cA; const char* nB = has_next ? (const char*)g.Bt + (size_t)nxt.pn * tstepB : cB;
; #pragma unroll 1
;         for (int t = 0; t < nt; t += 2) {
;             const bool last = (t == nt - 2);
;             const char* a1 = cA + (size_t)(t + 1) * kstep;
;             const char* a2 = last ? nA : cA + (size_t)(t + 2) * kstep; const char* b2 = last ? nB : cB + (size_t)(t + 2) * kstep;
;             const char* a3 = a2 + kstep; const char* b3 = b2 + kstep;
;     ...
; #pragma unroll
;         for (int a = 0; a < 2; ++a)
; #pragma unroll
;             for (int b = 0; b < 2; ++b)
; #pragma unroll
;                 for (int m = 0; m < 4; ++m)
; #pragma unroll
;                     for (int n = 0; n < 2; ++n) acc[a][b][m][n] = (f32x4){0.f, 0.f, 0.f, 0.f};
;         cur = nxt; cA = nA; cB = nB; ++ui;
.LBB0_710:
	v_mov_b32_e32 v125, 0
	s_andn2_b64 vcc, exec, s[20:21]
	v_mov_b32_e32 v124, v125
	v_mov_b32_e32 v123, v125
	v_mov_b32_e32 v122, v125
	v_mov_b32_e32 v129, v125
	v_mov_b32_e32 v128, v125
	v_mov_b32_e32 v127, v125
	v_mov_b32_e32 v126, v125
	v_mov_b32_e32 v113, v125
	v_mov_b32_e32 v112, v125
	v_mov_b32_e32 v111, v125
	v_mov_b32_e32 v110, v125
	v_mov_b32_e32 v109, v125
	v_mov_b32_e32 v108, v125
	v_mov_b32_e32 v107, v125
	v_mov_b32_e32 v106, v125
	v_mov_b32_e32 v97, v125
	v_mov_b32_e32 v96, v125
	v_mov_b32_e32 v95, v125
	v_mov_b32_e32 v94, v125
	v_mov_b32_e32 v93, v125
	v_mov_b32_e32 v92, v125
	v_mov_b32_e32 v91, v125
	v_mov_b32_e32 v90, v125
	v_mov_b32_e32 v81, v125
	v_mov_b32_e32 v80, v125
	v_mov_b32_e32 v79, v125
	v_mov_b32_e32 v78, v125
	v_mov_b32_e32 v77, v125
	v_mov_b32_e32 v76, v125
	v_mov_b32_e32 v75, v125
	v_mov_b32_e32 v74, v125
	v_mov_b32_e32 v121, v125
	v_mov_b32_e32 v120, v125
	v_mov_b32_e32 v119, v125
	v_mov_b32_e32 v118, v125
	v_mov_b32_e32 v117, v125
	v_mov_b32_e32 v116, v125
	v_mov_b32_e32 v115, v125
	v_mov_b32_e32 v114, v125
	v_mov_b32_e32 v105, v125
	v_mov_b32_e32 v104, v125
	v_mov_b32_e32 v103, v125
	v_mov_b32_e32 v102, v125
	v_mov_b32_e32 v101, v125
	v_mov_b32_e32 v100, v125
	v_mov_b32_e32 v99, v125
	v_mov_b32_e32 v98, v125
	v_mov_b32_e32 v89, v125
	v_mov_b32_e32 v88, v125
	v_mov_b32_e32 v87, v125
	v_mov_b32_e32 v86, v125
	v_mov_b32_e32 v85, v125
	v_mov_b32_e32 v84, v125
	v_mov_b32_e32 v83, v125
	v_mov_b32_e32 v82, v125
	v_mov_b32_e32 v73, v125
	v_mov_b32_e32 v72, v125
	v_mov_b32_e32 v71, v125
	v_mov_b32_e32 v70, v125
	v_mov_b32_e32 v69, v125
	v_mov_b32_e32 v68, v125
	v_mov_b32_e32 v67, v125
	v_mov_b32_e32 v66, v125
	v_mov_b32_e32 v65, v125
	v_mov_b32_e32 v64, v125
	v_mov_b32_e32 v63, v125
	v_mov_b32_e32 v62, v125
	v_mov_b32_e32 v61, v125
	v_mov_b32_e32 v60, v125
	v_mov_b32_e32 v59, v125
	v_mov_b32_e32 v58, v125
	v_mov_b32_e32 v49, v125
	v_mov_b32_e32 v48, v125
	v_mov_b32_e32 v47, v125
	v_mov_b32_e32 v46, v125
	v_mov_b32_e32 v45, v125
	v_mov_b32_e32 v44, v125
	v_mov_b32_e32 v43, v125
	v_mov_b32_e32 v42, v125
	v_mov_b32_e32 v33, v125
	v_mov_b32_e32 v32, v125
	v_mov_b32_e32 v31, v125
	v_mov_b32_e32 v30, v125
	v_mov_b32_e32 v29, v125
	v_mov_b32_e32 v28, v125
	v_mov_b32_e32 v27, v125
	v_mov_b32_e32 v26, v125
	v_mov_b32_e32 v17, v125
	v_mov_b32_e32 v16, v125
	v_mov_b32_e32 v15, v125
	v_mov_b32_e32 v14, v125
	v_mov_b32_e32 v13, v125
	v_mov_b32_e32 v12, v125
	v_mov_b32_e32 v11, v125
	v_mov_b32_e32 v10, v125
	v_mov_b32_e32 v57, v125
	v_mov_b32_e32 v56, v125
	v_mov_b32_e32 v55, v125
	v_mov_b32_e32 v54, v125
	v_mov_b32_e32 v53, v125
	v_mov_b32_e32 v52, v125
	v_mov_b32_e32 v51, v125
	v_mov_b32_e32 v50, v125
	v_mov_b32_e32 v41, v125
	v_mov_b32_e32 v40, v125
	v_mov_b32_e32 v39, v125
	v_mov_b32_e32 v38, v125
	v_mov_b32_e32 v37, v125
	v_mov_b32_e32 v36, v125
	v_mov_b32_e32 v35, v125
	v_mov_b32_e32 v34, v125
	v_mov_b32_e32 v25, v125
	v_mov_b32_e32 v24, v125
	v_mov_b32_e32 v23, v125
	v_mov_b32_e32 v22, v125
	v_mov_b32_e32 v21, v125
	v_mov_b32_e32 v20, v125
	v_mov_b32_e32 v19, v125
	v_mov_b32_e32 v18, v125
	v_mov_b32_e32 v9, v125
	v_mov_b32_e32 v8, v125
	v_mov_b32_e32 v7, v125
	v_mov_b32_e32 v6, v125
	v_mov_b32_e32 v5, v125
	v_mov_b32_e32 v4, v125
	v_mov_b32_e32 v3, v125
	v_mov_b32_e32 v2, v125
	s_cbranch_vccnz .LBB0_714
	s_add_u32 s38, s46, 0x80
	s_addc_u32 s39, s47, 0
	s_add_u32 s12, s40, 0x100
	v_mov_b32_e32 v2, 0
	s_addc_u32 s13, s41, 0
	s_mov_b32 s15, 0
	v_mov_b32_e32 v3, v2
	v_mov_b32_e32 v4, v2
	v_mov_b32_e32 v5, v2
	v_mov_b32_e32 v6, v2
	v_mov_b32_e32 v7, v2
	v_mov_b32_e32 v8, v2
	v_mov_b32_e32 v9, v2
	v_mov_b32_e32 v18, v2
	v_mov_b32_e32 v19, v2
	v_mov_b32_e32 v20, v2
	v_mov_b32_e32 v21, v2
	v_mov_b32_e32 v22, v2
	v_mov_b32_e32 v23, v2
	v_mov_b32_e32 v24, v2
	v_mov_b32_e32 v25, v2
	v_mov_b32_e32 v34, v2
	v_mov_b32_e32 v35, v2
	v_mov_b32_e32 v36, v2
	v_mov_b32_e32 v37, v2
	v_mov_b32_e32 v38, v2
	v_mov_b32_e32 v39, v2
	v_mov_b32_e32 v40, v2
	v_mov_b32_e32 v41, v2
	v_mov_b32_e32 v50, v2
	v_mov_b32_e32 v51, v2
	v_mov_b32_e32 v52, v2
	v_mov_b32_e32 v53, v2
	v_mov_b32_e32 v54, v2
	v_mov_b32_e32 v55, v2
	v_mov_b32_e32 v56, v2
	v_mov_b32_e32 v57, v2
	v_mov_b32_e32 v10, v2
	v_mov_b32_e32 v11, v2
	v_mov_b32_e32 v12, v2
	v_mov_b32_e32 v13, v2
	v_mov_b32_e32 v14, v2
	v_mov_b32_e32 v15, v2
	v_mov_b32_e32 v16, v2
	v_mov_b32_e32 v17, v2
	v_mov_b32_e32 v26, v2
	v_mov_b32_e32 v27, v2
	v_mov_b32_e32 v28, v2
	v_mov_b32_e32 v29, v2
	v_mov_b32_e32 v30, v2
	v_mov_b32_e32 v31, v2
	v_mov_b32_e32 v32, v2
	v_mov_b32_e32 v33, v2
	v_mov_b32_e32 v42, v2
	v_mov_b32_e32 v43, v2
	v_mov_b32_e32 v44, v2
	v_mov_b32_e32 v45, v2
	v_mov_b32_e32 v46, v2
	v_mov_b32_e32 v47, v2
	v_mov_b32_e32 v48, v2
	v_mov_b32_e32 v49, v2
	v_mov_b32_e32 v58, v2
	v_mov_b32_e32 v59, v2
	v_mov_b32_e32 v60, v2
	v_mov_b32_e32 v61, v2
	v_mov_b32_e32 v62, v2
	v_mov_b32_e32 v63, v2
	v_mov_b32_e32 v64, v2
	v_mov_b32_e32 v65, v2
	v_mov_b32_e32 v66, v2
	v_mov_b32_e32 v67, v2
	v_mov_b32_e32 v68, v2
	v_mov_b32_e32 v69, v2
	v_mov_b32_e32 v70, v2
	v_mov_b32_e32 v71, v2
	v_mov_b32_e32 v72, v2
	v_mov_b32_e32 v73, v2
	v_mov_b32_e32 v82, v2
	v_mov_b32_e32 v83, v2
	v_mov_b32_e32 v84, v2
	v_mov_b32_e32 v85, v2
	v_mov_b32_e32 v86, v2
	v_mov_b32_e32 v87, v2
	v_mov_b32_e32 v88, v2
	v_mov_b32_e32 v89, v2
	v_mov_b32_e32 v98, v2
	v_mov_b32_e32 v99, v2
	v_mov_b32_e32 v100, v2
	v_mov_b32_e32 v101, v2
	v_mov_b32_e32 v102, v2
	v_mov_b32_e32 v103, v2
	v_mov_b32_e32 v104, v2
	v_mov_b32_e32 v105, v2
	v_mov_b32_e32 v114, v2
	v_mov_b32_e32 v115, v2
	v_mov_b32_e32 v116, v2
	v_mov_b32_e32 v117, v2
	v_mov_b32_e32 v118, v2
	v_mov_b32_e32 v119, v2
	v_mov_b32_e32 v120, v2
	v_mov_b32_e32 v121, v2
	v_mov_b32_e32 v74, v2
	v_mov_b32_e32 v75, v2
	v_mov_b32_e32 v76, v2
	v_mov_b32_e32 v77, v2
	v_mov_b32_e32 v78, v2
	v_mov_b32_e32 v79, v2
	v_mov_b32_e32 v80, v2
	v_mov_b32_e32 v81, v2
	v_mov_b32_e32 v90, v2
	v_mov_b32_e32 v91, v2
	v_mov_b32_e32 v92, v2
	v_mov_b32_e32 v93, v2
	v_mov_b32_e32 v94, v2
	v_mov_b32_e32 v95, v2
	v_mov_b32_e32 v96, v2
	v_mov_b32_e32 v97, v2
	v_mov_b32_e32 v106, v2
	v_mov_b32_e32 v107, v2
	v_mov_b32_e32 v108, v2
	v_mov_b32_e32 v109, v2
	v_mov_b32_e32 v110, v2
	v_mov_b32_e32 v111, v2
	v_mov_b32_e32 v112, v2
	v_mov_b32_e32 v113, v2
	v_mov_b32_e32 v126, v2
	v_mov_b32_e32 v127, v2
	v_mov_b32_e32 v128, v2
	v_mov_b32_e32 v129, v2
	v_mov_b32_e32 v122, v2
	v_mov_b32_e32 v123, v2
	v_mov_b32_e32 v124, v2
	v_mov_b32_e32 v125, v2
	s_cmp_ge_u32 s84, 0x100
	s_cbranch_scc0 .Lprio_skip712
	s_setprio 1
; #define PG8_STAGE(bufoff, gbase, voff) do { _Pragma("unroll") for (int _i = 0; _i < 2; ++_i) \
;         __builtin_amdgcn_global_load_lds((const unsigned*)((const char*)(gbase) + (voff)[_i]), (PG8_LAS unsigned*)(lds + (bufoff) + ldsw + _i * 8192), 16, 0, 0); } while (0)
; #define PG8_LDA(dst, b, h) do { _Pragma("unroll") for (int m = 0; m < 4; ++m) _Pragma("unroll") for (int k = 0; k < 2; ++k) dst[m][k] = *(const PG8_LAS bf16x8*)(lds + PG8_SA(b, h) + aoff + m * 2048 + k * 1024); } while (0)
; #define PG8_LDB(dst, b, h) do { _Pragma("unroll") for (int n = 0; n < 2; ++n) _Pragma("unroll") for (int k = 0; k < 2; ++k) dst[n][k] = *(const PG8_LAS bf16x8*)(lds + PG8_SB(b, h) + boff + n * 2048 + k * 1024); } while (0)
; #define PG8_MMA(ai, bj, At, Bt) do { __builtin_amdgcn_s_setprio(1); _Pragma("unroll") for (int m = 0; m < 4; ++m) _Pragma("unroll") for (int n = 0; n < 2; ++n) _Pragma("unroll") for (int k = 0; k < 2; ++k) \
;         acc[ai][bj][m][n] = __builtin_amdgcn_mfma_f32_16x16x32_bf16(Bt[n][k], At[m][k], acc[ai][bj][m][n], 0, 0, 0); __builtin_amdgcn_s_setprio(0); } while (0)
; #define PG8_WAIT_V(n) asm volatile("s_waitcnt vmcnt(" #n ")" ::: "memory")
; #define PG8_BAR __builtin_amdgcn_s_barrier()
; template <class Epi, class Sched, bool ALIGN_EPI = false, bool SP2 = false>
; __device__ __forceinline__ void gemm_phase(PG8_LAS unsigned char* lds, const Gemm g, const Sched& S, const Epi& E, int tid_in) {
;     ...
;         for (int t = 0; t < nt; t += 2) {
;             const bool last = (t == nt - 2);
;             const char* a1 = cA + (size_t)(t + 1) * kstep;
;             const char* a2 = last ? nA : cA + (size_t)(t + 2) * kstep; const char* b2 = last ? nB : cB + (size_t)(t + 2) * kstep;
;             const char* a3 = a2 + kstep; const char* b3 = b2 + kstep;
;             if (last && has_next) S.a_ready(nxt);
;             if constexpr (SP2) {
;             PG8_LDB(B0, 0, 0); PG8_LDB(B1, 0, 1); PG8_SCHED; PG8_LDA(At, 0, 0); PG8_STAGE(PG8_SA(1, 1), a1 + hstepA, voffA);
;             PG8_WAIT_V(8); PG8_WAIT_L(0); PG8_BAR; PG8_MMA(0, 0, At, B0); PG8_MMA(0, 1, At, B1); PG8_BAR; PG8_SCHED;
;             PG8_LDA(At, 0, 1); PG8_STAGE(PG8_SB(0, 0), b2, voffB); PG8_STAGE(PG8_SB(0, 1), b2 + hstep, voffB); PG8_STAGE(PG8_SA(0, 0), a2, voffA);
;             PG8_WAIT_V(8); PG8_WAIT_L(0); PG8_BAR; PG8_MMA(1, 0, At, B0); PG8_MMA(1, 1, At, B1); PG8_BAR; PG8_SCHED;
.Lprio_skip712:
.LBB0_712:
	s_add_i32 s46, s15, 2
	s_add_u32 s40, s38, 0x80
	s_addc_u32 s41, s39, 0
	s_add_i32 s47, 0, 0x10000
	s_cmp_eq_u32 s59, s15
	s_cselect_b32 s41, s43, s41
	s_cselect_b32 s40, s42, s40
	v_add_u32_e32 v0, s47, v153
	s_cselect_b32 s65, s45, s13
	s_cselect_b32 s64, s44, s12
	s_add_i32 s15, 0, 0x14000
	ds_read_b128 v[142:145], v0
	ds_read_b128 v[146:149], v0 offset:1024
	ds_read_b128 v[160:163], v0 offset:2048
	ds_read_b128 v[164:167], v0 offset:3072
	v_add_u32_e32 v0, s15, v153
	ds_read_b128 v[168:171], v0
	ds_read_b128 v[172:175], v0 offset:1024
	ds_read_b128 v[176:179], v0 offset:2048
	ds_read_b128 v[180:183], v0 offset:3072
	v_lshl_add_u64 v[150:151], s[38:39], 0, v[138:139]
	s_add_i32 m0, s52, 0xc000
	ds_read_b128 v[184:187], v158
	ds_read_b128 v[188:191], v158 offset:1024
	ds_read_b128 v[192:195], v158 offset:2048
	ds_read_b128 v[204:207], v158 offset:3072
	ds_read_b128 v[208:211], v158 offset:4096
	ds_read_b128 v[212:215], v158 offset:5120
	ds_read_b128 v[216:219], v158 offset:6144
	ds_read_b128 v[220:223], v158 offset:7168
	global_load_lds_dwordx4 v[150:151], off
	v_lshl_add_u64 v[150:151], s[38:39], 0, v[140:141]
	s_add_i32 m0, s52, 0xe000
	s_nop 0
	global_load_lds_dwordx4 v[150:151], off
	s_waitcnt vmcnt(8)
	s_waitcnt lgkmcnt(0)
	s_barrier
	s_waitcnt lgkmcnt(0)
	v_mfma_f32_16x16x32_bf16 v[122:125], v[142:145], v[184:187], v[122:125]
	v_mfma_f32_16x16x32_bf16 v[126:129], v[160:163], v[184:187], v[126:129]
	v_mfma_f32_16x16x32_bf16 v[110:113], v[142:145], v[192:195], v[110:113]
	v_mfma_f32_16x16x32_bf16 v[106:109], v[160:163], v[192:195], v[106:109]
	v_mfma_f32_16x16x32_bf16 v[94:97], v[142:145], v[208:211], v[94:97]
	v_mfma_f32_16x16x32_bf16 v[90:93], v[160:163], v[208:211], v[90:93]
	v_mfma_f32_16x16x32_bf16 v[78:81], v[142:145], v[216:219], v[78:81]
	v_mfma_f32_16x16x32_bf16 v[74:77], v[160:163], v[216:219], v[74:77]
	v_mfma_f32_16x16x32_bf16 v[122:125], v[146:149], v[188:191], v[122:125]
	v_mfma_f32_16x16x32_bf16 v[126:129], v[164:167], v[188:191], v[126:129]
	v_mfma_f32_16x16x32_bf16 v[110:113], v[146:149], v[204:207], v[110:113]
	v_mfma_f32_16x16x32_bf16 v[106:109], v[164:167], v[204:207], v[106:109]
	v_mfma_f32_16x16x32_bf16 v[94:97], v[146:149], v[212:215], v[94:97]
	v_mfma_f32_16x16x32_bf16 v[90:93], v[164:167], v[212:215], v[90:93]
	v_mfma_f32_16x16x32_bf16 v[78:81], v[146:149], v[220:223], v[78:81]
	v_mfma_f32_16x16x32_bf16 v[74:77], v[164:167], v[220:223], v[74:77]
	v_mfma_f32_16x16x32_bf16 v[118:121], v[168:171], v[184:187], v[118:121]
	v_mfma_f32_16x16x32_bf16 v[114:117], v[176:179], v[184:187], v[114:117]
	v_mfma_f32_16x16x32_bf16 v[102:105], v[168:171], v[192:195], v[102:105]
	v_mfma_f32_16x16x32_bf16 v[98:101], v[176:179], v[192:195], v[98:101]
	v_mfma_f32_16x16x32_bf16 v[86:89], v[168:171], v[208:211], v[86:89]
	v_mfma_f32_16x16x32_bf16 v[82:85], v[176:179], v[208:211], v[82:85]
	v_mfma_f32_16x16x32_bf16 v[70:73], v[168:171], v[216:219], v[70:73]
	v_mfma_f32_16x16x32_bf16 v[66:69], v[176:179], v[216:219], v[66:69]
	v_mfma_f32_16x16x32_bf16 v[118:121], v[172:175], v[188:191], v[118:121]
	v_mfma_f32_16x16x32_bf16 v[114:117], v[180:183], v[188:191], v[114:117]
	v_mfma_f32_16x16x32_bf16 v[102:105], v[172:175], v[204:207], v[102:105]
	v_mfma_f32_16x16x32_bf16 v[98:101], v[180:183], v[204:207], v[98:101]
	v_mfma_f32_16x16x32_bf16 v[86:89], v[172:175], v[212:215], v[86:89]
	v_mfma_f32_16x16x32_bf16 v[82:85], v[180:183], v[212:215], v[82:85]
	v_mfma_f32_16x16x32_bf16 v[70:73], v[172:175], v[220:223], v[70:73]
	v_mfma_f32_16x16x32_bf16 v[66:69], v[180:183], v[220:223], v[66:69]
	s_barrier
	s_add_i32 s47, s47, s51
	v_lshl_add_u64 v[150:151], s[64:65], 0, v[132:133]
	s_mov_b32 m0, s47
	ds_read_b128 v[184:187], v158 offset:16384
	ds_read_b128 v[188:191], v158 offset:17408
	ds_read_b128 v[192:195], v158 offset:18432
	ds_read_b128 v[204:207], v158 offset:19456
	ds_read_b128 v[208:211], v158 offset:20480
	ds_read_b128 v[212:215], v158 offset:21504
	ds_read_b128 v[216:219], v158 offset:22528
	ds_read_b128 v[220:223], v158 offset:23552
	global_load_lds_dwordx4 v[150:151], off
	s_add_i32 m0, s47, 0x2000
	v_lshl_add_u64 v[224:225], s[64:65], 0, v[136:137]
	s_add_u32 s64, s64, s8
	s_addc_u32 s65, s65, s9
	s_add_i32 s15, s15, s51
	global_load_lds_dwordx4 v[224:225], off
	v_lshl_add_u64 v[226:227], s[64:65], 0, v[132:133]
	s_mov_b32 m0, s15
	v_lshl_add_u64 v[228:229], s[64:65], 0, v[136:137]
	global_load_lds_dwordx4 v[226:227], off
	s_add_i32 m0, s15, 0x2000
	v_lshl_add_u64 v[230:231], s[40:41], 0, v[130:131]
	global_load_lds_dwordx4 v[228:229], off
	s_mov_b32 m0, s52
	v_lshl_add_u64 v[232:233], s[40:41], 0, v[134:135]
	global_load_lds_dwordx4 v[230:231], off
	s_mov_b32 m0, s53
	s_nop 0
	global_load_lds_dwordx4 v[232:233], off
	s_waitcnt vmcnt(8)
	s_waitcnt lgkmcnt(0)
	s_barrier
; #define PG8_STAGE(bufoff, gbase, voff) do { _Pragma("unroll") for (int _i = 0; _i < 2; ++_i) \
;         __builtin_amdgcn_global_load_lds((const unsigned*)((const char*)(gbase) + (voff)[_i]), (PG8_LAS unsigned*)(lds + (bufoff) + ldsw + _i * 8192), 16, 0, 0); } while (0)
; #define PG8_LDA(dst, b, h) do { _Pragma("unroll") for (int m = 0; m < 4; ++m) _Pragma("unroll") for (int k = 0; k < 2; ++k) dst[m][k] = *(const PG8_LAS bf16x8*)(lds + PG8_SA(b, h) + aoff + m * 2048 + k * 1024); } while (0)
; #define PG8_LDB(dst, b, h) do { _Pragma("unroll") for (int n = 0; n < 2; ++n) _Pragma("unroll") for (int k = 0; k < 2; ++k) dst[n][k] = *(const PG8_LAS bf16x8*)(lds + PG8_SB(b, h) + boff + n * 2048 + k * 1024); } while (0)
; #define PG8_MMA(ai, bj, At, Bt) do { __builtin_amdgcn_s_setprio(1); _Pragma("unroll") for (int m = 0; m < 4; ++m) _Pragma("unroll") for (int n = 0; n < 2; ++n) _Pragma("unroll") for (int k = 0; k < 2; ++k) \
;         acc[ai][bj][m][n] = __builtin_amdgcn_mfma_f32_16x16x32_bf16(Bt[n][k], At[m][k], acc[ai][bj][m][n], 0, 0, 0); __builtin_amdgcn_s_setprio(0); } while (0)
; #define PG8_WAIT_V(n) asm volatile("s_waitcnt vmcnt(" #n ")" ::: "memory")
; #define PG8_WAIT_L(n) asm volatile("s_waitcnt lgkmcnt(" #n ")" ::: "memory")
; #define PG8_BAR __builtin_amdgcn_s_barrier()
; #define PG8_SCHED __builtin_amdgcn_sched_barrier(0)
; template <class Epi, class Sched, bool ALIGN_EPI = false, bool SP2 = false>
; __device__ __forceinline__ void gemm_phase(PG8_LAS unsigned char* lds, const Gemm g, const Sched& S, const Epi& E, int tid_in) {
;     ...
;             PG8_WAIT_V(8); PG8_WAIT_L(0); PG8_BAR; PG8_MMA(1, 0, At, B0); PG8_MMA(1, 1, At, B1); PG8_BAR; PG8_SCHED;
;             PG8_LDB(B0, 1, 0); PG8_LDB(B1, 1, 1); PG8_SCHED; PG8_LDA(At, 1, 0); PG8_STAGE(PG8_SA(0, 1), a2 + hstepA, voffA);
;             PG8_WAIT_V(8); PG8_WAIT_L(0); PG8_BAR; PG8_MMA(0, 0, At, B0); PG8_MMA(0, 1, At, B1); PG8_BAR; PG8_SCHED;
	s_waitcnt lgkmcnt(0)
	v_mfma_f32_16x16x32_bf16 v[62:65], v[142:145], v[184:187], v[62:65]
	v_mfma_f32_16x16x32_bf16 v[58:61], v[160:163], v[184:187], v[58:61]
	v_mfma_f32_16x16x32_bf16 v[46:49], v[142:145], v[192:195], v[46:49]
	v_mfma_f32_16x16x32_bf16 v[42:45], v[160:163], v[192:195], v[42:45]
	v_mfma_f32_16x16x32_bf16 v[30:33], v[142:145], v[208:211], v[30:33]
	v_mfma_f32_16x16x32_bf16 v[26:29], v[160:163], v[208:211], v[26:29]
	v_mfma_f32_16x16x32_bf16 v[14:17], v[142:145], v[216:219], v[14:17]
	v_mfma_f32_16x16x32_bf16 v[10:13], v[160:163], v[216:219], v[10:13]
	v_mfma_f32_16x16x32_bf16 v[62:65], v[146:149], v[188:191], v[62:65]
	v_mfma_f32_16x16x32_bf16 v[58:61], v[164:167], v[188:191], v[58:61]
	v_mfma_f32_16x16x32_bf16 v[46:49], v[146:149], v[204:207], v[46:49]
	v_mfma_f32_16x16x32_bf16 v[42:45], v[164:167], v[204:207], v[42:45]
	v_mfma_f32_16x16x32_bf16 v[30:33], v[146:149], v[212:215], v[30:33]
	v_mfma_f32_16x16x32_bf16 v[26:29], v[164:167], v[212:215], v[26:29]
	v_mfma_f32_16x16x32_bf16 v[14:17], v[146:149], v[220:223], v[14:17]
	v_mfma_f32_16x16x32_bf16 v[10:13], v[164:167], v[220:223], v[10:13]
	v_mfma_f32_16x16x32_bf16 v[54:57], v[168:171], v[184:187], v[54:57]
	v_mfma_f32_16x16x32_bf16 v[50:53], v[176:179], v[184:187], v[50:53]
	v_mfma_f32_16x16x32_bf16 v[38:41], v[168:171], v[192:195], v[38:41]
	v_mfma_f32_16x16x32_bf16 v[34:37], v[176:179], v[192:195], v[34:37]
	v_mfma_f32_16x16x32_bf16 v[22:25], v[168:171], v[208:211], v[22:25]
	v_mfma_f32_16x16x32_bf16 v[18:21], v[176:179], v[208:211], v[18:21]
	v_mfma_f32_16x16x32_bf16 v[6:9], v[168:171], v[216:219], v[6:9]
	v_mfma_f32_16x16x32_bf16 v[2:5], v[176:179], v[216:219], v[2:5]
	v_mfma_f32_16x16x32_bf16 v[54:57], v[172:175], v[188:191], v[54:57]
	v_mfma_f32_16x16x32_bf16 v[50:53], v[180:183], v[188:191], v[50:53]
	v_mfma_f32_16x16x32_bf16 v[38:41], v[172:175], v[204:207], v[38:41]
	v_mfma_f32_16x16x32_bf16 v[34:37], v[180:183], v[204:207], v[34:37]
	v_mfma_f32_16x16x32_bf16 v[22:25], v[172:175], v[212:215], v[22:25]
	v_mfma_f32_16x16x32_bf16 v[18:21], v[180:183], v[212:215], v[18:21]
	v_mfma_f32_16x16x32_bf16 v[6:9], v[172:175], v[220:223], v[6:9]
	v_mfma_f32_16x16x32_bf16 v[2:5], v[180:183], v[220:223], v[2:5]
	s_barrier
	s_add_i32 s15, 0, 0x18000
	v_add_u32_e32 v0, s15, v153
	s_add_i32 s47, 0, 0x1c000
	ds_read_b128 v[142:145], v0
	ds_read_b128 v[146:149], v0 offset:1024
	ds_read_b128 v[160:163], v0 offset:2048
	ds_read_b128 v[164:167], v0 offset:3072
	v_add_u32_e32 v0, s47, v153
	ds_read_b128 v[168:171], v0
	ds_read_b128 v[172:175], v0 offset:1024
	ds_read_b128 v[176:179], v0 offset:2048
	ds_read_b128 v[180:183], v0 offset:3072
	s_add_u32 s40, s40, s8
	s_addc_u32 s41, s41, s9
	s_mov_b32 m0, s54
	v_lshl_add_u64 v[234:235], s[40:41], 0, v[130:131]
	ds_read_b128 v[184:187], v158 offset:32768
	ds_read_b128 v[188:191], v158 offset:33792
	ds_read_b128 v[192:195], v158 offset:34816
	ds_read_b128 v[204:207], v158 offset:35840
	ds_read_b128 v[208:211], v158 offset:36864
	ds_read_b128 v[212:215], v158 offset:37888
	ds_read_b128 v[216:219], v158 offset:38912
	ds_read_b128 v[220:223], v158 offset:39936
	global_load_lds_dwordx4 v[234:235], off
	v_lshl_add_u64 v[234:235], s[40:41], 0, v[134:135]
	s_mov_b32 m0, s55
	s_nop 0
	global_load_lds_dwordx4 v[234:235], off
	s_waitcnt vmcnt(8)
	s_waitcnt lgkmcnt(0)
	s_barrier
	s_waitcnt lgkmcnt(0)
	v_mfma_f32_16x16x32_bf16 v[122:125], v[142:145], v[184:187], v[122:125]
	v_mfma_f32_16x16x32_bf16 v[126:129], v[160:163], v[184:187], v[126:129]
	v_mfma_f32_16x16x32_bf16 v[110:113], v[142:145], v[192:195], v[110:113]
	v_mfma_f32_16x16x32_bf16 v[106:109], v[160:163], v[192:195], v[106:109]
	v_mfma_f32_16x16x32_bf16 v[94:97], v[142:145], v[208:211], v[94:97]
	v_mfma_f32_16x16x32_bf16 v[90:93], v[160:163], v[208:211], v[90:93]
	v_mfma_f32_16x16x32_bf16 v[78:81], v[142:145], v[216:219], v[78:81]
	v_mfma_f32_16x16x32_bf16 v[74:77], v[160:163], v[216:219], v[74:77]
	v_mfma_f32_16x16x32_bf16 v[122:125], v[146:149], v[188:191], v[122:125]
	v_mfma_f32_16x16x32_bf16 v[126:129], v[164:167], v[188:191], v[126:129]
	v_mfma_f32_16x16x32_bf16 v[110:113], v[146:149], v[204:207], v[110:113]
	v_mfma_f32_16x16x32_bf16 v[106:109], v[164:167], v[204:207], v[106:109]
	v_mfma_f32_16x16x32_bf16 v[94:97], v[146:149], v[212:215], v[94:97]
	v_mfma_f32_16x16x32_bf16 v[90:93], v[164:167], v[212:215], v[90:93]
	v_mfma_f32_16x16x32_bf16 v[78:81], v[146:149], v[220:223], v[78:81]
	v_mfma_f32_16x16x32_bf16 v[74:77], v[164:167], v[220:223], v[74:77]
	v_mfma_f32_16x16x32_bf16 v[118:121], v[168:171], v[184:187], v[118:121]
	v_mfma_f32_16x16x32_bf16 v[114:117], v[176:179], v[184:187], v[114:117]
	v_mfma_f32_16x16x32_bf16 v[102:105], v[168:171], v[192:195], v[102:105]
	v_mfma_f32_16x16x32_bf16 v[98:101], v[176:179], v[192:195], v[98:101]
	v_mfma_f32_16x16x32_bf16 v[86:89], v[168:171], v[208:211], v[86:89]
	v_mfma_f32_16x16x32_bf16 v[82:85], v[176:179], v[208:211], v[82:85]
	v_mfma_f32_16x16x32_bf16 v[70:73], v[168:171], v[216:219], v[70:73]
	v_mfma_f32_16x16x32_bf16 v[66:69], v[176:179], v[216:219], v[66:69]
	v_mfma_f32_16x16x32_bf16 v[118:121], v[172:175], v[188:191], v[118:121]
	v_mfma_f32_16x16x32_bf16 v[114:117], v[180:183], v[188:191], v[114:117]
	v_mfma_f32_16x16x32_bf16 v[102:105], v[172:175], v[204:207], v[102:105]
	v_mfma_f32_16x16x32_bf16 v[98:101], v[180:183], v[204:207], v[98:101]
	v_mfma_f32_16x16x32_bf16 v[86:89], v[172:175], v[212:215], v[86:89]
	v_mfma_f32_16x16x32_bf16 v[82:85], v[180:183], v[212:215], v[82:85]
	v_mfma_f32_16x16x32_bf16 v[70:73], v[172:175], v[220:223], v[70:73]
	v_mfma_f32_16x16x32_bf16 v[66:69], v[180:183], v[220:223], v[66:69]
	s_barrier
; #define PG8_STAGE(bufoff, gbase, voff) do { _Pragma("unroll") for (int _i = 0; _i < 2; ++_i) \
;         __builtin_amdgcn_global_load_lds((const unsigned*)((const char*)(gbase) + (voff)[_i]), (PG8_LAS unsigned*)(lds + (bufoff) + ldsw + _i * 8192), 16, 0, 0); } while (0)
; #define PG8_LDA(dst, b, h) do { _Pragma("unroll") for (int m = 0; m < 4; ++m) _Pragma("unroll") for (int k = 0; k < 2; ++k) dst[m][k] = *(const PG8_LAS bf16x8*)(lds + PG8_SA(b, h) + aoff + m * 2048 + k * 1024); } while (0)
; #define PG8_MMA(ai, bj, At, Bt) do { __builtin_amdgcn_s_setprio(1); _Pragma("unroll") for (int m = 0; m < 4; ++m) _Pragma("unroll") for (int n = 0; n < 2; ++n) _Pragma("unroll") for (int k = 0; k < 2; ++k) \
;         acc[ai][bj][m][n] = __builtin_amdgcn_mfma_f32_16x16x32_bf16(Bt[n][k], At[m][k], acc[ai][bj][m][n], 0, 0, 0); __builtin_amdgcn_s_setprio(0); } while (0)
; #define PG8_WAIT_V(n) asm volatile("s_waitcnt vmcnt(" #n ")" ::: "memory")
; #define PG8_WAIT_L(n) asm volatile("s_waitcnt lgkmcnt(" #n ")" ::: "memory")
; #define PG8_BAR __builtin_amdgcn_s_barrier()
; #define PG8_SCHED __builtin_amdgcn_sched_barrier(0)
; template <class Epi, class Sched, bool ALIGN_EPI = false, bool SP2 = false>
; __device__ __forceinline__ void gemm_phase(PG8_LAS unsigned char* lds, const Gemm g, const Sched& S, const Epi& E, int tid_in) {
;     ...
;         for (int t = 0; t < nt; t += 2) {
;             const bool last = (t == nt - 2);
;             const char* a1 = cA + (size_t)(t + 1) * kstep;
;             const char* a2 = last ? nA : cA + (size_t)(t + 2) * kstep; const char* b2 = last ? nB : cB + (size_t)(t + 2) * kstep;
;             const char* a3 = a2 + kstep; const char* b3 = b2 + kstep;
;     ...
;             PG8_LDA(At, 1, 1); PG8_STAGE(PG8_SB(1, 0), b3, voffB); PG8_STAGE(PG8_SB(1, 1), b3 + hstep, voffB); PG8_STAGE(PG8_SA(1, 0), a3, voffA);
;             PG8_WAIT_V(8); PG8_WAIT_L(0); PG8_BAR; PG8_MMA(1, 0, At, B0); PG8_MMA(1, 1, At, B1); PG8_BAR; PG8_SCHED;
	s_add_i32 s15, s15, s51
	v_lshl_add_u64 v[150:151], v[150:151], 0, s[28:29]
	s_mov_b32 m0, s15
	ds_read_b128 v[184:187], v158 offset:49152
	ds_read_b128 v[188:191], v158 offset:50176
	ds_read_b128 v[192:195], v158 offset:51200
	ds_read_b128 v[204:207], v158 offset:52224
	ds_read_b128 v[208:211], v158 offset:53248
	ds_read_b128 v[212:215], v158 offset:54272
	ds_read_b128 v[216:219], v158 offset:55296
	ds_read_b128 v[220:223], v158 offset:56320
	global_load_lds_dwordx4 v[150:151], off
	v_lshl_add_u64 v[150:151], v[224:225], 0, s[28:29]
	s_add_i32 m0, s15, 0x2000
	s_add_i32 s15, s47, s51
	global_load_lds_dwordx4 v[150:151], off
	v_lshl_add_u64 v[150:151], v[226:227], 0, s[28:29]
	s_mov_b32 m0, s15
	s_nop 0
	global_load_lds_dwordx4 v[150:151], off
	v_lshl_add_u64 v[150:151], v[228:229], 0, s[28:29]
	s_add_i32 m0, s15, 0x2000
	s_nop 0
	global_load_lds_dwordx4 v[150:151], off
	v_lshl_add_u64 v[150:151], v[230:231], 0, s[28:29]
	s_mov_b32 m0, s56
	s_nop 0
	global_load_lds_dwordx4 v[150:151], off
	v_lshl_add_u64 v[150:151], v[232:233], 0, s[28:29]
	s_mov_b32 m0, s57
	s_nop 0
	global_load_lds_dwordx4 v[150:151], off
	s_waitcnt vmcnt(8)
	s_waitcnt lgkmcnt(0)
	s_barrier
	s_waitcnt lgkmcnt(0)
	v_mfma_f32_16x16x32_bf16 v[62:65], v[142:145], v[184:187], v[62:65]
	v_mfma_f32_16x16x32_bf16 v[58:61], v[160:163], v[184:187], v[58:61]
	v_mfma_f32_16x16x32_bf16 v[46:49], v[142:145], v[192:195], v[46:49]
	v_mfma_f32_16x16x32_bf16 v[42:45], v[160:163], v[192:195], v[42:45]
	v_mfma_f32_16x16x32_bf16 v[30:33], v[142:145], v[208:211], v[30:33]
	v_mfma_f32_16x16x32_bf16 v[26:29], v[160:163], v[208:211], v[26:29]
	v_mfma_f32_16x16x32_bf16 v[14:17], v[142:145], v[216:219], v[14:17]
	v_mfma_f32_16x16x32_bf16 v[10:13], v[160:163], v[216:219], v[10:13]
	v_mfma_f32_16x16x32_bf16 v[62:65], v[146:149], v[188:191], v[62:65]
	v_mfma_f32_16x16x32_bf16 v[58:61], v[164:167], v[188:191], v[58:61]
	v_mfma_f32_16x16x32_bf16 v[46:49], v[146:149], v[204:207], v[46:49]
	v_mfma_f32_16x16x32_bf16 v[42:45], v[164:167], v[204:207], v[42:45]
	v_mfma_f32_16x16x32_bf16 v[30:33], v[146:149], v[212:215], v[30:33]
	v_mfma_f32_16x16x32_bf16 v[26:29], v[164:167], v[212:215], v[26:29]
	v_mfma_f32_16x16x32_bf16 v[14:17], v[146:149], v[220:223], v[14:17]
	v_mfma_f32_16x16x32_bf16 v[10:13], v[164:167], v[220:223], v[10:13]
	v_mfma_f32_16x16x32_bf16 v[54:57], v[168:171], v[184:187], v[54:57]
	v_mfma_f32_16x16x32_bf16 v[50:53], v[176:179], v[184:187], v[50:53]
	v_mfma_f32_16x16x32_bf16 v[38:41], v[168:171], v[192:195], v[38:41]
	v_mfma_f32_16x16x32_bf16 v[34:37], v[176:179], v[192:195], v[34:37]
	v_mfma_f32_16x16x32_bf16 v[22:25], v[168:171], v[208:211], v[22:25]
	v_mfma_f32_16x16x32_bf16 v[18:21], v[176:179], v[208:211], v[18:21]
	v_mfma_f32_16x16x32_bf16 v[6:9], v[168:171], v[216:219], v[6:9]
	v_mfma_f32_16x16x32_bf16 v[2:5], v[176:179], v[216:219], v[2:5]
	v_mfma_f32_16x16x32_bf16 v[54:57], v[172:175], v[188:191], v[54:57]
	v_mfma_f32_16x16x32_bf16 v[50:53], v[180:183], v[188:191], v[50:53]
	v_mfma_f32_16x16x32_bf16 v[38:41], v[172:175], v[204:207], v[38:41]
	v_mfma_f32_16x16x32_bf16 v[34:37], v[180:183], v[204:207], v[34:37]
	v_mfma_f32_16x16x32_bf16 v[22:25], v[172:175], v[212:215], v[22:25]
	v_mfma_f32_16x16x32_bf16 v[18:21], v[180:183], v[212:215], v[18:21]
	v_mfma_f32_16x16x32_bf16 v[6:9], v[172:175], v[220:223], v[6:9]
	v_mfma_f32_16x16x32_bf16 v[2:5], v[180:183], v[220:223], v[2:5]
	s_barrier
	s_add_u32 s38, s38, 0x100
	s_addc_u32 s39, s39, 0
	s_add_u32 s12, s12, 0x100
	s_addc_u32 s13, s13, 0
	s_cmp_ge_i32 s46, s58
	s_mov_b32 s15, s46
	s_cbranch_scc0 .LBB0_712
	s_setprio 0
	s_movk_i32 s64, 0x6000
